# lru_m1: y/P stores of channel blocks (0,1),(2,3) paired by v_permlane16_swap into dwordx4 (16 instead of 32 stores per item)
# speedup vs baseline: 1.0169x; 1.0038x over previous
.LBB0_520:
	s_lshr_b32 s20, s24, 8
	s_lshr_b32 s21, s24, 9
	s_add_i32 s20, s20, s24
	s_and_b32 s21, s21, 12
	s_add_i32 s20, s20, s21
	s_and_b32 s91, s20, 15
	s_cmp_gt_u32 s91, 7
	s_cbranch_scc1 .LBB0_519
	s_ashr_i32 s20, s24, 31
	s_ashr_i32 s90, s24, 4
	s_lshr_b32 s20, s20, 25
	s_add_i32 s27, s90, s20
	s_and_b32 s20, s27, 0xffffff80
	v_mov_b32_e32 v122, v144
	s_mov_b32 s34, 3
	s_sub_i32 s46, s90, s20
	s_ashr_i32 s35, s34, 31
	s_lshl_b32 s20, s46, 6
	s_lshl_b64 s[34:35], s[34:35], 3
	s_add_u32 s34, s0, s34
	s_addc_u32 s35, s1, s35
	s_load_dwordx2 s[40:41], s[34:35], 0x0
	s_mov_b32 s34, 4
	s_ashr_i32 s35, s34, 31
	s_lshl_b64 s[34:35], s[34:35], 3
	s_add_u32 s34, s0, s34
	s_addc_u32 s35, s1, s35
	s_lshl_b32 s21, s91, 13
	s_add_u32 s92, s2, s21
	s_addc_u32 s93, s3, 0
	s_load_dwordx2 s[42:43], s[34:35], 0x0
	s_add_u32 s34, s68, s21
	s_mov_b32 s44, 6
	s_addc_u32 s35, s70, 0
	s_ashr_i32 s45, s44, 31
	s_lshl_b64 s[44:45], s[44:45], 3
	s_add_u32 s44, s0, s44
	s_addc_u32 s45, s1, s45
	s_waitcnt lgkmcnt(0)
	s_mov_b32 s48, 8
	s_load_dwordx2 s[44:45], s[44:45], 0x0
	s_ashr_i32 s49, s48, 31
	s_lshl_b32 s21, s91, 6
	s_lshl_b64 s[48:49], s[48:49], 3
	s_add_u32 s48, s0, s48
	s_addc_u32 s49, s1, s49
	s_load_dwordx2 s[48:49], s[48:49], 0x0
	v_ashrrev_i32_e32 v8, 4, v122
	v_and_b32_e32 v136, 15, v122
	v_lshlrev_b32_e32 v4, 3, v8
	v_lshlrev_b32_e32 v2, 7, v136
	s_waitcnt lgkmcnt(0)
	s_add_u32 s47, s48, s88
	s_mov_b32 s48, 9
	s_addc_u32 s50, s49, s89
	s_ashr_i32 s49, s48, 31
	s_lshl_b64 s[48:49], s[48:49], 3
	s_add_u32 s48, s0, s48
	s_addc_u32 s49, s1, s49
	s_add_u32 s48, s78, 0x3b00000
	s_addc_u32 s49, s79, 0x0
	v_ashrrev_i32_e32 v5, 31, v4
	v_lshl_add_u64 v[0:1], s[92:93], 0, v[2:3]
	v_lshlrev_b64 v[100:101], 1, v[4:5]
	v_lshl_add_u64 v[0:1], v[0:1], 0, v[100:101]
	s_waitcnt lgkmcnt(0)
	s_add_u32 s51, s48, s88
	s_addc_u32 s52, s49, s89
	s_lshl_b32 s27, s27, 6
	s_and_b32 s27, s27, 0xffffe000
	s_add_u32 s48, s40, s96
	s_addc_u32 s49, s41, s97
	s_add_u32 s42, s42, s88
	s_addc_u32 s43, s43, s89
	s_add_u32 s40, s44, s88
	s_addc_u32 s41, s45, s89
	s_lshl_b32 s53, s91, 8
	s_add_u32 s40, s40, s53
	v_lshl_add_u64 v[6:7], s[34:35], 0, v[2:3]
	s_addc_u32 s41, s41, 0
	v_lshl_add_u64 v[6:7], v[6:7], 0, v[100:101]
	flat_load_dwordx4 v[52:55], v[0:1]
	flat_load_dwordx4 v[56:59], v[6:7]
	flat_load_dwordx4 v[60:63], v[0:1] offset:64
	flat_load_dwordx4 v[64:67], v[6:7] offset:64
	s_add_u32 s44, s47, s53
	v_lshlrev_b32_e32 v0, 2, v8
	s_addc_u32 s45, s50, 0
	v_ashrrev_i32_e32 v1, 31, v0
	s_add_u32 s50, s51, s53
	v_lshlrev_b64 v[6:7], 2, v[0:1]
	s_addc_u32 s51, s52, 0
	v_lshl_add_u64 v[108:109], s[40:41], 0, v[6:7]
	s_add_i32 s40, s20, -3
	v_add_u32_e32 v78, s21, v4
	v_lshl_add_u64 v[110:111], s[44:45], 0, v[6:7]
	v_lshl_add_u64 v[112:113], s[50:51], 0, v[6:7]
	v_ashrrev_i32_e32 v79, 31, v78
	v_add_u32_e32 v6, s40, v136
	v_lshlrev_b64 v[4:5], 2, v[78:79]
	v_cmp_lt_i32_e64 s[50:51], -1, v6
	v_lshl_add_u64 v[76:77], s[42:43], 0, v[4:5]
	v_lshl_add_u64 v[86:87], s[48:49], 0, v[4:5]
	s_mov_b64 s[42:43], 0x1000
	v_cndmask_b32_e64 v4, 0, v6, s[50:51]
	v_lshl_add_u64 v[36:37], v[86:87], 0, s[42:43]
	s_mov_b64 s[42:43], 0x1800
	v_lshl_add_u64 v[80:81], v[78:79], 1, s[8:9]
	v_add_u32_e32 v79, s27, v4
	v_lshl_add_u64 v[82:83], v[86:87], 0, s[42:43]
	v_max_i32_e32 v4, -1, v6
	s_or_b32 s80, s27, 1
	v_add_u32_e32 v92, s80, v4
	v_max_i32_e32 v4, -2, v6
	s_or_b32 s81, s27, 2
	v_add_u32_e32 v93, s81, v4
	s_cmp_gt_i32 s46, -1
	v_or_b32_e32 v4, s20, v136
	s_cselect_b64 s[42:43], -1, 0
	v_cndmask_b32_e64 v4, 0, v4, s[42:43]
	v_add_u32_e32 v94, s27, v4
	global_load_dwordx4 v[48:51], v[108:109], off
	global_load_dwordx4 v[44:47], v[110:111], off
	global_load_dwordx4 v[88:91], v[112:113], off
	v_lshl_add_u32 v95, v8, 5, s6
	v_cmp_lt_i32_e64 s[48:49], -2, v6
	v_cmp_lt_i32_e64 s[44:45], -3, v6
	global_load_dwordx4 v[20:23], v[76:77], off offset:16
	s_nop 0
	global_load_dwordx4 v[4:7], v[76:77], off
	global_load_dwordx4 v[24:27], v[86:87], off offset:16
	global_load_dwordx4 v[32:35], v[86:87], off
	global_load_dwordx4 v[28:31], v[86:87], off offset:2064
	global_load_dwordx4 v[40:43], v[86:87], off offset:2048
	v_add_co_u32_e32 v96, vcc, s73, v86
	v_mad_u32_u24 v121, v136, s76, v95
	s_nop 0
	v_addc_co_u32_e32 v97, vcc, 0, v87, vcc
	global_load_dwordx4 v[68:71], v[96:97], off
	s_nop 0
	global_load_dwordx4 v[36:39], v[36:37], off offset:16
	s_nop 0
	global_load_dwordx4 v[104:107], v[96:97], off offset:2048
	global_load_dwordx4 v[114:117], v[82:83], off offset:16
	v_add_u32_e32 v186, s20, v136
	v_add_u32_e32 v187, -16, v186
	v_max_i32_e32 v187, 0, v187
	v_add_u32_e32 v187, s27, v187
	v_add_u32_e32 v186, s27, v186
	v_mad_i64_i32 v[188:189], s[46:47], v187, s72, v[80:81]
	global_load_dwordx4 v[222:225], v[188:189], off
	global_load_dwordx4 v[242:245], v[188:189], off offset:64
	v_mad_i64_i32 v[188:189], s[46:47], v186, s72, v[80:81]
	global_load_dwordx4 v[226:229], v[188:189], off
	global_load_dwordx4 v[246:249], v[188:189], off offset:64
	v_add_u32_e32 v187, 16, v186
	v_mad_i64_i32 v[188:189], s[46:47], v187, s72, v[80:81]
	global_load_dwordx4 v[230:233], v[188:189], off
	global_load_dwordx4 v[250:253], v[188:189], off offset:64
	v_add_u32_e32 v187, 32, v186
	v_mad_i64_i32 v[188:189], s[46:47], v187, s72, v[80:81]
	global_load_dwordx4 v[234:237], v[188:189], off
	global_load_dwordx4 v[190:193], v[188:189], off offset:64
	v_add_u32_e32 v187, 48, v186
	v_mad_i64_i32 v[188:189], s[46:47], v187, s72, v[80:81]
	global_load_dwordx4 v[238:241], v[188:189], off
	global_load_dwordx4 v[194:197], v[188:189], off offset:64
	v_or_b32_e32 v140, 16, v136
	v_or_b32_e32 v139, 32, v136
	v_or_b32_e32 v137, 48, v136
	v_mov_b64_e32 v[102:103], s[8:9]
	s_waitcnt vmcnt(0) lgkmcnt(0)
	v_mov_b32_dpp v72, v222 row_ror:3 row_mask:0xf bank_mask:0xf
	v_mov_b32_dpp v73, v223 row_ror:3 row_mask:0xf bank_mask:0xf
	v_mov_b32_dpp v74, v224 row_ror:3 row_mask:0xf bank_mask:0xf
	v_mov_b32_dpp v75, v225 row_ror:3 row_mask:0xf bank_mask:0xf
	v_mov_b32_dpp v72, v226 row_shr:3 row_mask:0xf bank_mask:0xf
	v_mov_b32_dpp v73, v227 row_shr:3 row_mask:0xf bank_mask:0xf
	v_mov_b32_dpp v74, v228 row_shr:3 row_mask:0xf bank_mask:0xf
	v_mov_b32_dpp v75, v229 row_shr:3 row_mask:0xf bank_mask:0xf
	v_mov_b32_dpp v16, v222 row_ror:2 row_mask:0xf bank_mask:0xf
	v_mov_b32_dpp v17, v223 row_ror:2 row_mask:0xf bank_mask:0xf
	v_mov_b32_dpp v18, v224 row_ror:2 row_mask:0xf bank_mask:0xf
	v_mov_b32_dpp v19, v225 row_ror:2 row_mask:0xf bank_mask:0xf
	v_mov_b32_dpp v16, v226 row_shr:2 row_mask:0xf bank_mask:0xf
	v_mov_b32_dpp v17, v227 row_shr:2 row_mask:0xf bank_mask:0xf
	v_mov_b32_dpp v18, v228 row_shr:2 row_mask:0xf bank_mask:0xf
	v_mov_b32_dpp v19, v229 row_shr:2 row_mask:0xf bank_mask:0xf
	v_mov_b32_dpp v12, v222 row_ror:1 row_mask:0xf bank_mask:0xf
	v_mov_b32_dpp v13, v223 row_ror:1 row_mask:0xf bank_mask:0xf
	v_mov_b32_dpp v14, v224 row_ror:1 row_mask:0xf bank_mask:0xf
	v_mov_b32_dpp v15, v225 row_ror:1 row_mask:0xf bank_mask:0xf
	v_mov_b32_dpp v12, v226 row_shr:1 row_mask:0xf bank_mask:0xf
	v_mov_b32_dpp v13, v227 row_shr:1 row_mask:0xf bank_mask:0xf
	v_mov_b32_dpp v14, v228 row_shr:1 row_mask:0xf bank_mask:0xf
	v_mov_b32_dpp v15, v229 row_shr:1 row_mask:0xf bank_mask:0xf
	v_mov_b64_e32 v[8:9], v[226:227]
	v_mov_b64_e32 v[10:11], v[228:229]
	v_lshlrev_b32_e32 v82, 16, v72
	v_lshlrev_b32_e32 v84, 16, v73
	v_and_b32_e32 v83, 0xffff0000, v72
	v_and_b32_e32 v85, 0xffff0000, v73
	v_cndmask_b32_e64 v73, 0, v33, s[50:51]
	v_cndmask_b32_e64 v72, 0, v32, s[50:51]
	v_cndmask_b32_e64 v99, 0, v35, s[50:51]
	v_cndmask_b32_e64 v98, 0, v34, s[50:51]
	v_pk_fma_f32 v[84:85], v[98:99], v[84:85], v[6:7]
	v_pk_fma_f32 v[72:73], v[72:73], v[82:83], v[4:5]
	v_lshlrev_b32_e32 v82, 16, v17
	v_lshlrev_b32_e32 v98, 16, v16
	v_and_b32_e32 v83, 0xffff0000, v17
	v_and_b32_e32 v99, 0xffff0000, v16
	v_cndmask_b32_e64 v17, 0, v43, s[48:49]
	v_cndmask_b32_e64 v16, 0, v42, s[48:49]
	v_cndmask_b32_e64 v119, 0, v41, s[48:49]
	v_cndmask_b32_e64 v118, 0, v40, s[48:49]
	v_pk_fma_f32 v[72:73], v[118:119], v[98:99], v[72:73]
	v_pk_fma_f32 v[16:17], v[16:17], v[82:83], v[84:85]
	v_lshlrev_b32_e32 v82, 16, v12
	v_lshlrev_b32_e32 v84, 16, v13
	v_and_b32_e32 v83, 0xffff0000, v12
	v_and_b32_e32 v85, 0xffff0000, v13
	v_cndmask_b32_e64 v13, 0, v69, s[44:45]
	v_cndmask_b32_e64 v12, 0, v68, s[44:45]
	v_cndmask_b32_e64 v99, 0, v71, s[44:45]
	v_cndmask_b32_e64 v98, 0, v70, s[44:45]
	v_pk_fma_f32 v[16:17], v[98:99], v[84:85], v[16:17]
	v_pk_fma_f32 v[12:13], v[12:13], v[82:83], v[72:73]
	v_lshlrev_b32_e32 v84, 16, v9
	v_lshlrev_b32_e32 v98, 16, v8
	v_and_b32_e32 v85, 0xffff0000, v9
	v_and_b32_e32 v99, 0xffff0000, v8
	v_cndmask_b32_e64 v73, 0, v107, s[42:43]
	v_cndmask_b32_e64 v72, 0, v106, s[42:43]
	v_cndmask_b32_e64 v83, 0, v105, s[42:43]
	v_cndmask_b32_e64 v82, 0, v104, s[42:43]
	v_pk_fma_f32 v[8:9], v[82:83], v[98:99], v[12:13]
	v_pk_fma_f32 v[12:13], v[72:73], v[84:85], v[16:17]
	v_cvt_pk_bf16_f32 v16, v8, v9
	v_cvt_pk_bf16_f32 v17, v12, v13
	ds_write2_b32 v121, v12, v13 offset0:2 offset1:3
	ds_write2_b32 v121, v8, v9 offset1:1
	v_lshlrev_b32_e32 v8, 16, v74
	v_lshlrev_b32_e32 v12, 16, v75
	v_and_b32_e32 v9, 0xffff0000, v74
	v_and_b32_e32 v13, 0xffff0000, v75
	v_cndmask_b32_e64 v75, 0, v25, s[50:51]
	v_cndmask_b32_e64 v74, 0, v24, s[50:51]
	v_cndmask_b32_e64 v85, 0, v27, s[50:51]
	v_cndmask_b32_e64 v84, 0, v26, s[50:51]
	v_pk_fma_f32 v[12:13], v[84:85], v[12:13], v[22:23]
	v_pk_fma_f32 v[8:9], v[74:75], v[8:9], v[20:21]
	v_lshlrev_b32_e32 v74, 16, v19
	v_lshlrev_b32_e32 v84, 16, v18
	v_and_b32_e32 v75, 0xffff0000, v19
	v_and_b32_e32 v85, 0xffff0000, v18
	v_cndmask_b32_e64 v19, 0, v31, s[48:49]
	v_cndmask_b32_e64 v18, 0, v30, s[48:49]
	v_cndmask_b32_e64 v99, 0, v29, s[48:49]
	v_cndmask_b32_e64 v98, 0, v28, s[48:49]
	v_pk_fma_f32 v[8:9], v[98:99], v[84:85], v[8:9]
	v_pk_fma_f32 v[12:13], v[18:19], v[74:75], v[12:13]
	v_lshlrev_b32_e32 v18, 16, v14
	v_lshlrev_b32_e32 v74, 16, v15
	v_and_b32_e32 v19, 0xffff0000, v14
	v_and_b32_e32 v75, 0xffff0000, v15
	v_cndmask_b32_e64 v15, 0, v37, s[44:45]
	v_cndmask_b32_e64 v14, 0, v36, s[44:45]
	v_cndmask_b32_e64 v85, 0, v39, s[44:45]
	v_cndmask_b32_e64 v84, 0, v38, s[44:45]
	v_pk_fma_f32 v[12:13], v[84:85], v[74:75], v[12:13]
	v_pk_fma_f32 v[8:9], v[14:15], v[18:19], v[8:9]
	v_lshlrev_b32_e32 v14, 16, v11
	v_lshlrev_b32_e32 v18, 16, v10
	v_and_b32_e32 v15, 0xffff0000, v11
	v_and_b32_e32 v19, 0xffff0000, v10
	v_cndmask_b32_e64 v75, 0, v117, s[42:43]
	v_cndmask_b32_e64 v74, 0, v116, s[42:43]
	v_cndmask_b32_e64 v85, 0, v115, s[42:43]
	v_cndmask_b32_e64 v84, 0, v114, s[42:43]
	v_add_u32_e32 v98, s40, v140
	v_pk_fma_f32 v[8:9], v[84:85], v[18:19], v[8:9]
	v_pk_fma_f32 v[10:11], v[74:75], v[14:15], v[12:13]
	v_cmp_lt_i32_e64 s[62:63], -1, v98
	v_cvt_pk_bf16_f32 v18, v8, v9
	ds_write2_b32 v121, v10, v11 offset0:6 offset1:7
	ds_write2_b32 v121, v8, v9 offset0:4 offset1:5
	v_cndmask_b32_e64 v8, 0, v98, s[62:63]
	v_cmp_lt_i32_e64 s[60:61], -2, v98
	v_max_i32_e32 v12, -1, v98
	v_cmp_lt_i32_e64 s[58:59], -3, v98
	v_max_i32_e32 v98, -2, v98
	v_add_u32_e32 v142, s81, v98
	v_add_u32_e32 v134, s27, v8
	v_add_u32_e32 v135, s80, v12
	v_mov_b32_dpp v104, v226 row_ror:1 row_mask:0xf bank_mask:0xf
	v_mov_b32_dpp v105, v227 row_ror:1 row_mask:0xf bank_mask:0xf
	v_mov_b32_dpp v106, v228 row_ror:1 row_mask:0xf bank_mask:0xf
	v_mov_b32_dpp v107, v229 row_ror:1 row_mask:0xf bank_mask:0xf
	v_mov_b32_dpp v104, v230 row_shr:1 row_mask:0xf bank_mask:0xf
	v_mov_b32_dpp v105, v231 row_shr:1 row_mask:0xf bank_mask:0xf
	v_mov_b32_dpp v106, v232 row_shr:1 row_mask:0xf bank_mask:0xf
	v_mov_b32_dpp v107, v233 row_shr:1 row_mask:0xf bank_mask:0xf
	v_or_b32_e32 v98, s20, v140
	v_cvt_pk_bf16_f32 v19, v10, v11
	v_mov_b32_dpp v8, v226 row_ror:3 row_mask:0xf bank_mask:0xf
	v_mov_b32_dpp v9, v227 row_ror:3 row_mask:0xf bank_mask:0xf
	v_mov_b32_dpp v10, v228 row_ror:3 row_mask:0xf bank_mask:0xf
	v_mov_b32_dpp v11, v229 row_ror:3 row_mask:0xf bank_mask:0xf
	v_mov_b32_dpp v8, v230 row_shr:3 row_mask:0xf bank_mask:0xf
	v_mov_b32_dpp v9, v231 row_shr:3 row_mask:0xf bank_mask:0xf
	v_mov_b32_dpp v10, v232 row_shr:3 row_mask:0xf bank_mask:0xf
	v_mov_b32_dpp v11, v233 row_shr:3 row_mask:0xf bank_mask:0xf
	v_cndmask_b32_e64 v98, 0, v98, s[42:43]
	v_mov_b32_dpp v12, v226 row_ror:2 row_mask:0xf bank_mask:0xf
	v_mov_b32_dpp v13, v227 row_ror:2 row_mask:0xf bank_mask:0xf
	v_mov_b32_dpp v14, v228 row_ror:2 row_mask:0xf bank_mask:0xf
	v_mov_b32_dpp v15, v229 row_ror:2 row_mask:0xf bank_mask:0xf
	v_mov_b32_dpp v12, v230 row_shr:2 row_mask:0xf bank_mask:0xf
	v_mov_b32_dpp v13, v231 row_shr:2 row_mask:0xf bank_mask:0xf
	v_mov_b32_dpp v14, v232 row_shr:2 row_mask:0xf bank_mask:0xf
	v_mov_b32_dpp v15, v233 row_shr:2 row_mask:0xf bank_mask:0xf
	v_add_u32_e32 v143, s27, v98
	v_mov_b64_e32 v[114:115], v[230:231]
	v_mov_b64_e32 v[116:117], v[232:233]
	v_mov_b32_e32 v98, 0x1040
	v_mad_u32_u24 v123, v136, s76, v98
	v_cndmask_b32_e64 v127, 0, v35, s[62:63]
	v_cndmask_b32_e64 v126, 0, v34, s[62:63]
	v_cndmask_b32_e64 v129, 0, v41, s[60:61]
	v_cndmask_b32_e64 v128, 0, v40, s[60:61]
	v_add_u32_e32 v125, v95, v123
	s_waitcnt vmcnt(0) lgkmcnt(0)
	v_lshlrev_b32_e32 v98, 16, v8
	v_lshlrev_b32_e32 v118, 16, v9
	v_and_b32_e32 v99, 0xffff0000, v8
	v_and_b32_e32 v119, 0xffff0000, v9
	v_cndmask_b32_e64 v9, 0, v33, s[62:63]
	v_cndmask_b32_e64 v8, 0, v32, s[62:63]
	v_pk_fma_f32 v[118:119], v[126:127], v[118:119], v[6:7]
	v_pk_fma_f32 v[8:9], v[8:9], v[98:99], v[4:5]
	v_lshlrev_b32_e32 v98, 16, v13
	v_lshlrev_b32_e32 v126, 16, v12
	v_and_b32_e32 v99, 0xffff0000, v13
	v_and_b32_e32 v127, 0xffff0000, v12
	v_cndmask_b32_e64 v13, 0, v43, s[60:61]
	v_cndmask_b32_e64 v12, 0, v42, s[60:61]
	v_pk_fma_f32 v[8:9], v[128:129], v[126:127], v[8:9]
	v_pk_fma_f32 v[12:13], v[12:13], v[98:99], v[118:119]
	v_lshlrev_b32_e32 v98, 16, v104
	v_lshlrev_b32_e32 v118, 16, v105
	v_and_b32_e32 v99, 0xffff0000, v104
	v_and_b32_e32 v119, 0xffff0000, v105
	v_cndmask_b32_e64 v105, 0, v69, s[58:59]
	v_cndmask_b32_e64 v104, 0, v68, s[58:59]
	v_cndmask_b32_e64 v127, 0, v71, s[58:59]
	v_cndmask_b32_e64 v126, 0, v70, s[58:59]
	v_pk_fma_f32 v[12:13], v[126:127], v[118:119], v[12:13]
	v_pk_fma_f32 v[8:9], v[104:105], v[98:99], v[8:9]
	v_lshlrev_b32_e32 v98, 16, v115
	v_lshlrev_b32_e32 v104, 16, v114
	v_and_b32_e32 v99, 0xffff0000, v115
	v_and_b32_e32 v105, 0xffff0000, v114
	v_pk_fma_f32 v[8:9], v[82:83], v[104:105], v[8:9]
	v_pk_fma_f32 v[98:99], v[72:73], v[98:99], v[12:13]
	v_cvt_pk_bf16_f32 v12, v8, v9
	v_cvt_pk_bf16_f32 v13, v98, v99
	ds_write2_b32 v125, v98, v99 offset0:2 offset1:3
	ds_write2_b32 v125, v8, v9 offset1:1
	v_lshlrev_b32_e32 v8, 16, v10
	v_lshlrev_b32_e32 v98, 16, v11
	v_and_b32_e32 v9, 0xffff0000, v10
	v_and_b32_e32 v99, 0xffff0000, v11
	v_cndmask_b32_e64 v11, 0, v25, s[62:63]
	v_cndmask_b32_e64 v10, 0, v24, s[62:63]
	v_cndmask_b32_e64 v105, 0, v27, s[62:63]
	v_cndmask_b32_e64 v104, 0, v26, s[62:63]
	v_pk_fma_f32 v[98:99], v[104:105], v[98:99], v[22:23]
	v_pk_fma_f32 v[8:9], v[10:11], v[8:9], v[20:21]
	v_lshlrev_b32_e32 v10, 16, v15
	v_lshlrev_b32_e32 v104, 16, v14
	v_and_b32_e32 v11, 0xffff0000, v15
	v_and_b32_e32 v105, 0xffff0000, v14
	v_cndmask_b32_e64 v15, 0, v31, s[60:61]
	v_cndmask_b32_e64 v14, 0, v30, s[60:61]
	v_cndmask_b32_e64 v115, 0, v29, s[60:61]
	v_cndmask_b32_e64 v114, 0, v28, s[60:61]
	v_pk_fma_f32 v[8:9], v[114:115], v[104:105], v[8:9]
	v_pk_fma_f32 v[10:11], v[14:15], v[10:11], v[98:99]
	v_lshlrev_b32_e32 v14, 16, v106
	v_lshlrev_b32_e32 v98, 16, v107
	v_and_b32_e32 v15, 0xffff0000, v106
	v_and_b32_e32 v99, 0xffff0000, v107
	v_cndmask_b32_e64 v105, 0, v37, s[58:59]
	v_cndmask_b32_e64 v104, 0, v36, s[58:59]
	v_cndmask_b32_e64 v107, 0, v39, s[58:59]
	v_cndmask_b32_e64 v106, 0, v38, s[58:59]
	v_pk_fma_f32 v[10:11], v[106:107], v[98:99], v[10:11]
	v_pk_fma_f32 v[8:9], v[104:105], v[14:15], v[8:9]
	v_lshlrev_b32_e32 v14, 16, v117
	v_lshlrev_b32_e32 v98, 16, v116
	v_and_b32_e32 v15, 0xffff0000, v117
	v_and_b32_e32 v99, 0xffff0000, v116
	v_add_u32_e32 v114, s40, v139
	v_pk_fma_f32 v[8:9], v[84:85], v[98:99], v[8:9]
	v_pk_fma_f32 v[10:11], v[74:75], v[14:15], v[10:11]
	v_cmp_lt_i32_e64 s[56:57], -1, v114
	v_cvt_pk_bf16_f32 v14, v8, v9
	ds_write2_b32 v125, v10, v11 offset0:6 offset1:7
	ds_write2_b32 v125, v8, v9 offset0:4 offset1:5
	v_cndmask_b32_e64 v8, 0, v114, s[56:57]
	v_max_i32_e32 v98, -1, v114
	v_add_u32_e32 v130, s27, v8
	v_add_u32_e32 v131, s80, v98
	v_cvt_pk_bf16_f32 v15, v10, v11
	v_mov_b32_dpp v8, v230 row_ror:3 row_mask:0xf bank_mask:0xf
	v_mov_b32_dpp v9, v231 row_ror:3 row_mask:0xf bank_mask:0xf
	v_mov_b32_dpp v10, v232 row_ror:3 row_mask:0xf bank_mask:0xf
	v_mov_b32_dpp v11, v233 row_ror:3 row_mask:0xf bank_mask:0xf
	v_mov_b32_dpp v8, v234 row_shr:3 row_mask:0xf bank_mask:0xf
	v_mov_b32_dpp v9, v235 row_shr:3 row_mask:0xf bank_mask:0xf
	v_mov_b32_dpp v10, v236 row_shr:3 row_mask:0xf bank_mask:0xf
	v_mov_b32_dpp v11, v237 row_shr:3 row_mask:0xf bank_mask:0xf
	v_cmp_lt_i32_e64 s[54:55], -2, v114
	v_mov_b32_dpp v104, v230 row_ror:2 row_mask:0xf bank_mask:0xf
	v_mov_b32_dpp v105, v231 row_ror:2 row_mask:0xf bank_mask:0xf
	v_mov_b32_dpp v106, v232 row_ror:2 row_mask:0xf bank_mask:0xf
	v_mov_b32_dpp v107, v233 row_ror:2 row_mask:0xf bank_mask:0xf
	v_mov_b32_dpp v104, v234 row_shr:2 row_mask:0xf bank_mask:0xf
	v_mov_b32_dpp v105, v235 row_shr:2 row_mask:0xf bank_mask:0xf
	v_mov_b32_dpp v106, v236 row_shr:2 row_mask:0xf bank_mask:0xf
	v_mov_b32_dpp v107, v237 row_shr:2 row_mask:0xf bank_mask:0xf
	v_max_i32_e32 v98, -2, v114
	v_add_u32_e32 v132, s81, v98
	v_cmp_lt_i32_e64 s[52:53], -3, v114
	v_mov_b32_dpp v114, v230 row_ror:1 row_mask:0xf bank_mask:0xf
	v_mov_b32_dpp v115, v231 row_ror:1 row_mask:0xf bank_mask:0xf
	v_mov_b32_dpp v116, v232 row_ror:1 row_mask:0xf bank_mask:0xf
	v_mov_b32_dpp v117, v233 row_ror:1 row_mask:0xf bank_mask:0xf
	v_mov_b32_dpp v114, v234 row_shr:1 row_mask:0xf bank_mask:0xf
	v_mov_b32_dpp v115, v235 row_shr:1 row_mask:0xf bank_mask:0xf
	v_mov_b32_dpp v116, v236 row_shr:1 row_mask:0xf bank_mask:0xf
	v_mov_b32_dpp v117, v237 row_shr:1 row_mask:0xf bank_mask:0xf
	v_or_b32_e32 v98, s20, v139
	v_cndmask_b32_e64 v98, 0, v98, s[42:43]
	v_add_u32_e32 v133, s27, v98
	v_mov_b64_e32 v[126:127], v[234:235]
	v_mov_b64_e32 v[128:129], v[236:237]
	v_mov_b32_e32 v98, 0x2080
	v_mad_u32_u24 v141, v136, s76, v98
	v_cndmask_b32_e64 v147, 0, v35, s[56:57]
	v_cndmask_b32_e64 v146, 0, v34, s[56:57]
	v_cndmask_b32_e64 v149, 0, v41, s[54:55]
	v_cndmask_b32_e64 v148, 0, v40, s[54:55]
	v_add_u32_e32 v124, v95, v141
	s_waitcnt vmcnt(0) lgkmcnt(0)
	v_lshlrev_b32_e32 v98, 16, v8
	v_lshlrev_b32_e32 v118, 16, v9
	v_and_b32_e32 v99, 0xffff0000, v8
	v_and_b32_e32 v119, 0xffff0000, v9
	v_cndmask_b32_e64 v9, 0, v33, s[56:57]
	v_cndmask_b32_e64 v8, 0, v32, s[56:57]
	v_pk_fma_f32 v[118:119], v[146:147], v[118:119], v[6:7]
	v_pk_fma_f32 v[8:9], v[8:9], v[98:99], v[4:5]
	v_lshlrev_b32_e32 v98, 16, v105
	v_lshlrev_b32_e32 v146, 16, v104
	v_and_b32_e32 v99, 0xffff0000, v105
	v_and_b32_e32 v147, 0xffff0000, v104
	v_cndmask_b32_e64 v105, 0, v43, s[54:55]
	v_cndmask_b32_e64 v104, 0, v42, s[54:55]
	v_pk_fma_f32 v[8:9], v[148:149], v[146:147], v[8:9]
	v_pk_fma_f32 v[98:99], v[104:105], v[98:99], v[118:119]
	v_lshlrev_b32_e32 v104, 16, v114
	v_lshlrev_b32_e32 v118, 16, v115
	v_and_b32_e32 v105, 0xffff0000, v114
	v_and_b32_e32 v119, 0xffff0000, v115
	v_cndmask_b32_e64 v115, 0, v69, s[52:53]
	v_cndmask_b32_e64 v114, 0, v68, s[52:53]
	v_cndmask_b32_e64 v147, 0, v71, s[52:53]
	v_cndmask_b32_e64 v146, 0, v70, s[52:53]
	v_pk_fma_f32 v[98:99], v[146:147], v[118:119], v[98:99]
	v_pk_fma_f32 v[8:9], v[114:115], v[104:105], v[8:9]
	v_lshlrev_b32_e32 v104, 16, v127
	v_lshlrev_b32_e32 v114, 16, v126
	v_and_b32_e32 v105, 0xffff0000, v127
	v_and_b32_e32 v115, 0xffff0000, v126
	v_pk_fma_f32 v[114:115], v[82:83], v[114:115], v[8:9]
	v_pk_fma_f32 v[98:99], v[72:73], v[104:105], v[98:99]
	v_cvt_pk_bf16_f32 v8, v114, v115
	v_cvt_pk_bf16_f32 v9, v98, v99
	ds_write2_b32 v124, v98, v99 offset0:2 offset1:3
	ds_write2_b32 v124, v114, v115 offset1:1
	v_lshlrev_b32_e32 v98, 16, v10
	v_lshlrev_b32_e32 v104, 16, v11
	v_and_b32_e32 v99, 0xffff0000, v10
	v_and_b32_e32 v105, 0xffff0000, v11
	v_cndmask_b32_e64 v11, 0, v25, s[56:57]
	v_cndmask_b32_e64 v10, 0, v24, s[56:57]
	v_cndmask_b32_e64 v115, 0, v27, s[56:57]
	v_cndmask_b32_e64 v114, 0, v26, s[56:57]
	v_pk_fma_f32 v[104:105], v[114:115], v[104:105], v[22:23]
	v_pk_fma_f32 v[10:11], v[10:11], v[98:99], v[20:21]
	v_lshlrev_b32_e32 v98, 16, v107
	v_lshlrev_b32_e32 v114, 16, v106
	v_and_b32_e32 v99, 0xffff0000, v107
	v_and_b32_e32 v115, 0xffff0000, v106
	v_cndmask_b32_e64 v107, 0, v31, s[54:55]
	v_cndmask_b32_e64 v106, 0, v30, s[54:55]
	v_cndmask_b32_e64 v119, 0, v29, s[54:55]
	v_cndmask_b32_e64 v118, 0, v28, s[54:55]
	v_pk_fma_f32 v[10:11], v[118:119], v[114:115], v[10:11]
	v_pk_fma_f32 v[98:99], v[106:107], v[98:99], v[104:105]
	v_lshlrev_b32_e32 v104, 16, v116
	v_lshlrev_b32_e32 v106, 16, v117
	v_and_b32_e32 v105, 0xffff0000, v116
	v_and_b32_e32 v107, 0xffff0000, v117
	v_cndmask_b32_e64 v115, 0, v37, s[52:53]
	v_cndmask_b32_e64 v114, 0, v36, s[52:53]
	v_cndmask_b32_e64 v117, 0, v39, s[52:53]
	v_cndmask_b32_e64 v116, 0, v38, s[52:53]
	v_pk_fma_f32 v[98:99], v[116:117], v[106:107], v[98:99]
	v_pk_fma_f32 v[10:11], v[114:115], v[104:105], v[10:11]
	v_lshlrev_b32_e32 v104, 16, v129
	v_and_b32_e32 v105, 0xffff0000, v129
	v_add_u32_e32 v118, s40, v137
	v_lshlrev_b32_e32 v106, 16, v128
	v_and_b32_e32 v107, 0xffff0000, v128
	v_pk_fma_f32 v[98:99], v[74:75], v[104:105], v[98:99]
	v_cmp_lt_i32_e64 s[46:47], -1, v118
	v_pk_fma_f32 v[106:107], v[84:85], v[106:107], v[10:11]
	v_cvt_pk_bf16_f32 v11, v98, v99
	ds_write2_b32 v124, v98, v99 offset0:6 offset1:7
	ds_write2_b32 v124, v106, v107 offset0:4 offset1:5
	v_cndmask_b32_e64 v98, 0, v118, s[46:47]
	v_add_u32_e32 v126, s27, v98
	v_cvt_pk_bf16_f32 v10, v106, v107
	v_mov_b32_dpp v104, v234 row_ror:3 row_mask:0xf bank_mask:0xf
	v_mov_b32_dpp v105, v235 row_ror:3 row_mask:0xf bank_mask:0xf
	v_mov_b32_dpp v106, v236 row_ror:3 row_mask:0xf bank_mask:0xf
	v_mov_b32_dpp v107, v237 row_ror:3 row_mask:0xf bank_mask:0xf
	v_mov_b32_dpp v104, v238 row_shr:3 row_mask:0xf bank_mask:0xf
	v_mov_b32_dpp v105, v239 row_shr:3 row_mask:0xf bank_mask:0xf
	v_mov_b32_dpp v106, v240 row_shr:3 row_mask:0xf bank_mask:0xf
	v_mov_b32_dpp v107, v241 row_shr:3 row_mask:0xf bank_mask:0xf
	v_max_i32_e32 v98, -1, v118
	v_add_u32_e32 v127, s80, v98
	v_mov_b32_dpp v114, v234 row_ror:2 row_mask:0xf bank_mask:0xf
	v_mov_b32_dpp v115, v235 row_ror:2 row_mask:0xf bank_mask:0xf
	v_mov_b32_dpp v116, v236 row_ror:2 row_mask:0xf bank_mask:0xf
	v_mov_b32_dpp v117, v237 row_ror:2 row_mask:0xf bank_mask:0xf
	v_mov_b32_dpp v114, v238 row_shr:2 row_mask:0xf bank_mask:0xf
	v_mov_b32_dpp v115, v239 row_shr:2 row_mask:0xf bank_mask:0xf
	v_mov_b32_dpp v116, v240 row_shr:2 row_mask:0xf bank_mask:0xf
	v_mov_b32_dpp v117, v241 row_shr:2 row_mask:0xf bank_mask:0xf
	v_max_i32_e32 v98, -2, v118
	v_add_u32_e32 v128, s81, v98
	v_mov_b32_dpp v146, v234 row_ror:1 row_mask:0xf bank_mask:0xf
	v_mov_b32_dpp v147, v235 row_ror:1 row_mask:0xf bank_mask:0xf
	v_mov_b32_dpp v148, v236 row_ror:1 row_mask:0xf bank_mask:0xf
	v_mov_b32_dpp v149, v237 row_ror:1 row_mask:0xf bank_mask:0xf
	v_mov_b32_dpp v146, v238 row_shr:1 row_mask:0xf bank_mask:0xf
	v_mov_b32_dpp v147, v239 row_shr:1 row_mask:0xf bank_mask:0xf
	v_mov_b32_dpp v148, v240 row_shr:1 row_mask:0xf bank_mask:0xf
	v_mov_b32_dpp v149, v241 row_shr:1 row_mask:0xf bank_mask:0xf
	v_or_b32_e32 v98, s20, v137
	v_cndmask_b32_e64 v98, 0, v98, s[42:43]
	v_add_u32_e32 v129, s27, v98
	v_mov_b64_e32 v[150:151], v[238:239]
	v_mov_b64_e32 v[152:153], v[240:241]
	v_mov_b32_e32 v80, 0x30c0
	v_cmp_lt_i32_e64 s[40:41], -2, v118
	v_mad_u32_u24 v138, v136, s76, v80
	v_cndmask_b32_e64 v33, 0, v33, s[46:47]
	v_cndmask_b32_e64 v32, 0, v32, s[46:47]
	v_cndmask_b32_e64 v35, 0, v35, s[46:47]
	v_cndmask_b32_e64 v34, 0, v34, s[46:47]
	v_cmp_lt_i32_e32 vcc, -3, v118
	v_cndmask_b32_e64 v43, 0, v43, s[40:41]
	v_cndmask_b32_e64 v42, 0, v42, s[40:41]
	v_cndmask_b32_e64 v41, 0, v41, s[40:41]
	v_cndmask_b32_e64 v40, 0, v40, s[40:41]
	v_add_u32_e32 v120, v95, v138
	v_cndmask_b32_e64 v25, 0, v25, s[46:47]
	v_cndmask_b32_e64 v24, 0, v24, s[46:47]
	v_cndmask_b32_e64 v27, 0, v27, s[46:47]
	v_cndmask_b32_e64 v26, 0, v26, s[46:47]
	v_cndmask_b32_e64 v29, 0, v29, s[40:41]
	v_cndmask_b32_e64 v28, 0, v28, s[40:41]
	s_mov_b64 s[80:81], 0x1080
	s_waitcnt vmcnt(0) lgkmcnt(0)
	v_lshlrev_b32_e32 v80, 16, v104
	v_lshlrev_b32_e32 v98, 16, v105
	v_and_b32_e32 v81, 0xffff0000, v104
	v_and_b32_e32 v99, 0xffff0000, v105
	v_pk_fma_f32 v[6:7], v[34:35], v[98:99], v[6:7]
	v_pk_fma_f32 v[4:5], v[32:33], v[80:81], v[4:5]
	v_lshlrev_b32_e32 v32, 16, v115
	v_lshlrev_b32_e32 v34, 16, v114
	v_and_b32_e32 v33, 0xffff0000, v115
	v_and_b32_e32 v35, 0xffff0000, v114
	v_pk_fma_f32 v[4:5], v[40:41], v[34:35], v[4:5]
	v_pk_fma_f32 v[6:7], v[42:43], v[32:33], v[6:7]
	v_lshlrev_b32_e32 v32, 16, v146
	v_lshlrev_b32_e32 v34, 16, v147
	v_and_b32_e32 v33, 0xffff0000, v146
	v_and_b32_e32 v35, 0xffff0000, v147
	v_cndmask_b32_e32 v41, 0, v69, vcc
	v_cndmask_b32_e32 v40, 0, v68, vcc
	v_cndmask_b32_e32 v43, 0, v71, vcc
	v_cndmask_b32_e32 v42, 0, v70, vcc
	v_pk_fma_f32 v[6:7], v[42:43], v[34:35], v[6:7]
	v_pk_fma_f32 v[4:5], v[40:41], v[32:33], v[4:5]
	v_lshlrev_b32_e32 v32, 16, v151
	v_and_b32_e32 v33, 0xffff0000, v151
	v_lshlrev_b32_e32 v34, 16, v150
	v_and_b32_e32 v35, 0xffff0000, v150
	v_pk_fma_f32 v[6:7], v[72:73], v[32:33], v[6:7]
	v_pk_fma_f32 v[34:35], v[82:83], v[34:35], v[4:5]
	v_cvt_pk_bf16_f32 v5, v6, v7
	ds_write2_b32 v120, v6, v7 offset0:2 offset1:3
	ds_write2_b32 v120, v34, v35 offset1:1
	v_lshlrev_b32_e32 v6, 16, v106
	v_lshlrev_b32_e32 v32, 16, v107
	v_and_b32_e32 v7, 0xffff0000, v106
	v_and_b32_e32 v33, 0xffff0000, v107
	v_pk_fma_f32 v[22:23], v[26:27], v[32:33], v[22:23]
	v_pk_fma_f32 v[6:7], v[24:25], v[6:7], v[20:21]
	v_lshlrev_b32_e32 v20, 16, v117
	v_lshlrev_b32_e32 v24, 16, v116
	v_and_b32_e32 v21, 0xffff0000, v117
	v_and_b32_e32 v25, 0xffff0000, v116
	v_cndmask_b32_e64 v27, 0, v31, s[40:41]
	v_cndmask_b32_e64 v26, 0, v30, s[40:41]
	v_pk_fma_f32 v[6:7], v[28:29], v[24:25], v[6:7]
	v_pk_fma_f32 v[20:21], v[26:27], v[20:21], v[22:23]
	v_lshlrev_b32_e32 v22, 16, v148
	v_lshlrev_b32_e32 v24, 16, v149
	v_and_b32_e32 v23, 0xffff0000, v148
	v_and_b32_e32 v25, 0xffff0000, v149
	v_cndmask_b32_e32 v27, 0, v37, vcc
	v_cndmask_b32_e32 v26, 0, v36, vcc
	v_cndmask_b32_e32 v29, 0, v39, vcc
	v_cndmask_b32_e32 v28, 0, v38, vcc
	v_pk_fma_f32 v[20:21], v[28:29], v[24:25], v[20:21]
	v_pk_fma_f32 v[6:7], v[26:27], v[22:23], v[6:7]
	v_lshlrev_b32_e32 v22, 16, v153
	v_and_b32_e32 v23, 0xffff0000, v153
	v_lshlrev_b32_e32 v24, 16, v152
	v_and_b32_e32 v25, 0xffff0000, v152
	v_pk_fma_f32 v[20:21], v[74:75], v[22:23], v[20:21]
	v_pk_fma_f32 v[24:25], v[84:85], v[24:25], v[6:7]
	v_cvt_pk_bf16_f32 v7, v20, v21
	ds_write2_b32 v120, v20, v21 offset0:6 offset1:7
	ds_write2_b32 v120, v24, v25 offset0:4 offset1:5
	v_add_u32_e32 v20, 32, v78
	v_ashrrev_i32_e32 v21, 31, v20
	v_lshl_add_u64 v[84:85], v[86:87], 0, s[80:81]
	s_mov_b64 s[80:81], 0x1880
	v_lshl_add_u64 v[106:107], v[86:87], 0, s[80:81]
	v_lshlrev_b64 v[104:105], 1, v[20:21]
	v_mov_b32_dpp v80, v242 row_ror:3 row_mask:0xf bank_mask:0xf
	v_mov_b32_dpp v81, v243 row_ror:3 row_mask:0xf bank_mask:0xf
	v_mov_b32_dpp v82, v244 row_ror:3 row_mask:0xf bank_mask:0xf
	v_mov_b32_dpp v83, v245 row_ror:3 row_mask:0xf bank_mask:0xf
	v_mov_b32_dpp v80, v246 row_shr:3 row_mask:0xf bank_mask:0xf
	v_mov_b32_dpp v81, v247 row_shr:3 row_mask:0xf bank_mask:0xf
	v_mov_b32_dpp v82, v248 row_shr:3 row_mask:0xf bank_mask:0xf
	v_mov_b32_dpp v83, v249 row_shr:3 row_mask:0xf bank_mask:0xf
	v_cvt_pk_bf16_f32 v4, v34, v35
	v_mov_b32_dpp v32, v242 row_ror:2 row_mask:0xf bank_mask:0xf
	v_mov_b32_dpp v33, v243 row_ror:2 row_mask:0xf bank_mask:0xf
	v_mov_b32_dpp v34, v244 row_ror:2 row_mask:0xf bank_mask:0xf
	v_mov_b32_dpp v35, v245 row_ror:2 row_mask:0xf bank_mask:0xf
	v_mov_b32_dpp v32, v246 row_shr:2 row_mask:0xf bank_mask:0xf
	v_mov_b32_dpp v33, v247 row_shr:2 row_mask:0xf bank_mask:0xf
	v_mov_b32_dpp v34, v248 row_shr:2 row_mask:0xf bank_mask:0xf
	v_mov_b32_dpp v35, v249 row_shr:2 row_mask:0xf bank_mask:0xf
	v_mov_b32_dpp v28, v242 row_ror:1 row_mask:0xf bank_mask:0xf
	v_mov_b32_dpp v29, v243 row_ror:1 row_mask:0xf bank_mask:0xf
	v_mov_b32_dpp v30, v244 row_ror:1 row_mask:0xf bank_mask:0xf
	v_mov_b32_dpp v31, v245 row_ror:1 row_mask:0xf bank_mask:0xf
	v_mov_b32_dpp v28, v246 row_shr:1 row_mask:0xf bank_mask:0xf
	v_mov_b32_dpp v29, v247 row_shr:1 row_mask:0xf bank_mask:0xf
	v_mov_b32_dpp v30, v248 row_shr:1 row_mask:0xf bank_mask:0xf
	v_mov_b32_dpp v31, v249 row_shr:1 row_mask:0xf bank_mask:0xf
	v_cvt_pk_bf16_f32 v6, v24, v25
	v_mov_b64_e32 v[24:25], v[246:247]
	v_mov_b64_e32 v[26:27], v[248:249]
	global_load_dwordx4 v[40:43], v[76:77], off offset:144
	global_load_dwordx4 v[72:75], v[76:77], off offset:128
	global_load_dwordx4 v[68:71], v[86:87], off offset:144
	s_nop 0
	global_load_dwordx4 v[76:79], v[86:87], off offset:128
	global_load_dwordx4 v[36:39], v[86:87], off offset:2192
	global_load_dwordx4 v[20:23], v[86:87], off offset:2176
	global_load_dwordx4 v[92:95], v[96:97], off offset:128
	s_nop 0
	global_load_dwordx4 v[84:87], v[84:85], off offset:16
	s_nop 0
	global_load_dwordx4 v[96:99], v[96:97], off offset:2176
	s_nop 0
	global_load_dwordx4 v[146:149], v[106:107], off offset:16
	s_waitcnt vmcnt(0) lgkmcnt(0)
	v_lshlrev_b32_e32 v106, 16, v80
	v_lshlrev_b32_e32 v114, 16, v81
	v_and_b32_e32 v107, 0xffff0000, v80
	v_and_b32_e32 v115, 0xffff0000, v81
	v_cndmask_b32_e64 v81, 0, v77, s[50:51]
	v_cndmask_b32_e64 v80, 0, v76, s[50:51]
	v_cndmask_b32_e64 v117, 0, v79, s[50:51]
	v_cndmask_b32_e64 v116, 0, v78, s[50:51]
	v_pk_fma_f32 v[114:115], v[116:117], v[114:115], v[74:75]
	v_pk_fma_f32 v[80:81], v[80:81], v[106:107], v[72:73]
	v_lshlrev_b32_e32 v106, 16, v33
	v_lshlrev_b32_e32 v116, 16, v32
	v_and_b32_e32 v107, 0xffff0000, v33
	v_and_b32_e32 v117, 0xffff0000, v32
	v_cndmask_b32_e64 v33, 0, v23, s[48:49]
	v_cndmask_b32_e64 v32, 0, v22, s[48:49]
	v_cndmask_b32_e64 v119, 0, v21, s[48:49]
	v_cndmask_b32_e64 v118, 0, v20, s[48:49]
	v_pk_fma_f32 v[80:81], v[118:119], v[116:117], v[80:81]
	v_pk_fma_f32 v[32:33], v[32:33], v[106:107], v[114:115]
	v_lshlrev_b32_e32 v106, 16, v28
	v_lshlrev_b32_e32 v114, 16, v29
	v_and_b32_e32 v107, 0xffff0000, v28
	v_and_b32_e32 v115, 0xffff0000, v29
	v_cndmask_b32_e64 v29, 0, v93, s[44:45]
	v_cndmask_b32_e64 v28, 0, v92, s[44:45]
	v_cndmask_b32_e64 v117, 0, v95, s[44:45]
	v_cndmask_b32_e64 v116, 0, v94, s[44:45]
	v_pk_fma_f32 v[32:33], v[116:117], v[114:115], v[32:33]
	v_pk_fma_f32 v[28:29], v[28:29], v[106:107], v[80:81]
	v_lshlrev_b32_e32 v80, 16, v25
	v_lshlrev_b32_e32 v116, 16, v24
	v_and_b32_e32 v81, 0xffff0000, v25
	v_and_b32_e32 v117, 0xffff0000, v24
	v_cndmask_b32_e64 v107, 0, v99, s[42:43]
	v_cndmask_b32_e64 v106, 0, v98, s[42:43]
	v_cndmask_b32_e64 v115, 0, v97, s[42:43]
	v_cndmask_b32_e64 v114, 0, v96, s[42:43]
	v_pk_fma_f32 v[24:25], v[114:115], v[116:117], v[28:29]
	v_pk_fma_f32 v[28:29], v[106:107], v[80:81], v[32:33]
	v_cvt_pk_bf16_f32 v32, v24, v25
	v_cvt_pk_bf16_f32 v33, v28, v29
	ds_write2_b32 v121, v28, v29 offset0:34 offset1:35
	ds_write2_b32 v121, v24, v25 offset0:32 offset1:33
	v_lshlrev_b32_e32 v24, 16, v82
	v_lshlrev_b32_e32 v28, 16, v83
	v_and_b32_e32 v25, 0xffff0000, v82
	v_and_b32_e32 v29, 0xffff0000, v83
	v_cndmask_b32_e64 v81, 0, v69, s[50:51]
	v_cndmask_b32_e64 v80, 0, v68, s[50:51]
	v_cndmask_b32_e64 v83, 0, v71, s[50:51]
	v_cndmask_b32_e64 v82, 0, v70, s[50:51]
	v_pk_fma_f32 v[28:29], v[82:83], v[28:29], v[42:43]
	v_pk_fma_f32 v[24:25], v[80:81], v[24:25], v[40:41]
	v_lshlrev_b32_e32 v80, 16, v35
	v_lshlrev_b32_e32 v82, 16, v34
	v_and_b32_e32 v81, 0xffff0000, v35
	v_and_b32_e32 v83, 0xffff0000, v34
	v_cndmask_b32_e64 v35, 0, v39, s[48:49]
	v_cndmask_b32_e64 v34, 0, v38, s[48:49]
	v_cndmask_b32_e64 v97, 0, v37, s[48:49]
	v_cndmask_b32_e64 v96, 0, v36, s[48:49]
	v_pk_fma_f32 v[24:25], v[96:97], v[82:83], v[24:25]
	v_pk_fma_f32 v[28:29], v[34:35], v[80:81], v[28:29]
	v_lshlrev_b32_e32 v34, 16, v30
	v_lshlrev_b32_e32 v80, 16, v31
	v_and_b32_e32 v35, 0xffff0000, v30
	v_and_b32_e32 v81, 0xffff0000, v31
	v_cndmask_b32_e64 v31, 0, v85, s[44:45]
	v_cndmask_b32_e64 v30, 0, v84, s[44:45]
	v_cndmask_b32_e64 v83, 0, v87, s[44:45]
	v_cndmask_b32_e64 v82, 0, v86, s[44:45]
	v_pk_fma_f32 v[28:29], v[82:83], v[80:81], v[28:29]
	v_pk_fma_f32 v[24:25], v[30:31], v[34:35], v[24:25]
	v_lshlrev_b32_e32 v30, 16, v27
	v_lshlrev_b32_e32 v34, 16, v26
	v_and_b32_e32 v31, 0xffff0000, v27
	v_and_b32_e32 v35, 0xffff0000, v26
	v_cndmask_b32_e64 v117, 0, v149, s[42:43]
	v_cndmask_b32_e64 v116, 0, v148, s[42:43]
	v_cndmask_b32_e64 v119, 0, v147, s[42:43]
	v_cndmask_b32_e64 v118, 0, v146, s[42:43]
	v_pk_fma_f32 v[24:25], v[118:119], v[34:35], v[24:25]
	v_pk_fma_f32 v[26:27], v[116:117], v[30:31], v[28:29]
	v_cvt_pk_bf16_f32 v34, v24, v25
	ds_write2_b32 v121, v26, v27 offset0:38 offset1:39
	ds_write2_b32 v121, v24, v25 offset0:36 offset1:37
	v_cvt_pk_bf16_f32 v35, v26, v27
	v_mov_b32_dpp v24, v246 row_ror:3 row_mask:0xf bank_mask:0xf
	v_mov_b32_dpp v25, v247 row_ror:3 row_mask:0xf bank_mask:0xf
	v_mov_b32_dpp v26, v248 row_ror:3 row_mask:0xf bank_mask:0xf
	v_mov_b32_dpp v27, v249 row_ror:3 row_mask:0xf bank_mask:0xf
	v_mov_b32_dpp v24, v250 row_shr:3 row_mask:0xf bank_mask:0xf
	v_mov_b32_dpp v25, v251 row_shr:3 row_mask:0xf bank_mask:0xf
	v_mov_b32_dpp v26, v252 row_shr:3 row_mask:0xf bank_mask:0xf
	v_mov_b32_dpp v27, v253 row_shr:3 row_mask:0xf bank_mask:0xf
	v_mov_b32_dpp v28, v246 row_ror:2 row_mask:0xf bank_mask:0xf
	v_mov_b32_dpp v29, v247 row_ror:2 row_mask:0xf bank_mask:0xf
	v_mov_b32_dpp v30, v248 row_ror:2 row_mask:0xf bank_mask:0xf
	v_mov_b32_dpp v31, v249 row_ror:2 row_mask:0xf bank_mask:0xf
	v_mov_b32_dpp v28, v250 row_shr:2 row_mask:0xf bank_mask:0xf
	v_mov_b32_dpp v29, v251 row_shr:2 row_mask:0xf bank_mask:0xf
	v_mov_b32_dpp v30, v252 row_shr:2 row_mask:0xf bank_mask:0xf
	v_mov_b32_dpp v31, v253 row_shr:2 row_mask:0xf bank_mask:0xf
	v_mov_b32_dpp v80, v246 row_ror:1 row_mask:0xf bank_mask:0xf
	v_mov_b32_dpp v81, v247 row_ror:1 row_mask:0xf bank_mask:0xf
	v_mov_b32_dpp v82, v248 row_ror:1 row_mask:0xf bank_mask:0xf
	v_mov_b32_dpp v83, v249 row_ror:1 row_mask:0xf bank_mask:0xf
	v_mov_b32_dpp v80, v250 row_shr:1 row_mask:0xf bank_mask:0xf
	v_mov_b32_dpp v81, v251 row_shr:1 row_mask:0xf bank_mask:0xf
	v_mov_b32_dpp v82, v252 row_shr:1 row_mask:0xf bank_mask:0xf
	v_mov_b32_dpp v83, v253 row_shr:1 row_mask:0xf bank_mask:0xf
	v_mov_b64_e32 v[96:97], v[250:251]
	v_mov_b64_e32 v[98:99], v[252:253]
	v_cndmask_b32_e64 v147, 0, v79, s[62:63]
	v_cndmask_b32_e64 v146, 0, v78, s[62:63]
	v_cndmask_b32_e64 v149, 0, v21, s[60:61]
	v_cndmask_b32_e64 v148, 0, v20, s[60:61]
	s_add_i32 s48, s20, s27
	s_lshl_b32 s20, s91, 7
	s_add_u32 s44, s10, s20
	s_addc_u32 s45, s11, 0
	s_waitcnt vmcnt(0) lgkmcnt(0)
	v_lshlrev_b32_e32 v134, 16, v24
	v_lshlrev_b32_e32 v142, 16, v25
	v_and_b32_e32 v135, 0xffff0000, v24
	v_and_b32_e32 v143, 0xffff0000, v25
	v_cndmask_b32_e64 v25, 0, v77, s[62:63]
	v_cndmask_b32_e64 v24, 0, v76, s[62:63]
	v_pk_fma_f32 v[142:143], v[146:147], v[142:143], v[74:75]
	v_pk_fma_f32 v[24:25], v[24:25], v[134:135], v[72:73]
	v_lshlrev_b32_e32 v134, 16, v29
	v_lshlrev_b32_e32 v146, 16, v28
	v_and_b32_e32 v135, 0xffff0000, v29
	v_and_b32_e32 v147, 0xffff0000, v28
	v_cndmask_b32_e64 v29, 0, v23, s[60:61]
	v_cndmask_b32_e64 v28, 0, v22, s[60:61]
	v_pk_fma_f32 v[24:25], v[148:149], v[146:147], v[24:25]
	v_pk_fma_f32 v[28:29], v[28:29], v[134:135], v[142:143]
	v_lshlrev_b32_e32 v134, 16, v80
	v_lshlrev_b32_e32 v142, 16, v81
	v_and_b32_e32 v135, 0xffff0000, v80
	v_and_b32_e32 v143, 0xffff0000, v81
	v_cndmask_b32_e64 v81, 0, v93, s[58:59]
	v_cndmask_b32_e64 v80, 0, v92, s[58:59]
	v_cndmask_b32_e64 v147, 0, v95, s[58:59]
	v_cndmask_b32_e64 v146, 0, v94, s[58:59]
	v_pk_fma_f32 v[28:29], v[146:147], v[142:143], v[28:29]
	v_pk_fma_f32 v[24:25], v[80:81], v[134:135], v[24:25]
	v_lshlrev_b32_e32 v80, 16, v97
	v_lshlrev_b32_e32 v134, 16, v96
	v_and_b32_e32 v81, 0xffff0000, v97
	v_and_b32_e32 v135, 0xffff0000, v96
	v_pk_fma_f32 v[24:25], v[114:115], v[134:135], v[24:25]
	v_pk_fma_f32 v[80:81], v[106:107], v[80:81], v[28:29]
	v_cvt_pk_bf16_f32 v28, v24, v25
	v_cvt_pk_bf16_f32 v29, v80, v81
	ds_write2_b32 v125, v80, v81 offset0:34 offset1:35
	ds_write2_b32 v125, v24, v25 offset0:32 offset1:33
	v_lshlrev_b32_e32 v24, 16, v26
	v_lshlrev_b32_e32 v80, 16, v27
	v_and_b32_e32 v25, 0xffff0000, v26
	v_and_b32_e32 v81, 0xffff0000, v27
	v_cndmask_b32_e64 v27, 0, v69, s[62:63]
	v_cndmask_b32_e64 v26, 0, v68, s[62:63]
	v_cndmask_b32_e64 v97, 0, v71, s[62:63]
	v_cndmask_b32_e64 v96, 0, v70, s[62:63]
	v_pk_fma_f32 v[80:81], v[96:97], v[80:81], v[42:43]
	v_pk_fma_f32 v[24:25], v[26:27], v[24:25], v[40:41]
	v_lshlrev_b32_e32 v26, 16, v31
	v_lshlrev_b32_e32 v96, 16, v30
	v_and_b32_e32 v27, 0xffff0000, v31
	v_and_b32_e32 v97, 0xffff0000, v30
	v_cndmask_b32_e64 v31, 0, v39, s[60:61]
	v_cndmask_b32_e64 v30, 0, v38, s[60:61]
	v_cndmask_b32_e64 v135, 0, v37, s[60:61]
	v_cndmask_b32_e64 v134, 0, v36, s[60:61]
	v_pk_fma_f32 v[24:25], v[134:135], v[96:97], v[24:25]
	v_pk_fma_f32 v[26:27], v[30:31], v[26:27], v[80:81]
	v_lshlrev_b32_e32 v30, 16, v82
	v_lshlrev_b32_e32 v80, 16, v83
	v_and_b32_e32 v31, 0xffff0000, v82
	v_and_b32_e32 v81, 0xffff0000, v83
	v_cndmask_b32_e64 v83, 0, v85, s[58:59]
	v_cndmask_b32_e64 v82, 0, v84, s[58:59]
	v_cndmask_b32_e64 v97, 0, v87, s[58:59]
	v_cndmask_b32_e64 v96, 0, v86, s[58:59]
	v_pk_fma_f32 v[26:27], v[96:97], v[80:81], v[26:27]
	v_pk_fma_f32 v[24:25], v[82:83], v[30:31], v[24:25]
	v_lshlrev_b32_e32 v30, 16, v99
	v_lshlrev_b32_e32 v80, 16, v98
	v_and_b32_e32 v31, 0xffff0000, v99
	v_and_b32_e32 v81, 0xffff0000, v98
	v_pk_fma_f32 v[24:25], v[118:119], v[80:81], v[24:25]
	v_pk_fma_f32 v[26:27], v[116:117], v[30:31], v[26:27]
	v_cvt_pk_bf16_f32 v30, v24, v25
	ds_write2_b32 v125, v26, v27 offset0:38 offset1:39
	ds_write2_b32 v125, v24, v25 offset0:36 offset1:37
	v_cvt_pk_bf16_f32 v31, v26, v27
	v_mov_b32_dpp v24, v250 row_ror:3 row_mask:0xf bank_mask:0xf
	v_mov_b32_dpp v25, v251 row_ror:3 row_mask:0xf bank_mask:0xf
	v_mov_b32_dpp v26, v252 row_ror:3 row_mask:0xf bank_mask:0xf
	v_mov_b32_dpp v27, v253 row_ror:3 row_mask:0xf bank_mask:0xf
	v_mov_b32_dpp v24, v190 row_shr:3 row_mask:0xf bank_mask:0xf
	v_mov_b32_dpp v25, v191 row_shr:3 row_mask:0xf bank_mask:0xf
	v_mov_b32_dpp v26, v192 row_shr:3 row_mask:0xf bank_mask:0xf
	v_mov_b32_dpp v27, v193 row_shr:3 row_mask:0xf bank_mask:0xf
	v_mov_b32_dpp v80, v250 row_ror:2 row_mask:0xf bank_mask:0xf
	v_mov_b32_dpp v81, v251 row_ror:2 row_mask:0xf bank_mask:0xf
	v_mov_b32_dpp v82, v252 row_ror:2 row_mask:0xf bank_mask:0xf
	v_mov_b32_dpp v83, v253 row_ror:2 row_mask:0xf bank_mask:0xf
	v_mov_b32_dpp v80, v190 row_shr:2 row_mask:0xf bank_mask:0xf
	v_mov_b32_dpp v81, v191 row_shr:2 row_mask:0xf bank_mask:0xf
	v_mov_b32_dpp v82, v192 row_shr:2 row_mask:0xf bank_mask:0xf
	v_mov_b32_dpp v83, v193 row_shr:2 row_mask:0xf bank_mask:0xf
	v_mov_b32_dpp v96, v250 row_ror:1 row_mask:0xf bank_mask:0xf
	v_mov_b32_dpp v97, v251 row_ror:1 row_mask:0xf bank_mask:0xf
	v_mov_b32_dpp v98, v252 row_ror:1 row_mask:0xf bank_mask:0xf
	v_mov_b32_dpp v99, v253 row_ror:1 row_mask:0xf bank_mask:0xf
	v_mov_b32_dpp v96, v190 row_shr:1 row_mask:0xf bank_mask:0xf
	v_mov_b32_dpp v97, v191 row_shr:1 row_mask:0xf bank_mask:0xf
	v_mov_b32_dpp v98, v192 row_shr:1 row_mask:0xf bank_mask:0xf
	v_mov_b32_dpp v99, v193 row_shr:1 row_mask:0xf bank_mask:0xf
	v_mov_b64_e32 v[130:131], v[190:191]
	v_mov_b64_e32 v[132:133], v[192:193]
	v_cndmask_b32_e64 v147, 0, v79, s[56:57]
	v_cndmask_b32_e64 v146, 0, v78, s[56:57]
	v_cndmask_b32_e64 v149, 0, v21, s[54:55]
	v_cndmask_b32_e64 v148, 0, v20, s[54:55]
	v_cndmask_b32_e64 v79, 0, v79, s[46:47]
	v_cndmask_b32_e64 v78, 0, v78, s[46:47]
	v_cndmask_b32_e64 v21, 0, v21, s[40:41]
	v_cndmask_b32_e64 v20, 0, v20, s[40:41]
	s_waitcnt vmcnt(0) lgkmcnt(0)
	v_lshlrev_b32_e32 v134, 16, v24
	v_lshlrev_b32_e32 v142, 16, v25
	v_and_b32_e32 v135, 0xffff0000, v24
	v_and_b32_e32 v143, 0xffff0000, v25
	v_cndmask_b32_e64 v25, 0, v77, s[56:57]
	v_cndmask_b32_e64 v24, 0, v76, s[56:57]
	v_pk_fma_f32 v[142:143], v[146:147], v[142:143], v[74:75]
	v_pk_fma_f32 v[24:25], v[24:25], v[134:135], v[72:73]
	v_lshlrev_b32_e32 v134, 16, v81
	v_lshlrev_b32_e32 v146, 16, v80
	v_and_b32_e32 v135, 0xffff0000, v81
	v_and_b32_e32 v147, 0xffff0000, v80
	v_cndmask_b32_e64 v81, 0, v23, s[54:55]
	v_cndmask_b32_e64 v80, 0, v22, s[54:55]
	v_pk_fma_f32 v[24:25], v[148:149], v[146:147], v[24:25]
	v_pk_fma_f32 v[80:81], v[80:81], v[134:135], v[142:143]
	v_lshlrev_b32_e32 v134, 16, v96
	v_lshlrev_b32_e32 v142, 16, v97
	v_and_b32_e32 v135, 0xffff0000, v96
	v_and_b32_e32 v143, 0xffff0000, v97
	v_cndmask_b32_e64 v97, 0, v93, s[52:53]
	v_cndmask_b32_e64 v96, 0, v92, s[52:53]
	v_cndmask_b32_e64 v147, 0, v95, s[52:53]
	v_cndmask_b32_e64 v146, 0, v94, s[52:53]
	v_pk_fma_f32 v[80:81], v[146:147], v[142:143], v[80:81]
	v_pk_fma_f32 v[24:25], v[96:97], v[134:135], v[24:25]
	v_lshlrev_b32_e32 v96, 16, v131
	v_lshlrev_b32_e32 v134, 16, v130
	v_and_b32_e32 v97, 0xffff0000, v131
	v_and_b32_e32 v135, 0xffff0000, v130
	v_pk_fma_f32 v[130:131], v[114:115], v[134:135], v[24:25]
	v_pk_fma_f32 v[80:81], v[106:107], v[96:97], v[80:81]
	v_cvt_pk_bf16_f32 v24, v130, v131
	v_cvt_pk_bf16_f32 v25, v80, v81
	ds_write2_b32 v124, v80, v81 offset0:34 offset1:35
	ds_write2_b32 v124, v130, v131 offset0:32 offset1:33
	v_lshlrev_b32_e32 v80, 16, v26
	v_lshlrev_b32_e32 v96, 16, v27
	v_and_b32_e32 v81, 0xffff0000, v26
	v_and_b32_e32 v97, 0xffff0000, v27
	v_cndmask_b32_e64 v27, 0, v69, s[56:57]
	v_cndmask_b32_e64 v26, 0, v68, s[56:57]
	v_cndmask_b32_e64 v131, 0, v71, s[56:57]
	v_cndmask_b32_e64 v130, 0, v70, s[56:57]
	v_pk_fma_f32 v[96:97], v[130:131], v[96:97], v[42:43]
	v_pk_fma_f32 v[26:27], v[26:27], v[80:81], v[40:41]
	v_lshlrev_b32_e32 v80, 16, v83
	v_lshlrev_b32_e32 v130, 16, v82
	v_and_b32_e32 v81, 0xffff0000, v83
	v_and_b32_e32 v131, 0xffff0000, v82
	v_cndmask_b32_e64 v83, 0, v39, s[54:55]
	v_cndmask_b32_e64 v82, 0, v38, s[54:55]
	v_cndmask_b32_e64 v135, 0, v37, s[54:55]
	v_cndmask_b32_e64 v134, 0, v36, s[54:55]
	v_pk_fma_f32 v[26:27], v[134:135], v[130:131], v[26:27]
	v_pk_fma_f32 v[80:81], v[82:83], v[80:81], v[96:97]
	v_lshlrev_b32_e32 v82, 16, v98
	v_lshlrev_b32_e32 v96, 16, v99
	v_and_b32_e32 v83, 0xffff0000, v98
	v_and_b32_e32 v97, 0xffff0000, v99
	v_cndmask_b32_e64 v99, 0, v85, s[52:53]
	v_cndmask_b32_e64 v98, 0, v84, s[52:53]
	v_cndmask_b32_e64 v131, 0, v87, s[52:53]
	v_cndmask_b32_e64 v130, 0, v86, s[52:53]
	v_pk_fma_f32 v[80:81], v[130:131], v[96:97], v[80:81]
	v_pk_fma_f32 v[26:27], v[98:99], v[82:83], v[26:27]
	v_lshlrev_b32_e32 v82, 16, v133
	v_and_b32_e32 v83, 0xffff0000, v133
	v_lshlrev_b32_e32 v96, 16, v132
	v_and_b32_e32 v97, 0xffff0000, v132
	v_pk_fma_f32 v[80:81], v[116:117], v[82:83], v[80:81]
	v_pk_fma_f32 v[96:97], v[118:119], v[96:97], v[26:27]
	v_cvt_pk_bf16_f32 v27, v80, v81
	ds_write2_b32 v124, v80, v81 offset0:38 offset1:39
	ds_write2_b32 v124, v96, v97 offset0:36 offset1:37
	v_mov_b32_dpp v130, v190 row_ror:3 row_mask:0xf bank_mask:0xf
	v_mov_b32_dpp v131, v191 row_ror:3 row_mask:0xf bank_mask:0xf
	v_mov_b32_dpp v132, v192 row_ror:3 row_mask:0xf bank_mask:0xf
	v_mov_b32_dpp v133, v193 row_ror:3 row_mask:0xf bank_mask:0xf
	v_mov_b32_dpp v130, v194 row_shr:3 row_mask:0xf bank_mask:0xf
	v_mov_b32_dpp v131, v195 row_shr:3 row_mask:0xf bank_mask:0xf
	v_mov_b32_dpp v132, v196 row_shr:3 row_mask:0xf bank_mask:0xf
	v_mov_b32_dpp v133, v197 row_shr:3 row_mask:0xf bank_mask:0xf
	v_mov_b32_dpp v124, v190 row_ror:2 row_mask:0xf bank_mask:0xf
	v_mov_b32_dpp v125, v191 row_ror:2 row_mask:0xf bank_mask:0xf
	v_mov_b32_dpp v126, v192 row_ror:2 row_mask:0xf bank_mask:0xf
	v_mov_b32_dpp v127, v193 row_ror:2 row_mask:0xf bank_mask:0xf
	v_mov_b32_dpp v124, v194 row_shr:2 row_mask:0xf bank_mask:0xf
	v_mov_b32_dpp v125, v195 row_shr:2 row_mask:0xf bank_mask:0xf
	v_mov_b32_dpp v126, v196 row_shr:2 row_mask:0xf bank_mask:0xf
	v_mov_b32_dpp v127, v197 row_shr:2 row_mask:0xf bank_mask:0xf
	v_cvt_pk_bf16_f32 v26, v96, v97
	v_mov_b32_dpp v96, v190 row_ror:1 row_mask:0xf bank_mask:0xf
	v_mov_b32_dpp v97, v191 row_ror:1 row_mask:0xf bank_mask:0xf
	v_mov_b32_dpp v98, v192 row_ror:1 row_mask:0xf bank_mask:0xf
	v_mov_b32_dpp v99, v193 row_ror:1 row_mask:0xf bank_mask:0xf
	v_mov_b32_dpp v96, v194 row_shr:1 row_mask:0xf bank_mask:0xf
	v_mov_b32_dpp v97, v195 row_shr:1 row_mask:0xf bank_mask:0xf
	v_mov_b32_dpp v98, v196 row_shr:1 row_mask:0xf bank_mask:0xf
	v_mov_b32_dpp v99, v197 row_shr:1 row_mask:0xf bank_mask:0xf
	v_mov_b64_e32 v[80:81], v[194:195]
	v_mov_b64_e32 v[82:83], v[196:197]
	v_cndmask_b32_e64 v77, 0, v77, s[46:47]
	v_cndmask_b32_e64 v76, 0, v76, s[46:47]
	v_cndmask_b32_e64 v23, 0, v23, s[40:41]
	v_cndmask_b32_e64 v22, 0, v22, s[40:41]
	v_cndmask_b32_e64 v69, 0, v69, s[46:47]
	v_cndmask_b32_e64 v68, 0, v68, s[46:47]
	v_cndmask_b32_e64 v71, 0, v71, s[46:47]
	v_cndmask_b32_e64 v70, 0, v70, s[46:47]
	v_cndmask_b32_e64 v39, 0, v39, s[40:41]
	v_cndmask_b32_e64 v38, 0, v38, s[40:41]
	v_cndmask_b32_e64 v37, 0, v37, s[40:41]
	v_cndmask_b32_e64 v36, 0, v36, s[40:41]
	s_add_u32 s46, s71, s20
	s_addc_u32 s47, s64, 0
	s_ashr_i32 s91, s90, 31
	s_lshl_b64 s[42:43], s[90:91], 9
	s_or_b32 s42, s42, s21
	s_waitcnt vmcnt(0) lgkmcnt(0)
; __device__ __forceinline__ void w_lru_m1(const Args& a, int l, unsigned char* ws, const bf16_t* proj, bf16_t* y, LAS unsigned char* wl, int b, int ck_, int h, int lane) {
;     ...
;         for (int tb = 0; tb < 4; ++tb) { const int tok = 16 * tb + lo, t = 64 * ck_ + tok; float s[8];
; #pragma unroll
;             for (int j = 0; j < 8; ++j) s[j] = bs[j];
; #pragma unroll
;             for (int k = 0; k < 4; ++k) { const int tt = t - 3 + k; float x[8];
;                 ld8bf(proj + (size_t)(b * SEQ + (tt >= 0 ? tt : 0)) * NIN + C_LX + ch0, x);
; #pragma unroll
;                 for (int j = 0; j < 8; ++j) s[j] += (tt >= 0 ? w[k][j] : 0.f) * x[j]; }
;             Xf[tb][kk] = pack_frag(s);
; #pragma unroll
;             for (int j = 0; j < 8; ++j) xcf[tok * 65 + 32 * kk + 8 * fq + j] = s[j]; }
;     }
;     WAVE_LDS_FENCE();
; #pragma unroll
;     for (int jb = 0; jb < 4; ++jb) {
;         bf16x8 WaF[2], WxF[2]; f32x4 pba, pbx, plam;
; #pragma unroll
;         for (int kk = 0; kk < 2; ++kk) { WaF[kk] = nWa[kk]; WxF[kk] = nWx[kk]; }
;         pba = nba; pbx = nbx; plam = nlam;
;         if (jb < 3) {
; #pragma unroll
;             for (int kk = 0; kk < 2; ++kk) { nWa[kk] = *(const bf16x8*)(waT + (16 * (jb + 1) + lo) * 64 + 32 * kk + 8 * fq); nWx[kk] = *(const bf16x8*)(wxT + (16 * (jb + 1) + lo) * 64 + 32 * kk + 8 * fq); }
;             nba = *(const f32x4*)(ba + 16 * (jb + 1) + 4 * fq); nbx = *(const f32x4*)(bx + 16 * (jb + 1) + 4 * fq); nlam = *(const f32x4*)(lam + 16 * (jb + 1) + 4 * fq);
;         }
;         const int j0 = 16 * jb + 4 * fq;
;         float bav[4], bxv[4], sp[4], hc[4], Pc[4];
; #pragma unroll
;         for (int r = 0; r < 4; ++r) { bav[r] = pba[r]; bxv[r] = pbx[r]; sp[r] = log1pf(__expf(-plam[r])); hc[r] = 0.f; Pc[r] = 1.f; }
; #pragma unroll
;         for (int tb = 0; tb < 4; ++tb) { const int tok = 16 * tb + lo;
;             f32x4 ga = {0.f, 0.f, 0.f, 0.f}, gx = {0.f, 0.f, 0.f, 0.f};
; #pragma unroll
;             for (int kk = 0; kk < 2; ++kk) { ga = __builtin_amdgcn_mfma_f32_16x16x32_bf16(WaF[kk], Xf[tb][kk], ga, 0, 0, 0); gx = __builtin_amdgcn_mfma_f32_16x16x32_bf16(WxF[kk], Xf[tb][kk], gx, 0, 0, 0); }
;             float hv[4], pv[4];
; #pragma unroll
;             for (int r = 0; r < 4; ++r) {
;                 const float rg = sigmoidf_(ga[r] + bav[r]), ig = sigmoidf_(gx[r] + bxv[r]);
	v_lshlrev_b32_e32 v102, 16, v130
	v_lshlrev_b32_e32 v104, 16, v131
	v_and_b32_e32 v103, 0xffff0000, v130
	v_and_b32_e32 v105, 0xffff0000, v131
	v_pk_fma_f32 v[74:75], v[78:79], v[104:105], v[74:75]
	v_pk_fma_f32 v[72:73], v[76:77], v[102:103], v[72:73]
	v_lshlrev_b32_e32 v76, 16, v125
	v_lshlrev_b32_e32 v78, 16, v124
	v_and_b32_e32 v77, 0xffff0000, v125
	v_and_b32_e32 v79, 0xffff0000, v124
	v_pk_fma_f32 v[20:21], v[20:21], v[78:79], v[72:73]
	v_pk_fma_f32 v[22:23], v[22:23], v[76:77], v[74:75]
	v_lshlrev_b32_e32 v72, 16, v96
	v_lshlrev_b32_e32 v74, 16, v97
	v_and_b32_e32 v73, 0xffff0000, v96
	v_and_b32_e32 v75, 0xffff0000, v97
	v_cndmask_b32_e32 v77, 0, v93, vcc
	v_cndmask_b32_e32 v76, 0, v92, vcc
	v_cndmask_b32_e32 v79, 0, v95, vcc
	v_cndmask_b32_e32 v78, 0, v94, vcc
	v_pk_fma_f32 v[22:23], v[78:79], v[74:75], v[22:23]
	v_pk_fma_f32 v[20:21], v[76:77], v[72:73], v[20:21]
	v_lshlrev_b32_e32 v72, 16, v81
	v_and_b32_e32 v73, 0xffff0000, v81
	v_lshlrev_b32_e32 v74, 16, v80
	v_and_b32_e32 v75, 0xffff0000, v80
	v_pk_fma_f32 v[22:23], v[106:107], v[72:73], v[22:23]
	v_pk_fma_f32 v[74:75], v[114:115], v[74:75], v[20:21]
	v_cvt_pk_bf16_f32 v21, v22, v23
	ds_write2_b32 v120, v22, v23 offset0:34 offset1:35
	ds_write2_b32 v120, v74, v75 offset0:32 offset1:33
	v_lshlrev_b32_e32 v22, 16, v132
	v_lshlrev_b32_e32 v72, 16, v133
	v_and_b32_e32 v23, 0xffff0000, v132
	v_and_b32_e32 v73, 0xffff0000, v133
	v_pk_fma_f32 v[42:43], v[70:71], v[72:73], v[42:43]
	v_pk_fma_f32 v[22:23], v[68:69], v[22:23], v[40:41]
	v_lshlrev_b32_e32 v40, 16, v127
	v_lshlrev_b32_e32 v68, 16, v126
	v_and_b32_e32 v41, 0xffff0000, v127
	v_and_b32_e32 v69, 0xffff0000, v126
	v_pk_fma_f32 v[22:23], v[36:37], v[68:69], v[22:23]
	v_pk_fma_f32 v[36:37], v[38:39], v[40:41], v[42:43]
	v_lshlrev_b32_e32 v38, 16, v98
	v_lshlrev_b32_e32 v40, 16, v99
	v_and_b32_e32 v39, 0xffff0000, v98
	v_and_b32_e32 v41, 0xffff0000, v99
	v_cndmask_b32_e32 v43, 0, v85, vcc
	v_cndmask_b32_e32 v42, 0, v84, vcc
	v_cndmask_b32_e32 v69, 0, v87, vcc
	v_cndmask_b32_e32 v68, 0, v86, vcc
	v_pk_fma_f32 v[36:37], v[68:69], v[40:41], v[36:37]
	v_pk_fma_f32 v[22:23], v[42:43], v[38:39], v[22:23]
	v_lshlrev_b32_e32 v38, 16, v83
	v_and_b32_e32 v39, 0xffff0000, v83
	v_lshlrev_b32_e32 v40, 16, v82
	v_and_b32_e32 v41, 0xffff0000, v82
	v_pk_fma_f32 v[36:37], v[116:117], v[38:39], v[36:37]
	v_pk_fma_f32 v[40:41], v[118:119], v[40:41], v[22:23]
	v_cvt_pk_bf16_f32 v23, v36, v37
	ds_write2_b32 v120, v36, v37 offset0:38 offset1:39
	ds_write2_b32 v120, v40, v41 offset0:36 offset1:37
	v_lshlrev_b32_e32 v36, 2, v122
	v_lshl_add_u64 v[118:119], s[92:93], 0, v[100:101]
	v_lshl_add_u64 v[120:121], s[34:35], 0, v[100:101]
	v_and_b32_e32 v143, 0xc0, v36
	v_lshl_add_u64 v[36:37], v[118:119], 0, v[2:3]
	v_lshl_add_u64 v[38:39], v[120:121], 0, v[2:3]
	s_nop 7
	s_waitcnt lgkmcnt(0)
	v_cvt_pk_bf16_f32 v20, v74, v75
	v_cvt_pk_bf16_f32 v22, v40, v41
	s_nop 7
	global_load_dwordx4 v[68:71], v[36:37], off offset:2048
	global_load_dwordx4 v[72:75], v[38:39], off offset:2048
	global_load_dwordx4 v[76:79], v[36:37], off offset:2112
	global_load_dwordx4 v[80:83], v[38:39], off offset:2112
	global_load_dwordx4 v[40:43], v[108:109], off offset:64
	s_nop 0
	global_load_dwordx4 v[36:39], v[110:111], off offset:64
	global_load_dwordx4 v[84:87], v[112:113], off offset:64
	s_nop 7
	v_mov_b32_e32 v104, 1.0
	s_nop 7
	v_mov_b32_e32 v105, 1.0
	s_nop 7
	v_cmp_eq_u32_e32 vcc, 0, v136
	s_nop 0
	s_nop 7
	s_nop 1
	s_nop 7
	s_nop 1
	s_nop 7
	v_mov_b32_e32 v145, v88
	s_nop 7
	s_nop 0
	s_nop 7
	s_nop 0
	s_nop 7
	s_nop 0
	s_nop 7
	s_nop 0
	s_nop 7
	s_nop 0
	s_nop 7
	s_nop 0
	s_nop 7
	s_nop 1
	s_nop 7
	s_nop 1
	s_nop 7
	s_nop 1
	s_nop 7
	v_mov_b32_e32 v147, v89
	s_nop 7
	s_nop 0
	s_nop 7
	s_nop 0
	s_nop 7
	v_mov_b32_e32 v103, 1.0
	s_nop 7
	s_nop 0
	s_nop 7
	s_nop 1
	s_nop 7
	s_nop 1
	s_nop 7
	s_nop 1
	s_nop 7
	v_mov_b32_e32 v2, v90
	s_nop 7
	s_nop 0
	s_nop 7
	s_nop 0
	s_nop 7
	s_nop 0
	s_nop 7
	s_nop 0
	s_nop 7
	v_mov_b32_e32 v100, 1.0
	s_nop 7
	v_mov_b32_e32 v101, 1.0
	s_nop 7
	v_mfma_f32_16x16x32_bf16 v[92:95], v[56:59], v[16:19], 0
	v_mov_b32_e32 v98, 1.0
	s_nop 7
	v_mfma_f32_16x16x32_bf16 v[92:95], v[64:67], v[32:35], v[92:95]
	v_mov_b32_e32 v99, 1.0
	s_nop 7
	s_nop 1
	s_nop 7
	v_mov_b32_e32 v146, v91
	v_and_b32_e32 v88, -16, v122
	v_add_u32_e32 v142, s6, v88
	v_lshlrev_b64 v[88:89], 1, v[0:1]
	v_lshl_add_u64 v[114:115], s[44:45], 0, v[88:89]
	v_lshl_add_u64 v[116:117], s[46:47], 0, v[88:89]
	v_and_b32_e32 v198, 16, v144
	v_lshrrev_b32_e32 v199, 1, v198
	v_add_u32_e32 v198, v198, v199
	v_mov_b32_e32 v199, 0
	v_lshl_add_u64 v[114:115], v[114:115], 0, v[198:199]
	v_lshl_add_u64 v[116:117], v[116:117], 0, v[198:199]
	v_mfma_f32_16x16x32_bf16 v[88:91], v[52:55], v[16:19], 0
	v_mad_u32_u24 v122, v136, s76, v142
	ds_read2_b32 v[124:125], v122 offset1:1
	ds_read2_b32 v[128:129], v122 offset0:2 offset1:3
	v_mfma_f32_16x16x32_bf16 v[88:91], v[60:63], v[32:35], v[88:91]
	v_mov_b32_e32 v102, 1.0
	v_add_u32_e32 v148, v142, v123
	v_add_u32_e32 v150, v142, v141
	s_nop 4
	v_add_f32_e32 v88, v48, v88
	v_add_f32_e32 v89, v49, v89
	v_mul_f32_e32 v88, 0xbfb8aa3b, v88
	v_mul_f32_e32 v89, 0xbfb8aa3b, v89
	v_exp_f32_e32 v88, v88
	v_exp_f32_e32 v89, v89
	v_add_f32_e32 v90, v50, v90
	v_mul_f32_e32 v90, 0xbfb8aa3b, v90
	v_add_f32_e32 v88, 1.0, v88
	v_add_f32_e32 v89, 1.0, v89
	v_rcp_f32_e32 v96, v88
	v_rcp_f32_e32 v97, v89
	v_add_f32_e32 v88, v44, v92
	v_add_f32_e32 v89, v45, v93
	v_mul_f32_e32 v92, 0xc1000000, v96
	v_mul_f32_e32 v93, 0xc1000000, v97
	v_mul_f32_e32 v88, 0xbfb8aa3b, v88
	v_mul_f32_e32 v92, v145, v92
	v_mul_f32_e32 v89, 0xbfb8aa3b, v89
	v_mul_f32_e32 v93, v147, v93
	v_exp_f32_e32 v88, v88
	v_mul_f32_e32 v92, 0x3fb8aa3b, v92
	v_exp_f32_e32 v89, v89
	v_mul_f32_e32 v93, 0x3fb8aa3b, v93
	v_exp_f32_e32 v92, v92
	v_exp_f32_e32 v93, v93
	v_add_f32_e32 v88, 1.0, v88
	v_add_f32_e32 v89, 1.0, v89
	v_rcp_f32_e32 v88, v88
	v_fma_f32 v96, -v92, v92, 1.0
	v_rcp_f32_e32 v89, v89
	v_fma_f32 v97, -v93, v93, 1.0
	v_sqrt_f32_e32 v96, v96
	v_sqrt_f32_e32 v97, v97
	s_waitcnt lgkmcnt(0)
; __device__ __forceinline__ unsigned pk2(float lo, float hi) { const f32x2_t v = {lo, hi}; const bf16x2_t b = __builtin_convertvector(v, bf16x2_t); return __builtin_bit_cast(unsigned, b); }
; __device__ __forceinline__ float sigmoidf_(float x) { return __builtin_amdgcn_rcpf(1.0f + __expf(-x)); }
; __device__ __forceinline__ float bcast15(float v, int lane) { return bperm_f((lane & 48) | 15, v); }
; __device__ __forceinline__ void w_lru_m1(const Args& a, int l, unsigned char* ws, const bf16_t* proj, bf16_t* y, LAS unsigned char* wl, int b, int ck_, int h, int lane) {
;     ...
;         for (int tb = 0; tb < 4; ++tb) { const int tok = 16 * tb + lo;
;             f32x4 ga = {0.f, 0.f, 0.f, 0.f}, gx = {0.f, 0.f, 0.f, 0.f};
; #pragma unroll
;             for (int kk = 0; kk < 2; ++kk) { ga = __builtin_amdgcn_mfma_f32_16x16x32_bf16(WaF[kk], Xf[tb][kk], ga, 0, 0, 0); gx = __builtin_amdgcn_mfma_f32_16x16x32_bf16(WxF[kk], Xf[tb][kk], gx, 0, 0, 0); }
;             float hv[4], pv[4];
; #pragma unroll
;             for (int r = 0; r < 4; ++r) {
;                 const float rg = sigmoidf_(ga[r] + bav[r]), ig = sigmoidf_(gx[r] + bxv[r]);
;                 const float la = -8.0f * rg * sp[r]; float A = __expf(la);
;                 float U = __builtin_amdgcn_sqrtf(1.0f - A * A) * (ig * xcf[tok * 65 + j0 + r]);
;                 { const float As = dpp_shr1<1>(A), Us = dpp_shr0<1>(U); U = A * Us + U; A = A * As; }
;                 { const float As = dpp_shr1<2>(A), Us = dpp_shr0<2>(U); U = A * Us + U; A = A * As; }
;                 { const float As = dpp_shr1<4>(A), Us = dpp_shr0<4>(U); U = A * Us + U; A = A * As; }
;                 { const float As = dpp_shr1<8>(A), Us = dpp_shr0<8>(U); U = A * Us + U; A = A * As; }
;                 const float hh = U + A * hc[r], PP = A * Pc[r];
;                 hc[r] = bcast15(hh, lane); Pc[r] = bcast15(PP, lane); hv[r] = hh; pv[r] = PP; }
;             *(unsigned long long*)(y + (size_t)(row0 + tok) * DM + 64 * h + j0) = (unsigned long long)pk2(hv[0], hv[1]) | ((unsigned long long)pk2(hv[2], hv[3]) << 32);
;             *(unsigned long long*)((bf16_t*)(ws + WS_P) + (size_t)(row0 + tok) * 512 + 64 * h + j0) = (unsigned long long)pk2(pv[0], pv[1]) | ((unsigned long long)pk2(pv[2], pv[3]) << 32);
	v_pk_mul_f32 v[88:89], v[124:125], v[88:89]
	v_mov_b32_dpp v98, v92 row_shr:1 row_mask:0xf bank_mask:0xf
	v_mov_b32_dpp v99, v93 row_shr:1 row_mask:0xf bank_mask:0xf
	v_pk_mul_f32 v[88:89], v[88:89], v[96:97]
	v_pk_mul_f32 v[98:99], v[92:93], v[98:99]
	v_exp_f32_e32 v90, v90
	v_mov_b32_dpp v96, v88 row_shr:1 row_mask:0xf bank_mask:0xf bound_ctrl:1
	v_mov_b32_dpp v97, v89 row_shr:1 row_mask:0xf bank_mask:0xf bound_ctrl:1
	v_pk_fma_f32 v[88:89], v[92:93], v[96:97], v[88:89]
	v_mov_b32_dpp v100, v98 row_shr:2 row_mask:0xf bank_mask:0xf
	v_mov_b32_dpp v101, v99 row_shr:2 row_mask:0xf bank_mask:0xf
	v_mov_b32_dpp v92, v88 row_shr:2 row_mask:0xf bank_mask:0xf bound_ctrl:1
	v_mov_b32_dpp v93, v89 row_shr:2 row_mask:0xf bank_mask:0xf bound_ctrl:1
	v_pk_fma_f32 v[88:89], v[98:99], v[92:93], v[88:89]
	v_pk_mul_f32 v[100:101], v[98:99], v[100:101]
	v_add_f32_e32 v90, 1.0, v90
	v_mov_b32_dpp v92, v88 row_shr:4 row_mask:0xf bank_mask:0xf bound_ctrl:1
	v_mov_b32_dpp v93, v89 row_shr:4 row_mask:0xf bank_mask:0xf bound_ctrl:1
	v_mov_b32_dpp v102, v100 row_shr:4 row_mask:0xf bank_mask:0xf
	v_mov_b32_dpp v103, v101 row_shr:4 row_mask:0xf bank_mask:0xf
	v_pk_fma_f32 v[88:89], v[100:101], v[92:93], v[88:89]
	v_pk_mul_f32 v[102:103], v[100:101], v[102:103]
	v_add_f32_e32 v91, v51, v91
	v_mov_b32_dpp v92, v88 row_shr:8 row_mask:0xf bank_mask:0xf bound_ctrl:1
	v_mov_b32_dpp v93, v89 row_shr:8 row_mask:0xf bank_mask:0xf bound_ctrl:1
	v_pk_fma_f32 v[88:89], v[102:103], v[92:93], v[88:89]
	v_rcp_f32_e32 v92, v90
	v_mul_f32_e32 v91, 0xbfb8aa3b, v91
	v_exp_f32_e32 v91, v91
	v_add_f32_e32 v90, v46, v94
	v_mul_f32_e32 v92, 0xc1000000, v92
	v_mul_f32_e32 v92, v2, v92
	v_mul_f32_e32 v92, 0x3fb8aa3b, v92
	v_exp_f32_e32 v92, v92
	v_add_f32_e32 v91, 1.0, v91
	v_mul_f32_e32 v90, 0xbfb8aa3b, v90
	v_exp_f32_e32 v90, v90
	v_fma_f32 v93, -v92, v92, 1.0
	v_sqrt_f32_e32 v94, v93
	v_rcp_f32_e32 v93, v91
	v_add_f32_e32 v91, v47, v95
	v_mul_f32_e32 v91, 0xbfb8aa3b, v91
	v_exp_f32_e32 v91, v91
	v_mul_f32_e32 v93, 0xc1000000, v93
	v_mul_f32_e32 v93, v146, v93
	v_mul_f32_e32 v93, 0x3fb8aa3b, v93
	v_exp_f32_e32 v93, v93
	v_add_f32_e32 v90, 1.0, v90
	v_add_f32_e32 v91, 1.0, v91
	v_rcp_f32_e32 v90, v90
	v_rcp_f32_e32 v91, v91
	v_fma_f32 v95, -v93, v93, 1.0
	v_sqrt_f32_e32 v95, v95
	v_mov_b32_e32 v96, 1.0
	v_pk_mul_f32 v[90:91], v[90:91], v[128:129]
	v_mov_b32_e32 v97, 1.0
	v_pk_mul_f32 v[90:91], v[94:95], v[90:91]
	v_mov_b32_dpp v96, v92 row_shr:1 row_mask:0xf bank_mask:0xf
	v_mov_b32_dpp v97, v93 row_shr:1 row_mask:0xf bank_mask:0xf
	v_mov_b32_dpp v94, v90 row_shr:1 row_mask:0xf bank_mask:0xf bound_ctrl:1
	v_mov_b32_dpp v95, v91 row_shr:1 row_mask:0xf bank_mask:0xf bound_ctrl:1
	v_pk_mul_f32 v[96:97], v[92:93], v[96:97]
	v_mov_b32_e32 v100, 1.0
	v_mov_b32_e32 v101, 1.0
	v_pk_fma_f32 v[90:91], v[92:93], v[94:95], v[90:91]
	v_mov_b32_dpp v104, v102 row_shr:8 row_mask:0xf bank_mask:0xf
	v_mov_b32_dpp v105, v103 row_shr:8 row_mask:0xf bank_mask:0xf
	v_mov_b32_dpp v100, v96 row_shr:2 row_mask:0xf bank_mask:0xf
	v_mov_b32_dpp v101, v97 row_shr:2 row_mask:0xf bank_mask:0xf
	v_mov_b32_dpp v92, v90 row_shr:2 row_mask:0xf bank_mask:0xf bound_ctrl:1
	v_mov_b32_dpp v93, v91 row_shr:2 row_mask:0xf bank_mask:0xf bound_ctrl:1
	v_pk_mul_f32 v[106:107], v[102:103], v[104:105]
	v_pk_mul_f32 v[100:101], v[96:97], v[100:101]
	v_mov_b32_e32 v102, 1.0
	v_mov_b32_e32 v103, 1.0
	v_pk_fma_f32 v[90:91], v[96:97], v[92:93], v[90:91]
	v_mov_b32_dpp v102, v100 row_shr:4 row_mask:0xf bank_mask:0xf
	v_mov_b32_dpp v103, v101 row_shr:4 row_mask:0xf bank_mask:0xf
	v_mov_b32_dpp v92, v90 row_shr:4 row_mask:0xf bank_mask:0xf bound_ctrl:1
	v_mov_b32_dpp v93, v91 row_shr:4 row_mask:0xf bank_mask:0xf bound_ctrl:1
	v_pk_mul_f32 v[102:103], v[100:101], v[102:103]
	v_mov_b32_e32 v124, 1.0
	v_mov_b32_e32 v125, 1.0
	v_pk_fma_f32 v[90:91], v[100:101], v[92:93], v[90:91]
	v_mov_b32_dpp v124, v102 row_shr:8 row_mask:0xf bank_mask:0xf
	v_mov_b32_dpp v125, v103 row_shr:8 row_mask:0xf bank_mask:0xf
	v_mov_b32_dpp v92, v90 row_shr:8 row_mask:0xf bank_mask:0xf bound_ctrl:1
	v_mov_b32_dpp v93, v91 row_shr:8 row_mask:0xf bank_mask:0xf bound_ctrl:1
	v_pk_mul_f32 v[126:127], v[102:103], v[124:125]
	v_pk_fma_f32 v[90:91], v[102:103], v[92:93], v[90:91]
	v_pk_fma_f32 v[88:89], v[106:107], 0, v[88:89] op_sel_hi:[1,0,1]
	v_pk_fma_f32 v[90:91], v[126:127], 0, v[90:91] op_sel_hi:[1,0,1]
	ds_bpermute_b32 v98, v143, v88 offset:60
	ds_bpermute_b32 v99, v143, v89 offset:60
	ds_bpermute_b32 v96, v143, v90 offset:60
	v_cvt_pk_bf16_f32 v88, v88, v89
	v_cvt_pk_bf16_f32 v89, v90, v91
	v_or_b32_e32 v90, s48, v136
	ds_bpermute_b32 v97, v143, v91 offset:60
	v_ashrrev_i32_e32 v91, 31, v90
	v_lshlrev_b64 v[92:93], 11, v[90:91]
	v_lshl_add_u64 v[100:101], v[114:115], 0, v[92:93]
	v_lshlrev_b64 v[90:91], 10, v[90:91]
	v_mov_b64_e32 v[222:223], v[88:89]
	v_cvt_pk_bf16_f32 v88, v106, v107
	v_cvt_pk_bf16_f32 v89, v126, v127
	v_lshl_add_u64 v[102:103], v[116:117], 0, v[90:91]
	v_mov_b64_e32 v[226:227], v[88:89]
	v_mfma_f32_16x16x32_bf16 v[88:91], v[52:55], v[12:15], 0
	ds_bpermute_b32 v124, v143, v126 offset:60
	ds_bpermute_b32 v125, v143, v127 offset:60
	ds_bpermute_b32 v104, v143, v106 offset:60
	v_mfma_f32_16x16x32_bf16 v[126:129], v[56:59], v[12:15], 0
	ds_bpermute_b32 v105, v143, v107 offset:60
	v_mfma_f32_16x16x32_bf16 v[92:95], v[60:63], v[28:31], v[88:91]
	v_mfma_f32_16x16x32_bf16 v[88:91], v[64:67], v[28:31], v[126:129]
	s_nop 6
	v_add_f32_e32 v92, v48, v92
	v_mul_f32_e32 v92, 0xbfb8aa3b, v92
	v_exp_f32_e32 v92, v92
	v_add_f32_e32 v88, v44, v88
	v_mul_f32_e32 v88, 0xbfb8aa3b, v88
	v_exp_f32_e32 v88, v88
	v_add_f32_e32 v92, 1.0, v92
	v_rcp_f32_e32 v92, v92
; __device__ __forceinline__ float sigmoidf_(float x) { return __builtin_amdgcn_rcpf(1.0f + __expf(-x)); }
; __device__ __forceinline__ float bcast15(float v, int lane) { return bperm_f((lane & 48) | 15, v); }
; __device__ __forceinline__ void w_lru_m1(const Args& a, int l, unsigned char* ws, const bf16_t* proj, bf16_t* y, LAS unsigned char* wl, int b, int ck_, int h, int lane) {
;     ...
;         for (int tb = 0; tb < 4; ++tb) { const int tok = 16 * tb + lo;
;             f32x4 ga = {0.f, 0.f, 0.f, 0.f}, gx = {0.f, 0.f, 0.f, 0.f};
; #pragma unroll
;             for (int kk = 0; kk < 2; ++kk) { ga = __builtin_amdgcn_mfma_f32_16x16x32_bf16(WaF[kk], Xf[tb][kk], ga, 0, 0, 0); gx = __builtin_amdgcn_mfma_f32_16x16x32_bf16(WxF[kk], Xf[tb][kk], gx, 0, 0, 0); }
;             float hv[4], pv[4];
; #pragma unroll
;             for (int r = 0; r < 4; ++r) {
;                 const float rg = sigmoidf_(ga[r] + bav[r]), ig = sigmoidf_(gx[r] + bxv[r]);
;                 const float la = -8.0f * rg * sp[r]; float A = __expf(la);
;                 float U = __builtin_amdgcn_sqrtf(1.0f - A * A) * (ig * xcf[tok * 65 + j0 + r]);
;                 { const float As = dpp_shr1<1>(A), Us = dpp_shr0<1>(U); U = A * Us + U; A = A * As; }
;                 { const float As = dpp_shr1<2>(A), Us = dpp_shr0<2>(U); U = A * Us + U; A = A * As; }
;                 { const float As = dpp_shr1<4>(A), Us = dpp_shr0<4>(U); U = A * Us + U; A = A * As; }
;                 { const float As = dpp_shr1<8>(A), Us = dpp_shr0<8>(U); U = A * Us + U; A = A * As; }
;                 const float hh = U + A * hc[r], PP = A * Pc[r];
;                 hc[r] = bcast15(hh, lane); Pc[r] = bcast15(PP, lane); hv[r] = hh; pv[r] = PP; }
	v_add_f32_e32 v89, v45, v89
	v_add_f32_e32 v88, 1.0, v88
	v_rcp_f32_e32 v106, v88
	v_mul_f32_e32 v88, 0xc1000000, v92
	v_add_f32_e32 v92, v49, v93
	v_mul_f32_e32 v92, 0xbfb8aa3b, v92
	v_exp_f32_e32 v92, v92
	v_mul_f32_e32 v89, 0xbfb8aa3b, v89
	v_exp_f32_e32 v89, v89
	v_mul_f32_e32 v88, v145, v88
	v_add_f32_e32 v92, 1.0, v92
	v_rcp_f32_e32 v92, v92
	v_add_f32_e32 v89, 1.0, v89
	v_rcp_f32_e32 v107, v89
	v_mul_f32_e32 v88, 0x3fb8aa3b, v88
	v_mul_f32_e32 v89, 0xc1000000, v92
	v_mul_f32_e32 v89, v147, v89
	v_mul_f32_e32 v89, 0x3fb8aa3b, v89
	v_exp_f32_e32 v122, v88
	v_exp_f32_e32 v123, v89
	v_add_f32_e32 v94, v50, v94
	v_add_f32_e32 v95, v51, v95
	v_fma_f32 v88, -v122, v122, 1.0
	v_fma_f32 v89, -v123, v123, 1.0
	v_sqrt_f32_e32 v126, v88
	v_mov_b32_e32 v88, 1.0
	v_sqrt_f32_e32 v127, v89
	v_mov_b32_e32 v89, 1.0
	v_mov_b32_dpp v88, v122 row_shr:1 row_mask:0xf bank_mask:0xf
	v_mul_f32_e32 v94, 0xbfb8aa3b, v94
	v_mov_b32_dpp v89, v123 row_shr:1 row_mask:0xf bank_mask:0xf
	v_pk_mul_f32 v[128:129], v[122:123], v[88:89]
	v_mov_b32_e32 v88, 1.0
	v_mov_b32_e32 v89, 1.0
	v_mul_f32_e32 v95, 0xbfb8aa3b, v95
	v_mov_b32_dpp v88, v128 row_shr:2 row_mask:0xf bank_mask:0xf
	v_mov_b32_dpp v89, v129 row_shr:2 row_mask:0xf bank_mask:0xf
	v_pk_mul_f32 v[130:131], v[128:129], v[88:89]
	v_mov_b32_e32 v88, 1.0
	v_mov_b32_e32 v89, 1.0
	v_exp_f32_e32 v94, v94
	v_mov_b32_dpp v88, v130 row_shr:4 row_mask:0xf bank_mask:0xf
	v_mov_b32_dpp v89, v131 row_shr:4 row_mask:0xf bank_mask:0xf
	v_pk_mul_f32 v[132:133], v[130:131], v[88:89]
	v_mov_b32_e32 v88, 1.0
	v_mov_b32_e32 v89, 1.0
	v_exp_f32_e32 v95, v95
	v_mov_b32_dpp v88, v132 row_shr:8 row_mask:0xf bank_mask:0xf
	v_mov_b32_dpp v89, v133 row_shr:8 row_mask:0xf bank_mask:0xf
	v_pk_mul_f32 v[134:135], v[132:133], v[88:89]
	v_add_f32_e32 v90, v46, v90
	s_waitcnt lgkmcnt(0)
	v_pk_mul_f32 v[92:93], v[134:135], v[104:105]
	ds_read2_b32 v[104:105], v148 offset1:1
	v_add_f32_e32 v91, v47, v91
	v_mul_f32_e32 v90, 0xbfb8aa3b, v90
	v_mul_f32_e32 v91, 0xbfb8aa3b, v91
	v_add_f32_e32 v94, 1.0, v94
	s_waitcnt lgkmcnt(0)
	v_pk_mul_f32 v[104:105], v[104:105], v[106:107]
	v_exp_f32_e32 v90, v90
	v_pk_mul_f32 v[104:105], v[104:105], v[126:127]
	v_add_f32_e32 v95, 1.0, v95
	v_exp_f32_e32 v91, v91
	v_mov_b32_dpp v106, v104 row_shr:1 row_mask:0xf bank_mask:0xf bound_ctrl:1
	v_mov_b32_dpp v107, v105 row_shr:1 row_mask:0xf bank_mask:0xf bound_ctrl:1
	v_pk_fma_f32 v[104:105], v[122:123], v[106:107], v[104:105]
	v_rcp_f32_e32 v94, v94
	v_rcp_f32_e32 v95, v95
	v_mov_b32_dpp v106, v104 row_shr:2 row_mask:0xf bank_mask:0xf bound_ctrl:1
	v_mov_b32_dpp v107, v105 row_shr:2 row_mask:0xf bank_mask:0xf bound_ctrl:1
	v_pk_fma_f32 v[104:105], v[128:129], v[106:107], v[104:105]
	v_add_f32_e32 v90, 1.0, v90
	v_add_f32_e32 v91, 1.0, v91
	v_mov_b32_dpp v106, v104 row_shr:4 row_mask:0xf bank_mask:0xf bound_ctrl:1
	v_mov_b32_dpp v107, v105 row_shr:4 row_mask:0xf bank_mask:0xf bound_ctrl:1
	v_pk_fma_f32 v[104:105], v[130:131], v[106:107], v[104:105]
	ds_bpermute_b32 v88, v143, v92 offset:60
	ds_bpermute_b32 v89, v143, v93 offset:60
	v_mov_b32_dpp v106, v104 row_shr:8 row_mask:0xf bank_mask:0xf bound_ctrl:1
	v_mov_b32_dpp v107, v105 row_shr:8 row_mask:0xf bank_mask:0xf bound_ctrl:1
	v_pk_fma_f32 v[104:105], v[132:133], v[106:107], v[104:105]
	v_rcp_f32_e32 v106, v90
	v_mul_f32_e32 v90, 0xc1000000, v94
	v_rcp_f32_e32 v107, v91
	v_mul_f32_e32 v91, 0xc1000000, v95
	v_mul_f32_e32 v90, v2, v90
	v_mul_f32_e32 v91, v146, v91
	v_mul_f32_e32 v90, 0x3fb8aa3b, v90
	v_mul_f32_e32 v91, 0x3fb8aa3b, v91
	v_exp_f32_e32 v94, v90
	v_exp_f32_e32 v95, v91
	v_pk_fma_f32 v[104:105], v[134:135], v[98:99], v[104:105]
	ds_read2_b32 v[134:135], v148 offset0:2 offset1:3
	v_fma_f32 v90, -v94, v94, 1.0
	v_fma_f32 v91, -v95, v95, 1.0
	v_sqrt_f32_e32 v122, v90
	v_sqrt_f32_e32 v123, v91
	s_waitcnt lgkmcnt(0)
	v_pk_mul_f32 v[106:107], v[106:107], v[134:135]
	v_mov_b32_e32 v90, 1.0
	v_mov_b32_e32 v91, 1.0
	v_pk_mul_f32 v[106:107], v[122:123], v[106:107]
	v_mov_b32_dpp v90, v94 row_shr:1 row_mask:0xf bank_mask:0xf
	v_mov_b32_dpp v91, v95 row_shr:1 row_mask:0xf bank_mask:0xf
	v_mov_b32_dpp v122, v106 row_shr:1 row_mask:0xf bank_mask:0xf bound_ctrl:1
	v_mov_b32_dpp v123, v107 row_shr:1 row_mask:0xf bank_mask:0xf bound_ctrl:1
	v_pk_mul_f32 v[126:127], v[94:95], v[90:91]
	v_mov_b32_e32 v90, 1.0
	v_mov_b32_e32 v91, 1.0
	v_pk_fma_f32 v[94:95], v[94:95], v[122:123], v[106:107]
	v_mov_b32_dpp v90, v126 row_shr:2 row_mask:0xf bank_mask:0xf
	v_mov_b32_dpp v91, v127 row_shr:2 row_mask:0xf bank_mask:0xf
	v_mov_b32_dpp v106, v94 row_shr:2 row_mask:0xf bank_mask:0xf bound_ctrl:1
	v_mov_b32_dpp v107, v95 row_shr:2 row_mask:0xf bank_mask:0xf bound_ctrl:1
	v_pk_mul_f32 v[128:129], v[126:127], v[90:91]
	v_mov_b32_e32 v90, 1.0
	v_mov_b32_e32 v91, 1.0
	v_pk_fma_f32 v[94:95], v[126:127], v[106:107], v[94:95]
	v_mov_b32_dpp v90, v128 row_shr:4 row_mask:0xf bank_mask:0xf
	v_mov_b32_dpp v91, v129 row_shr:4 row_mask:0xf bank_mask:0xf
	v_mov_b32_dpp v106, v94 row_shr:4 row_mask:0xf bank_mask:0xf bound_ctrl:1
	v_mov_b32_dpp v107, v95 row_shr:4 row_mask:0xf bank_mask:0xf bound_ctrl:1
	v_pk_mul_f32 v[130:131], v[128:129], v[90:91]
	v_mov_b32_e32 v90, 1.0
	v_mov_b32_e32 v91, 1.0
	v_pk_fma_f32 v[94:95], v[128:129], v[106:107], v[94:95]
	v_mov_b32_dpp v90, v130 row_shr:8 row_mask:0xf bank_mask:0xf
	v_mov_b32_dpp v91, v131 row_shr:8 row_mask:0xf bank_mask:0xf
	v_mov_b32_dpp v106, v94 row_shr:8 row_mask:0xf bank_mask:0xf bound_ctrl:1
	v_mov_b32_dpp v107, v95 row_shr:8 row_mask:0xf bank_mask:0xf bound_ctrl:1
	v_pk_mul_f32 v[132:133], v[130:131], v[90:91]
	v_pk_fma_f32 v[94:95], v[130:131], v[106:107], v[94:95]
; __device__ __forceinline__ unsigned pk2(float lo, float hi) { const f32x2_t v = {lo, hi}; const bf16x2_t b = __builtin_convertvector(v, bf16x2_t); return __builtin_bit_cast(unsigned, b); }
; __device__ __forceinline__ float sigmoidf_(float x) { return __builtin_amdgcn_rcpf(1.0f + __expf(-x)); }
; __device__ __forceinline__ float bcast15(float v, int lane) { return bperm_f((lane & 48) | 15, v); }
; __device__ __forceinline__ void w_lru_m1(const Args& a, int l, unsigned char* ws, const bf16_t* proj, bf16_t* y, LAS unsigned char* wl, int b, int ck_, int h, int lane) {
;     ...
;         for (int tb = 0; tb < 4; ++tb) { const int tok = 16 * tb + lo;
;             f32x4 ga = {0.f, 0.f, 0.f, 0.f}, gx = {0.f, 0.f, 0.f, 0.f};
; #pragma unroll
;             for (int kk = 0; kk < 2; ++kk) { ga = __builtin_amdgcn_mfma_f32_16x16x32_bf16(WaF[kk], Xf[tb][kk], ga, 0, 0, 0); gx = __builtin_amdgcn_mfma_f32_16x16x32_bf16(WxF[kk], Xf[tb][kk], gx, 0, 0, 0); }
;             float hv[4], pv[4];
; #pragma unroll
;             for (int r = 0; r < 4; ++r) {
;                 const float rg = sigmoidf_(ga[r] + bav[r]), ig = sigmoidf_(gx[r] + bxv[r]);
;                 const float la = -8.0f * rg * sp[r]; float A = __expf(la);
;                 float U = __builtin_amdgcn_sqrtf(1.0f - A * A) * (ig * xcf[tok * 65 + j0 + r]);
;                 { const float As = dpp_shr1<1>(A), Us = dpp_shr0<1>(U); U = A * Us + U; A = A * As; }
;                 { const float As = dpp_shr1<2>(A), Us = dpp_shr0<2>(U); U = A * Us + U; A = A * As; }
;                 { const float As = dpp_shr1<4>(A), Us = dpp_shr0<4>(U); U = A * Us + U; A = A * As; }
;                 { const float As = dpp_shr1<8>(A), Us = dpp_shr0<8>(U); U = A * Us + U; A = A * As; }
;                 const float hh = U + A * hc[r], PP = A * Pc[r];
;                 hc[r] = bcast15(hh, lane); Pc[r] = bcast15(PP, lane); hv[r] = hh; pv[r] = PP; }
;             *(unsigned long long*)(y + (size_t)(row0 + tok) * DM + 64 * h + j0) = (unsigned long long)pk2(hv[0], hv[1]) | ((unsigned long long)pk2(hv[2], hv[3]) << 32);
;             *(unsigned long long*)((bf16_t*)(ws + WS_P) + (size_t)(row0 + tok) * 512 + 64 * h + j0) = (unsigned long long)pk2(pv[0], pv[1]) | ((unsigned long long)pk2(pv[2], pv[3]) << 32);
	ds_bpermute_b32 v98, v143, v104 offset:60
	v_pk_fma_f32 v[94:95], v[132:133], v[96:97], v[94:95]
	ds_bpermute_b32 v96, v143, v94 offset:60
	v_cvt_pk_bf16_f32 v107, v94, v95
	v_or_b32_e32 v94, s48, v140
	ds_bpermute_b32 v97, v143, v95 offset:60
	v_ashrrev_i32_e32 v95, 31, v94
	ds_bpermute_b32 v99, v143, v105 offset:60
	v_cvt_pk_bf16_f32 v106, v104, v105
	v_lshlrev_b64 v[104:105], 11, v[94:95]
	v_pk_mul_f32 v[124:125], v[132:133], v[124:125]
	v_lshl_add_u64 v[104:105], v[114:115], 0, v[104:105]
	v_lshlrev_b64 v[94:95], 10, v[94:95]
	v_mov_b64_e32 v[230:231], v[106:107]
	v_cvt_pk_bf16_f32 v92, v92, v93
	v_cvt_pk_bf16_f32 v93, v124, v125
	v_lshl_add_u64 v[106:107], v[116:117], 0, v[94:95]
	v_mov_b64_e32 v[234:235], v[92:93]
	v_mfma_f32_16x16x32_bf16 v[92:95], v[52:55], v[8:11], 0
	ds_bpermute_b32 v90, v143, v124 offset:60
	ds_bpermute_b32 v91, v143, v125 offset:60
	v_mfma_f32_16x16x32_bf16 v[126:129], v[60:63], v[24:27], v[92:95]
	v_mfma_f32_16x16x32_bf16 v[122:125], v[56:59], v[8:11], 0
	v_mfma_f32_16x16x32_bf16 v[122:125], v[64:67], v[24:27], v[122:125]
	s_nop 5
	v_add_f32_e32 v92, v48, v126
	v_mul_f32_e32 v92, 0xbfb8aa3b, v92
	v_exp_f32_e32 v92, v92
	v_mfma_f32_16x16x32_bf16 v[52:55], v[52:55], v[4:7], 0
	v_add_f32_e32 v92, 1.0, v92
	v_rcp_f32_e32 v93, v92
	v_add_f32_e32 v92, v44, v122
	v_mov_b32_e32 v122, 1.0
	v_mul_f32_e32 v92, 0xbfb8aa3b, v92
	v_mul_f32_e32 v93, 0xc1000000, v93
	v_mul_f32_e32 v93, v145, v93
	v_mul_f32_e32 v93, 0x3fb8aa3b, v93
	v_exp_f32_e32 v94, v93
	v_exp_f32_e32 v92, v92
	v_fma_f32 v93, -v94, v94, 1.0
	v_sqrt_f32_e32 v126, v93
	v_add_f32_e32 v93, v49, v127
	v_mul_f32_e32 v93, 0xbfb8aa3b, v93
	v_exp_f32_e32 v93, v93
	v_mov_b32_dpp v122, v94 row_shr:1 row_mask:0xf bank_mask:0xf
	v_add_f32_e32 v92, 1.0, v92
	v_rcp_f32_e32 v92, v92
	v_add_f32_e32 v93, 1.0, v93
	v_rcp_f32_e32 v95, v93
	v_add_f32_e32 v93, v45, v123
	v_mul_f32_e32 v93, 0xbfb8aa3b, v93
	v_exp_f32_e32 v93, v93
	v_mul_f32_e32 v95, 0xc1000000, v95
	v_mul_f32_e32 v95, v147, v95
	v_mul_f32_e32 v95, 0x3fb8aa3b, v95
	v_exp_f32_e32 v95, v95
	v_add_f32_e32 v93, 1.0, v93
	v_rcp_f32_e32 v93, v93
	v_fma_f32 v123, -v95, v95, 1.0
	v_sqrt_f32_e32 v127, v123
	v_mov_b32_e32 v123, 1.0
	s_nop 1
	v_mov_b32_dpp v123, v95 row_shr:1 row_mask:0xf bank_mask:0xf
	v_pk_mul_f32 v[130:131], v[94:95], v[122:123]
	v_mov_b32_e32 v122, 1.0
	v_mov_b32_e32 v123, 1.0
	s_nop 0
	v_mov_b32_dpp v122, v130 row_shr:2 row_mask:0xf bank_mask:0xf
	v_mov_b32_dpp v123, v131 row_shr:2 row_mask:0xf bank_mask:0xf
	v_pk_mul_f32 v[132:133], v[130:131], v[122:123]
	v_mov_b32_e32 v122, 1.0
	v_mov_b32_e32 v123, 1.0
	s_nop 0
	v_mov_b32_dpp v122, v132 row_shr:4 row_mask:0xf bank_mask:0xf
	v_mov_b32_dpp v123, v133 row_shr:4 row_mask:0xf bank_mask:0xf
	v_pk_mul_f32 v[134:135], v[132:133], v[122:123]
	v_mov_b32_e32 v122, 1.0
	v_mov_b32_e32 v123, 1.0
	s_nop 0
	v_mov_b32_dpp v122, v134 row_shr:8 row_mask:0xf bank_mask:0xf
	v_mov_b32_dpp v123, v135 row_shr:8 row_mask:0xf bank_mask:0xf
	v_pk_mul_f32 v[140:141], v[134:135], v[122:123]
	s_nop 0
	v_pk_mul_f32 v[148:149], v[140:141], v[88:89]
	ds_read2_b32 v[88:89], v150 offset1:1
	ds_bpermute_b32 v122, v143, v148 offset:60
	ds_bpermute_b32 v123, v143, v149 offset:60
	s_waitcnt lgkmcnt(0)
	v_pk_mul_f32 v[88:89], v[88:89], v[92:93]
	s_nop 0
	v_pk_mul_f32 v[88:89], v[88:89], v[126:127]
	s_nop 1
	v_mov_b32_dpp v92, v88 row_shr:1 row_mask:0xf bank_mask:0xf bound_ctrl:1
	v_mov_b32_dpp v93, v89 row_shr:1 row_mask:0xf bank_mask:0xf bound_ctrl:1
	v_pk_fma_f32 v[88:89], v[94:95], v[92:93], v[88:89]
	s_nop 1
	v_mov_b32_dpp v92, v88 row_shr:2 row_mask:0xf bank_mask:0xf bound_ctrl:1
	v_mov_b32_dpp v93, v89 row_shr:2 row_mask:0xf bank_mask:0xf bound_ctrl:1
	v_pk_fma_f32 v[88:89], v[130:131], v[92:93], v[88:89]
	s_nop 1
	v_mov_b32_dpp v92, v88 row_shr:4 row_mask:0xf bank_mask:0xf bound_ctrl:1
	v_mov_b32_dpp v93, v89 row_shr:4 row_mask:0xf bank_mask:0xf bound_ctrl:1
	v_pk_fma_f32 v[88:89], v[132:133], v[92:93], v[88:89]
	s_nop 1
	v_mov_b32_dpp v92, v88 row_shr:8 row_mask:0xf bank_mask:0xf bound_ctrl:1
	v_mov_b32_dpp v93, v89 row_shr:8 row_mask:0xf bank_mask:0xf bound_ctrl:1
	v_pk_fma_f32 v[88:89], v[134:135], v[92:93], v[88:89]
	v_mov_b32_e32 v92, 1.0
	v_pk_fma_f32 v[98:99], v[140:141], v[98:99], v[88:89]
	v_add_f32_e32 v88, v50, v128
	v_mul_f32_e32 v88, 0xbfb8aa3b, v88
	v_exp_f32_e32 v88, v88
	ds_read2_b32 v[140:141], v150 offset0:2 offset1:3
	ds_bpermute_b32 v94, v143, v98 offset:60
	ds_bpermute_b32 v95, v143, v99 offset:60
	v_add_f32_e32 v88, 1.0, v88
	v_rcp_f32_e32 v89, v88
	v_add_f32_e32 v88, v46, v124
	v_mul_f32_e32 v88, 0xbfb8aa3b, v88
	v_exp_f32_e32 v88, v88
	v_mul_f32_e32 v89, 0xc1000000, v89
	v_mul_f32_e32 v89, v2, v89
	v_mul_f32_e32 v89, 0x3fb8aa3b, v89
	v_exp_f32_e32 v124, v89
	v_add_f32_e32 v88, 1.0, v88
	v_rcp_f32_e32 v88, v88
	v_cvt_pk_bf16_f32 v98, v98, v99
	v_fma_f32 v89, -v124, v124, 1.0
	v_sqrt_f32_e32 v126, v89
	v_add_f32_e32 v89, v51, v129
	v_mul_f32_e32 v89, 0xbfb8aa3b, v89
	v_exp_f32_e32 v89, v89
	v_mov_b32_dpp v92, v124 row_shr:1 row_mask:0xf bank_mask:0xf
	v_add_f32_e32 v89, 1.0, v89
	v_rcp_f32_e32 v93, v89
	v_add_f32_e32 v89, v47, v125
	v_mul_f32_e32 v89, 0xbfb8aa3b, v89
	v_exp_f32_e32 v89, v89
	v_mul_f32_e32 v93, 0xc1000000, v93
	v_mul_f32_e32 v93, v146, v93
	v_mul_f32_e32 v93, 0x3fb8aa3b, v93
	v_exp_f32_e32 v125, v93
	v_add_f32_e32 v89, 1.0, v89
	v_rcp_f32_e32 v89, v89
	v_fma_f32 v93, -v125, v125, 1.0
	v_sqrt_f32_e32 v127, v93
	s_waitcnt lgkmcnt(0)
; __device__ __forceinline__ unsigned pk2(float lo, float hi) { const f32x2_t v = {lo, hi}; const bf16x2_t b = __builtin_convertvector(v, bf16x2_t); return __builtin_bit_cast(unsigned, b); }
; __device__ __forceinline__ float sigmoidf_(float x) { return __builtin_amdgcn_rcpf(1.0f + __expf(-x)); }
; __device__ __forceinline__ float bcast15(float v, int lane) { return bperm_f((lane & 48) | 15, v); }
; __device__ __forceinline__ void w_lru_m1(const Args& a, int l, unsigned char* ws, const bf16_t* proj, bf16_t* y, LAS unsigned char* wl, int b, int ck_, int h, int lane) {
;     ...
;         for (int tb = 0; tb < 4; ++tb) { const int tok = 16 * tb + lo;
;             f32x4 ga = {0.f, 0.f, 0.f, 0.f}, gx = {0.f, 0.f, 0.f, 0.f};
; #pragma unroll
;             for (int kk = 0; kk < 2; ++kk) { ga = __builtin_amdgcn_mfma_f32_16x16x32_bf16(WaF[kk], Xf[tb][kk], ga, 0, 0, 0); gx = __builtin_amdgcn_mfma_f32_16x16x32_bf16(WxF[kk], Xf[tb][kk], gx, 0, 0, 0); }
;             float hv[4], pv[4];
; #pragma unroll
;             for (int r = 0; r < 4; ++r) {
;                 const float rg = sigmoidf_(ga[r] + bav[r]), ig = sigmoidf_(gx[r] + bxv[r]);
;                 const float la = -8.0f * rg * sp[r]; float A = __expf(la);
;                 float U = __builtin_amdgcn_sqrtf(1.0f - A * A) * (ig * xcf[tok * 65 + j0 + r]);
;                 { const float As = dpp_shr1<1>(A), Us = dpp_shr0<1>(U); U = A * Us + U; A = A * As; }
;                 { const float As = dpp_shr1<2>(A), Us = dpp_shr0<2>(U); U = A * Us + U; A = A * As; }
;                 { const float As = dpp_shr1<4>(A), Us = dpp_shr0<4>(U); U = A * Us + U; A = A * As; }
;                 { const float As = dpp_shr1<8>(A), Us = dpp_shr0<8>(U); U = A * Us + U; A = A * As; }
;                 const float hh = U + A * hc[r], PP = A * Pc[r];
;                 hc[r] = bcast15(hh, lane); Pc[r] = bcast15(PP, lane); hv[r] = hh; pv[r] = PP; }
;             *(unsigned long long*)(y + (size_t)(row0 + tok) * DM + 64 * h + j0) = (unsigned long long)pk2(hv[0], hv[1]) | ((unsigned long long)pk2(hv[2], hv[3]) << 32);
;             *(unsigned long long*)((bf16_t*)(ws + WS_P) + (size_t)(row0 + tok) * 512 + 64 * h + j0) = (unsigned long long)pk2(pv[0], pv[1]) | ((unsigned long long)pk2(pv[2], pv[3]) << 32);
	v_pk_mul_f32 v[88:89], v[88:89], v[140:141]
	v_mov_b32_e32 v93, 1.0
	v_pk_mul_f32 v[88:89], v[126:127], v[88:89]
	s_nop 0
	v_mov_b32_dpp v93, v125 row_shr:1 row_mask:0xf bank_mask:0xf
	v_mov_b32_dpp v126, v88 row_shr:1 row_mask:0xf bank_mask:0xf bound_ctrl:1
	v_mov_b32_dpp v127, v89 row_shr:1 row_mask:0xf bank_mask:0xf bound_ctrl:1
	v_pk_mul_f32 v[128:129], v[124:125], v[92:93]
	v_mov_b32_e32 v92, 1.0
	v_mov_b32_e32 v93, 1.0
	v_pk_fma_f32 v[88:89], v[124:125], v[126:127], v[88:89]
	v_mov_b32_dpp v92, v128 row_shr:2 row_mask:0xf bank_mask:0xf
	v_mov_b32_dpp v93, v129 row_shr:2 row_mask:0xf bank_mask:0xf
	v_mov_b32_dpp v124, v88 row_shr:2 row_mask:0xf bank_mask:0xf bound_ctrl:1
	v_mov_b32_dpp v125, v89 row_shr:2 row_mask:0xf bank_mask:0xf bound_ctrl:1
	v_pk_mul_f32 v[130:131], v[128:129], v[92:93]
	v_mov_b32_e32 v92, 1.0
	v_mov_b32_e32 v93, 1.0
	v_pk_fma_f32 v[88:89], v[128:129], v[124:125], v[88:89]
	v_mov_b32_dpp v92, v130 row_shr:4 row_mask:0xf bank_mask:0xf
	v_mov_b32_dpp v93, v131 row_shr:4 row_mask:0xf bank_mask:0xf
	v_mov_b32_dpp v124, v88 row_shr:4 row_mask:0xf bank_mask:0xf bound_ctrl:1
	v_mov_b32_dpp v125, v89 row_shr:4 row_mask:0xf bank_mask:0xf bound_ctrl:1
	v_pk_mul_f32 v[132:133], v[130:131], v[92:93]
	v_mov_b32_e32 v92, 1.0
	v_mov_b32_e32 v93, 1.0
	v_pk_fma_f32 v[88:89], v[130:131], v[124:125], v[88:89]
	v_mov_b32_dpp v92, v132 row_shr:8 row_mask:0xf bank_mask:0xf
	v_mov_b32_dpp v93, v133 row_shr:8 row_mask:0xf bank_mask:0xf
	v_mov_b32_dpp v124, v88 row_shr:8 row_mask:0xf bank_mask:0xf bound_ctrl:1
	v_mov_b32_dpp v125, v89 row_shr:8 row_mask:0xf bank_mask:0xf bound_ctrl:1
	v_pk_mul_f32 v[134:135], v[132:133], v[92:93]
	v_pk_fma_f32 v[88:89], v[132:133], v[124:125], v[88:89]
	v_or_b32_e32 v124, s48, v139
	v_pk_fma_f32 v[96:97], v[134:135], v[96:97], v[88:89]
	v_ashrrev_i32_e32 v125, 31, v124
	v_pk_mul_f32 v[90:91], v[134:135], v[90:91]
	ds_bpermute_b32 v88, v143, v96 offset:60
	ds_bpermute_b32 v89, v143, v97 offset:60
	v_cvt_pk_bf16_f32 v99, v96, v97
	v_lshlrev_b64 v[96:97], 11, v[124:125]
	ds_bpermute_b32 v92, v143, v90 offset:60
	ds_bpermute_b32 v93, v143, v91 offset:60
	v_lshl_add_u64 v[96:97], v[114:115], 0, v[96:97]
	v_cvt_pk_bf16_f32 v127, v90, v91
	v_lshlrev_b64 v[90:91], 10, v[124:125]
	v_mov_b64_e32 v[238:239], v[98:99]
	v_cvt_pk_bf16_f32 v126, v148, v149
	v_lshl_add_u64 v[98:99], v[116:117], 0, v[90:91]
	v_mov_b64_e32 v[242:243], v[126:127]
	v_mfma_f32_16x16x32_bf16 v[124:127], v[56:59], v[4:7], 0
	v_mfma_f32_16x16x32_bf16 v[56:59], v[60:63], v[20:23], v[52:55]
	v_mfma_f32_16x16x32_bf16 v[52:55], v[64:67], v[20:23], v[124:127]
	s_nop 5
	v_add_u32_e32 v124, v142, v138
	v_add_f32_e32 v48, v48, v56
	v_add_f32_e32 v49, v49, v57
	v_mul_f32_e32 v48, 0xbfb8aa3b, v48
	v_mul_f32_e32 v49, 0xbfb8aa3b, v49
	v_exp_f32_e32 v48, v48
	v_exp_f32_e32 v49, v49
	v_add_f32_e32 v44, v44, v52
	v_add_f32_e32 v45, v45, v53
	v_mul_f32_e32 v44, 0xbfb8aa3b, v44
	v_mul_f32_e32 v45, 0xbfb8aa3b, v45
	v_add_f32_e32 v48, 1.0, v48
	v_exp_f32_e32 v44, v44
	v_add_f32_e32 v49, 1.0, v49
	v_exp_f32_e32 v45, v45
	v_rcp_f32_e32 v56, v48
	v_rcp_f32_e32 v52, v49
	v_add_f32_e32 v44, 1.0, v44
	v_add_f32_e32 v45, 1.0, v45
	v_rcp_f32_e32 v48, v44
	v_mul_f32_e32 v44, 0xc1000000, v56
	v_rcp_f32_e32 v49, v45
	v_mul_f32_e32 v45, 0xc1000000, v52
	v_mul_f32_e32 v44, v145, v44
	v_mul_f32_e32 v45, v147, v45
	v_mul_f32_e32 v44, 0x3fb8aa3b, v44
	v_mul_f32_e32 v45, 0x3fb8aa3b, v45
	v_exp_f32_e32 v56, v44
	v_exp_f32_e32 v57, v45
	v_add_f32_e32 v50, v50, v58
	v_mul_f32_e32 v50, 0xbfb8aa3b, v50
	v_fma_f32 v44, -v56, v56, 1.0
	v_fma_f32 v45, -v57, v57, 1.0
	v_sqrt_f32_e32 v60, v44
	v_mov_b32_e32 v44, 1.0
	v_sqrt_f32_e32 v61, v45
	v_mov_b32_e32 v45, 1.0
	v_exp_f32_e32 v50, v50
	v_mov_b32_dpp v44, v56 row_shr:1 row_mask:0xf bank_mask:0xf
	v_mov_b32_dpp v45, v57 row_shr:1 row_mask:0xf bank_mask:0xf
	v_pk_mul_f32 v[62:63], v[56:57], v[44:45]
	v_mov_b32_e32 v44, 1.0
	v_mov_b32_e32 v45, 1.0
	v_add_f32_e32 v46, v46, v54
	v_mov_b32_dpp v44, v62 row_shr:2 row_mask:0xf bank_mask:0xf
	v_mov_b32_dpp v45, v63 row_shr:2 row_mask:0xf bank_mask:0xf
	v_mul_f32_e32 v46, 0xbfb8aa3b, v46
	v_pk_mul_f32 v[64:65], v[62:63], v[44:45]
	v_mov_b32_e32 v44, 1.0
	v_mov_b32_e32 v45, 1.0
	v_add_f32_e32 v50, 1.0, v50
	v_exp_f32_e32 v46, v46
	v_mov_b32_dpp v44, v64 row_shr:4 row_mask:0xf bank_mask:0xf
	v_mov_b32_dpp v45, v65 row_shr:4 row_mask:0xf bank_mask:0xf
	v_rcp_f32_e32 v50, v50
	v_pk_mul_f32 v[66:67], v[64:65], v[44:45]
	v_mov_b32_e32 v44, 1.0
	v_mov_b32_e32 v45, 1.0
	v_add_f32_e32 v46, 1.0, v46
	v_mov_b32_dpp v44, v66 row_shr:8 row_mask:0xf bank_mask:0xf
	v_mov_b32_dpp v45, v67 row_shr:8 row_mask:0xf bank_mask:0xf
	v_pk_mul_f32 v[90:91], v[66:67], v[44:45]
	v_rcp_f32_e32 v54, v46
	v_pk_mul_f32 v[52:53], v[90:91], v[122:123]
	ds_read2_b32 v[122:123], v124 offset1:1
	v_mul_f32_e32 v46, 0xc1000000, v50
	v_mul_f32_e32 v2, v2, v46
	v_mul_f32_e32 v2, 0x3fb8aa3b, v2
	v_exp_f32_e32 v50, v2
	s_waitcnt lgkmcnt(0)
; __device__ __forceinline__ unsigned pk2(float lo, float hi) { const f32x2_t v = {lo, hi}; const bf16x2_t b = __builtin_convertvector(v, bf16x2_t); return __builtin_bit_cast(unsigned, b); }
; __device__ __forceinline__ float sigmoidf_(float x) { return __builtin_amdgcn_rcpf(1.0f + __expf(-x)); }
; __device__ __forceinline__ void w_lru_m1(const Args& a, int l, unsigned char* ws, const bf16_t* proj, bf16_t* y, LAS unsigned char* wl, int b, int ck_, int h, int lane) {
;     ...
;         for (int tb = 0; tb < 4; ++tb) { const int tok = 16 * tb + lo;
;             f32x4 ga = {0.f, 0.f, 0.f, 0.f}, gx = {0.f, 0.f, 0.f, 0.f};
; #pragma unroll
;             for (int kk = 0; kk < 2; ++kk) { ga = __builtin_amdgcn_mfma_f32_16x16x32_bf16(WaF[kk], Xf[tb][kk], ga, 0, 0, 0); gx = __builtin_amdgcn_mfma_f32_16x16x32_bf16(WxF[kk], Xf[tb][kk], gx, 0, 0, 0); }
;             float hv[4], pv[4];
; #pragma unroll
;             for (int r = 0; r < 4; ++r) {
;                 const float rg = sigmoidf_(ga[r] + bav[r]), ig = sigmoidf_(gx[r] + bxv[r]);
;                 const float la = -8.0f * rg * sp[r]; float A = __expf(la);
;                 float U = __builtin_amdgcn_sqrtf(1.0f - A * A) * (ig * xcf[tok * 65 + j0 + r]);
;                 { const float As = dpp_shr1<1>(A), Us = dpp_shr0<1>(U); U = A * Us + U; A = A * As; }
;                 { const float As = dpp_shr1<2>(A), Us = dpp_shr0<2>(U); U = A * Us + U; A = A * As; }
;                 { const float As = dpp_shr1<4>(A), Us = dpp_shr0<4>(U); U = A * Us + U; A = A * As; }
;                 { const float As = dpp_shr1<8>(A), Us = dpp_shr0<8>(U); U = A * Us + U; A = A * As; }
;                 const float hh = U + A * hc[r], PP = A * Pc[r];
;                 hc[r] = bcast15(hh, lane); Pc[r] = bcast15(PP, lane); hv[r] = hh; pv[r] = PP; }
;             *(unsigned long long*)(y + (size_t)(row0 + tok) * DM + 64 * h + j0) = (unsigned long long)pk2(hv[0], hv[1]) | ((unsigned long long)pk2(hv[2], hv[3]) << 32);
;             *(unsigned long long*)((bf16_t*)(ws + WS_P) + (size_t)(row0 + tok) * 512 + 64 * h + j0) = (unsigned long long)pk2(pv[0], pv[1]) | ((unsigned long long)pk2(pv[2], pv[3]) << 32);
;         }
;         if (lo == 0) { const size_t so = (size_t)(b * NCH + ck_) * 512 + 64 * h + j0;
; #pragma unroll
;             for (int r = 0; r < 4; ++r) { ((float*)(ws + WS_LRUA))[so + r] = Pc[r]; ((float*)(ws + WS_LRUH))[so + r] = hc[r]; } }
	v_pk_mul_f32 v[48:49], v[122:123], v[48:49]
	v_add_f32_e32 v47, v47, v55
	v_pk_mul_f32 v[48:49], v[48:49], v[60:61]
	v_fma_f32 v2, -v50, v50, 1.0
	v_mul_f32_e32 v47, 0xbfb8aa3b, v47
	v_mov_b32_dpp v60, v48 row_shr:1 row_mask:0xf bank_mask:0xf bound_ctrl:1
	v_mov_b32_dpp v61, v49 row_shr:1 row_mask:0xf bank_mask:0xf bound_ctrl:1
	v_pk_fma_f32 v[48:49], v[56:57], v[60:61], v[48:49]
	v_sqrt_f32_e32 v60, v2
	v_add_f32_e32 v2, v51, v59
	v_mul_f32_e32 v2, 0xbfb8aa3b, v2
	v_exp_f32_e32 v2, v2
	v_exp_f32_e32 v47, v47
	v_mov_b32_e32 v46, 1.0
	v_mov_b32_dpp v56, v48 row_shr:2 row_mask:0xf bank_mask:0xf bound_ctrl:1
	v_add_f32_e32 v2, 1.0, v2
	v_rcp_f32_e32 v2, v2
	v_add_f32_e32 v47, 1.0, v47
	v_rcp_f32_e32 v55, v47
	v_mov_b32_e32 v47, 1.0
	v_mul_f32_e32 v2, 0xc1000000, v2
	v_mul_f32_e32 v2, v146, v2
	v_mul_f32_e32 v2, 0x3fb8aa3b, v2
	v_exp_f32_e32 v51, v2
	v_mov_b32_dpp v57, v49 row_shr:2 row_mask:0xf bank_mask:0xf bound_ctrl:1
	v_mov_b32_dpp v46, v50 row_shr:1 row_mask:0xf bank_mask:0xf
	v_pk_fma_f32 v[48:49], v[62:63], v[56:57], v[48:49]
	v_mov_b32_dpp v47, v51 row_shr:1 row_mask:0xf bank_mask:0xf
	v_pk_mul_f32 v[62:63], v[50:51], v[46:47]
	v_mov_b32_e32 v46, 1.0
	v_mov_b32_e32 v47, 1.0
	v_mov_b32_dpp v56, v48 row_shr:4 row_mask:0xf bank_mask:0xf bound_ctrl:1
	v_mov_b32_dpp v57, v49 row_shr:4 row_mask:0xf bank_mask:0xf bound_ctrl:1
	v_mov_b32_dpp v46, v62 row_shr:2 row_mask:0xf bank_mask:0xf
	v_mov_b32_dpp v47, v63 row_shr:2 row_mask:0xf bank_mask:0xf
	v_pk_fma_f32 v[48:49], v[64:65], v[56:57], v[48:49]
	v_pk_mul_f32 v[64:65], v[62:63], v[46:47]
	v_mov_b32_e32 v46, 1.0
	v_mov_b32_e32 v47, 1.0
	v_mov_b32_dpp v56, v48 row_shr:8 row_mask:0xf bank_mask:0xf bound_ctrl:1
	v_mov_b32_dpp v57, v49 row_shr:8 row_mask:0xf bank_mask:0xf bound_ctrl:1
	v_mov_b32_dpp v46, v64 row_shr:4 row_mask:0xf bank_mask:0xf
	v_mov_b32_dpp v47, v65 row_shr:4 row_mask:0xf bank_mask:0xf
	v_pk_fma_f32 v[48:49], v[66:67], v[56:57], v[48:49]
	v_pk_mul_f32 v[66:67], v[64:65], v[46:47]
	v_mov_b32_e32 v46, 1.0
	v_mov_b32_e32 v47, 1.0
	v_pk_fma_f32 v[56:57], v[90:91], v[94:95], v[48:49]
	v_mov_b32_dpp v46, v66 row_shr:8 row_mask:0xf bank_mask:0xf
	v_mov_b32_dpp v47, v67 row_shr:8 row_mask:0xf bank_mask:0xf
	v_pk_mul_f32 v[90:91], v[66:67], v[46:47]
	v_fma_f32 v2, -v51, v51, 1.0
	v_pk_mul_f32 v[58:59], v[90:91], v[92:93]
	ds_read2_b32 v[92:93], v124 offset0:2 offset1:3
	v_sqrt_f32_e32 v61, v2
	ds_bpermute_b32 v44, v143, v52 offset:60
	ds_bpermute_b32 v48, v143, v56 offset:60
	ds_bpermute_b32 v49, v143, v57 offset:60
	s_waitcnt lgkmcnt(0)
	v_pk_mul_f32 v[54:55], v[54:55], v[92:93]
	ds_bpermute_b32 v45, v143, v53 offset:60
	v_pk_mul_f32 v[54:55], v[60:61], v[54:55]
	ds_bpermute_b32 v46, v143, v58 offset:60
	ds_bpermute_b32 v47, v143, v59 offset:60
	v_mov_b32_dpp v60, v54 row_shr:1 row_mask:0xf bank_mask:0xf bound_ctrl:1
	v_mov_b32_dpp v61, v55 row_shr:1 row_mask:0xf bank_mask:0xf bound_ctrl:1
	v_pk_fma_f32 v[50:51], v[50:51], v[60:61], v[54:55]
	v_cvt_pk_bf16_f32 v56, v56, v57
	v_cvt_pk_bf16_f32 v52, v52, v53
	v_mov_b32_dpp v54, v50 row_shr:2 row_mask:0xf bank_mask:0xf bound_ctrl:1
	v_mov_b32_dpp v55, v51 row_shr:2 row_mask:0xf bank_mask:0xf bound_ctrl:1
	v_pk_fma_f32 v[50:51], v[62:63], v[54:55], v[50:51]
	v_cvt_pk_bf16_f32 v53, v58, v59
	s_nop 0
	v_mov_b32_dpp v54, v50 row_shr:4 row_mask:0xf bank_mask:0xf bound_ctrl:1
	v_mov_b32_dpp v55, v51 row_shr:4 row_mask:0xf bank_mask:0xf bound_ctrl:1
	v_pk_fma_f32 v[50:51], v[64:65], v[54:55], v[50:51]
	s_nop 1
	v_mov_b32_dpp v54, v50 row_shr:8 row_mask:0xf bank_mask:0xf bound_ctrl:1
	v_mov_b32_dpp v55, v51 row_shr:8 row_mask:0xf bank_mask:0xf bound_ctrl:1
	v_pk_fma_f32 v[50:51], v[66:67], v[54:55], v[50:51]
	s_nop 0
	v_pk_fma_f32 v[54:55], v[90:91], v[88:89], v[50:51]
	ds_bpermute_b32 v50, v143, v54 offset:60
	ds_bpermute_b32 v51, v143, v55 offset:60
	v_cvt_pk_bf16_f32 v57, v54, v55
	v_or_b32_e32 v54, s48, v137
	v_ashrrev_i32_e32 v55, 31, v54
	v_lshlrev_b64 v[60:61], 11, v[54:55]
	v_lshlrev_b64 v[54:55], 10, v[54:55]
	v_lshl_add_u64 v[114:115], v[114:115], 0, v[60:61]
	v_lshl_add_u64 v[116:117], v[116:117], 0, v[54:55]
	v_mov_b64_e32 v[246:247], v[56:57]
	v_mov_b64_e32 v[250:251], v[52:53]
	s_and_saveexec_b64 s[34:35], vcc
	s_cbranch_execz .LBB0_523
	v_lshl_add_u64 v[52:53], s[42:43], 0, v[0:1]
	v_lshlrev_b64 v[52:53], 2, v[52:53]
	v_lshl_add_u64 v[54:55], s[84:85], 0, v[52:53]
	v_lshl_add_u64 v[52:53], s[86:87], 0, v[52:53]
	s_waitcnt lgkmcnt(0)
	global_store_dwordx4 v[54:55], v[44:47], off
	global_store_dwordx4 v[52:53], v[48:51], off
; __device__ __forceinline__ void w_lru_m1(const Args& a, int l, unsigned char* ws, const bf16_t* proj, bf16_t* y, LAS unsigned char* wl, int b, int ck_, int h, int lane) {
;     ...
;     for (int jb = 0; jb < 4; ++jb) {
;         bf16x8 WaF[2], WxF[2]; f32x4 pba, pbx, plam;
; #pragma unroll
;         for (int kk = 0; kk < 2; ++kk) { WaF[kk] = nWa[kk]; WxF[kk] = nWx[kk]; }
;         pba = nba; pbx = nbx; plam = nlam;
;         if (jb < 3) {
; #pragma unroll
;             for (int kk = 0; kk < 2; ++kk) { nWa[kk] = *(const bf16x8*)(waT + (16 * (jb + 1) + lo) * 64 + 32 * kk + 8 * fq); nWx[kk] = *(const bf16x8*)(wxT + (16 * (jb + 1) + lo) * 64 + 32 * kk + 8 * fq); }
;             nba = *(const f32x4*)(ba + 16 * (jb + 1) + 4 * fq); nbx = *(const f32x4*)(bx + 16 * (jb + 1) + 4 * fq); nlam = *(const f32x4*)(lam + 16 * (jb + 1) + 4 * fq);
;         }
;         const int j0 = 16 * jb + 4 * fq;
;         float bav[4], bxv[4], sp[4], hc[4], Pc[4];
; #pragma unroll
;         for (int r = 0; r < 4; ++r) { bav[r] = pba[r]; bxv[r] = pbx[r]; sp[r] = log1pf(__expf(-plam[r])); hc[r] = 0.f; Pc[r] = 1.f; }
; #pragma unroll
;         for (int tb = 0; tb < 4; ++tb) { const int tok = 16 * tb + lo;
;             f32x4 ga = {0.f, 0.f, 0.f, 0.f}, gx = {0.f, 0.f, 0.f, 0.f};
; #pragma unroll
;             for (int kk = 0; kk < 2; ++kk) { ga = __builtin_amdgcn_mfma_f32_16x16x32_bf16(WaF[kk], Xf[tb][kk], ga, 0, 0, 0); gx = __builtin_amdgcn_mfma_f32_16x16x32_bf16(WxF[kk], Xf[tb][kk], gx, 0, 0, 0); }
;             float hv[4], pv[4];
; #pragma unroll
;             for (int r = 0; r < 4; ++r) {
;                 const float rg = sigmoidf_(ga[r] + bav[r]), ig = sigmoidf_(gx[r] + bxv[r]);
;                 const float la = -8.0f * rg * sp[r]; float A = __expf(la);
;                 float U = __builtin_amdgcn_sqrtf(1.0f - A * A) * (ig * xcf[tok * 65 + j0 + r]);
;                 { const float As = dpp_shr1<1>(A), Us = dpp_shr0<1>(U); U = A * Us + U; A = A * As; }
;                 { const float As = dpp_shr1<2>(A), Us = dpp_shr0<2>(U); U = A * Us + U; A = A * As; }
;                 { const float As = dpp_shr1<4>(A), Us = dpp_shr0<4>(U); U = A * Us + U; A = A * As; }
;                 { const float As = dpp_shr1<8>(A), Us = dpp_shr0<8>(U); U = A * Us + U; A = A * As; }
;                 const float hh = U + A * hc[r], PP = A * Pc[r];
.LBB0_523:
	s_or_b64 exec, exec, s[34:35]
	v_lshlrev_b32_e32 v146, 6, v136
	v_lshl_or_b32 v2, v146, 1, v209
	s_waitcnt lgkmcnt(0)
	v_lshl_add_u64 v[44:45], v[118:119], 0, v[2:3]
	v_lshl_add_u64 v[46:47], v[120:121], 0, v[2:3]
	s_waitcnt vmcnt(2)
	s_nop 7
	v_mul_u32_u24_e32 v92, 0x104, v136
	v_add_u32_e32 v145, v142, v92
	global_load_dwordx4 v[64:67], v[44:45], off
	global_load_dwordx4 v[60:63], v[46:47], off
	global_load_dwordx4 v[56:59], v[44:45], off offset:64
	global_load_dwordx4 v[52:55], v[46:47], off offset:64
	global_load_dwordx4 v[48:51], v[108:109], off offset:128
	s_nop 0
	global_load_dwordx4 v[44:47], v[110:111], off offset:128
	global_load_dwordx4 v[88:91], v[112:113], off offset:128
	s_nop 7
	v_mov_b32_e32 v132, 1.0
	s_nop 7
	v_mov_b32_e32 v133, 1.0
	s_nop 7
	v_or_b32_e32 v1, 60, v143
	ds_read2_b32 v[136:137], v145 offset0:18 offset1:19
	s_nop 7
	s_nop 1
	s_nop 7
	s_nop 1
	s_nop 7
	v_mov_b32_e32 v147, v84
	s_nop 7
	s_nop 0
	s_nop 7
	s_nop 0
	s_nop 7
	s_nop 0
	s_nop 7
	s_nop 0
	s_nop 7
	s_nop 1
	s_nop 7
	s_nop 1
	s_nop 7
	s_nop 1
	s_nop 7
	v_mov_b32_e32 v149, v85
	s_nop 7
	s_nop 0
	s_nop 7
	s_nop 0
	s_nop 7
	v_mov_b32_e32 v130, 1.0
	s_nop 7
	v_mov_b32_e32 v131, 1.0
	s_nop 7
	s_nop 1
	s_nop 7
	s_nop 1
	s_nop 7
	s_nop 1
	s_nop 7
	v_mov_b32_e32 v2, v86
	s_nop 7
	s_nop 0
	s_nop 7
	s_nop 0
	s_nop 7
	s_nop 0
	s_nop 7
	s_nop 0
	s_nop 7
	v_mov_b32_e32 v128, 1.0
	s_nop 7
	v_mov_b32_e32 v129, 1.0
	s_nop 7
	v_mfma_f32_16x16x32_bf16 v[122:125], v[72:75], v[16:19], 0
	s_nop 0
	s_nop 7
	v_mfma_f32_16x16x32_bf16 v[124:127], v[80:83], v[32:35], v[122:125]
	s_nop 0
	s_nop 7
	s_nop 1
	s_nop 7
	v_mov_b32_e32 v148, v87
	v_mfma_f32_16x16x32_bf16 v[84:87], v[68:71], v[16:19], 0
	v_mfma_f32_16x16x32_bf16 v[84:87], v[76:79], v[32:35], v[84:87]
	s_nop 7
	v_add_f32_e32 v84, v40, v84
	v_mul_f32_e32 v84, 0xbfb8aa3b, v84
	v_exp_f32_e32 v84, v84
	v_add_f32_e32 v85, v41, v85
	v_mul_f32_e32 v85, 0xbfb8aa3b, v85
	v_exp_f32_e32 v85, v85
	v_add_f32_e32 v84, 1.0, v84
	v_rcp_f32_e32 v93, v84
	v_add_f32_e32 v84, v36, v124
	v_add_f32_e32 v85, 1.0, v85
	v_mul_f32_e32 v84, 0xbfb8aa3b, v84
	v_mul_f32_e32 v93, 0xc1000000, v93
	v_mul_f32_e32 v93, v147, v93
	v_mul_f32_e32 v93, 0x3fb8aa3b, v93
	v_exp_f32_e32 v94, v93
	v_exp_f32_e32 v84, v84
	v_mov_b32_e32 v124, 1.0
	v_add_f32_e32 v86, v42, v86
	v_fma_f32 v93, -v94, v94, 1.0
	v_sqrt_f32_e32 v122, v93
	v_rcp_f32_e32 v93, v85
	v_add_f32_e32 v85, v37, v125
	v_mul_f32_e32 v85, 0xbfb8aa3b, v85
	v_exp_f32_e32 v85, v85
	v_mul_f32_e32 v93, 0xc1000000, v93
	v_mul_f32_e32 v93, v149, v93
	v_mul_f32_e32 v93, 0x3fb8aa3b, v93
	v_exp_f32_e32 v95, v93
	v_add_f32_e32 v84, 1.0, v84
	v_add_f32_e32 v85, 1.0, v85
	v_rcp_f32_e32 v84, v84
	v_fma_f32 v93, -v95, v95, 1.0
	v_sqrt_f32_e32 v123, v93
	ds_read2_b32 v[92:93], v145 offset0:16 offset1:17
	v_rcp_f32_e32 v85, v85
	v_mov_b32_e32 v125, 1.0
	v_mov_b32_dpp v124, v94 row_shr:1 row_mask:0xf bank_mask:0xf
	v_mul_f32_e32 v86, 0xbfb8aa3b, v86
	s_waitcnt lgkmcnt(0)
	v_pk_mul_f32 v[84:85], v[92:93], v[84:85]
	v_mov_b32_dpp v125, v95 row_shr:1 row_mask:0xf bank_mask:0xf
	v_pk_mul_f32 v[84:85], v[84:85], v[122:123]
	v_pk_mul_f32 v[124:125], v[94:95], v[124:125]
	v_exp_f32_e32 v86, v86
	v_mov_b32_dpp v92, v84 row_shr:1 row_mask:0xf bank_mask:0xf bound_ctrl:1
	v_mov_b32_dpp v93, v85 row_shr:1 row_mask:0xf bank_mask:0xf bound_ctrl:1
	v_pk_fma_f32 v[84:85], v[94:95], v[92:93], v[84:85]
	v_mov_b32_dpp v128, v124 row_shr:2 row_mask:0xf bank_mask:0xf
	v_mov_b32_dpp v129, v125 row_shr:2 row_mask:0xf bank_mask:0xf
	v_mov_b32_dpp v92, v84 row_shr:2 row_mask:0xf bank_mask:0xf bound_ctrl:1
	v_mov_b32_dpp v93, v85 row_shr:2 row_mask:0xf bank_mask:0xf bound_ctrl:1
	v_pk_fma_f32 v[84:85], v[124:125], v[92:93], v[84:85]
	v_pk_mul_f32 v[128:129], v[124:125], v[128:129]
	v_add_f32_e32 v86, 1.0, v86
	v_mov_b32_dpp v92, v84 row_shr:4 row_mask:0xf bank_mask:0xf bound_ctrl:1
	v_mov_b32_dpp v93, v85 row_shr:4 row_mask:0xf bank_mask:0xf bound_ctrl:1
	v_mov_b32_dpp v130, v128 row_shr:4 row_mask:0xf bank_mask:0xf
	v_mov_b32_dpp v131, v129 row_shr:4 row_mask:0xf bank_mask:0xf
	v_pk_fma_f32 v[84:85], v[128:129], v[92:93], v[84:85]
	v_pk_mul_f32 v[130:131], v[128:129], v[130:131]
	v_add_f32_e32 v87, v43, v87
	v_mov_b32_dpp v92, v84 row_shr:8 row_mask:0xf bank_mask:0xf bound_ctrl:1
	v_mov_b32_dpp v93, v85 row_shr:8 row_mask:0xf bank_mask:0xf bound_ctrl:1
	v_pk_fma_f32 v[84:85], v[130:131], v[92:93], v[84:85]
	v_rcp_f32_e32 v92, v86
	v_mul_f32_e32 v87, 0xbfb8aa3b, v87
	v_exp_f32_e32 v87, v87
	v_add_f32_e32 v86, v38, v126
	v_mul_f32_e32 v92, 0xc1000000, v92
	v_mul_f32_e32 v92, v2, v92
	v_mul_f32_e32 v92, 0x3fb8aa3b, v92
	v_exp_f32_e32 v92, v92
	v_add_f32_e32 v87, 1.0, v87
	v_mul_f32_e32 v86, 0xbfb8aa3b, v86
	v_exp_f32_e32 v86, v86
	v_fma_f32 v93, -v92, v92, 1.0
	v_sqrt_f32_e32 v94, v93
	v_rcp_f32_e32 v93, v87
	v_add_f32_e32 v87, v39, v127
	v_mul_f32_e32 v87, 0xbfb8aa3b, v87
	v_exp_f32_e32 v87, v87
	v_mul_f32_e32 v93, 0xc1000000, v93
	v_mul_f32_e32 v93, v148, v93
	v_mul_f32_e32 v93, 0x3fb8aa3b, v93
	v_exp_f32_e32 v93, v93
	v_add_f32_e32 v86, 1.0, v86
	v_add_f32_e32 v87, 1.0, v87
	v_rcp_f32_e32 v86, v86
	v_rcp_f32_e32 v87, v87
	v_fma_f32 v95, -v93, v93, 1.0
	v_sqrt_f32_e32 v95, v95
	v_mov_b32_e32 v122, 1.0
	v_pk_mul_f32 v[86:87], v[86:87], v[136:137]
	v_mov_b32_e32 v123, 1.0
	v_pk_mul_f32 v[86:87], v[94:95], v[86:87]
	v_mov_b32_dpp v122, v92 row_shr:1 row_mask:0xf bank_mask:0xf
	v_mov_b32_dpp v123, v93 row_shr:1 row_mask:0xf bank_mask:0xf
	v_mov_b32_dpp v94, v86 row_shr:1 row_mask:0xf bank_mask:0xf bound_ctrl:1
	v_mov_b32_dpp v95, v87 row_shr:1 row_mask:0xf bank_mask:0xf bound_ctrl:1
	v_pk_mul_f32 v[122:123], v[92:93], v[122:123]
; __device__ __forceinline__ unsigned pk2(float lo, float hi) { const f32x2_t v = {lo, hi}; const bf16x2_t b = __builtin_convertvector(v, bf16x2_t); return __builtin_bit_cast(unsigned, b); }
; __device__ __forceinline__ float sigmoidf_(float x) { return __builtin_amdgcn_rcpf(1.0f + __expf(-x)); }
; __device__ __forceinline__ float bcast15(float v, int lane) { return bperm_f((lane & 48) | 15, v); }
; __device__ __forceinline__ void w_lru_m1(const Args& a, int l, unsigned char* ws, const bf16_t* proj, bf16_t* y, LAS unsigned char* wl, int b, int ck_, int h, int lane) {
;     ...
;         for (int tb = 0; tb < 4; ++tb) { const int tok = 16 * tb + lo;
;             f32x4 ga = {0.f, 0.f, 0.f, 0.f}, gx = {0.f, 0.f, 0.f, 0.f};
; #pragma unroll
;             for (int kk = 0; kk < 2; ++kk) { ga = __builtin_amdgcn_mfma_f32_16x16x32_bf16(WaF[kk], Xf[tb][kk], ga, 0, 0, 0); gx = __builtin_amdgcn_mfma_f32_16x16x32_bf16(WxF[kk], Xf[tb][kk], gx, 0, 0, 0); }
;             float hv[4], pv[4];
; #pragma unroll
;             for (int r = 0; r < 4; ++r) {
;                 const float rg = sigmoidf_(ga[r] + bav[r]), ig = sigmoidf_(gx[r] + bxv[r]);
;                 const float la = -8.0f * rg * sp[r]; float A = __expf(la);
;                 float U = __builtin_amdgcn_sqrtf(1.0f - A * A) * (ig * xcf[tok * 65 + j0 + r]);
;                 { const float As = dpp_shr1<1>(A), Us = dpp_shr0<1>(U); U = A * Us + U; A = A * As; }
;                 { const float As = dpp_shr1<2>(A), Us = dpp_shr0<2>(U); U = A * Us + U; A = A * As; }
;                 { const float As = dpp_shr1<4>(A), Us = dpp_shr0<4>(U); U = A * Us + U; A = A * As; }
;                 { const float As = dpp_shr1<8>(A), Us = dpp_shr0<8>(U); U = A * Us + U; A = A * As; }
;                 const float hh = U + A * hc[r], PP = A * Pc[r];
;                 hc[r] = bcast15(hh, lane); Pc[r] = bcast15(PP, lane); hv[r] = hh; pv[r] = PP; }
;             *(unsigned long long*)(y + (size_t)(row0 + tok) * DM + 64 * h + j0) = (unsigned long long)pk2(hv[0], hv[1]) | ((unsigned long long)pk2(hv[2], hv[3]) << 32);
;             *(unsigned long long*)((bf16_t*)(ws + WS_P) + (size_t)(row0 + tok) * 512 + 64 * h + j0) = (unsigned long long)pk2(pv[0], pv[1]) | ((unsigned long long)pk2(pv[2], pv[3]) << 32);
	v_mov_b32_e32 v126, 1.0
	v_mov_b32_e32 v127, 1.0
	v_pk_fma_f32 v[86:87], v[92:93], v[94:95], v[86:87]
	v_mov_b32_dpp v126, v122 row_shr:2 row_mask:0xf bank_mask:0xf
	v_mov_b32_dpp v127, v123 row_shr:2 row_mask:0xf bank_mask:0xf
	v_mov_b32_dpp v92, v86 row_shr:2 row_mask:0xf bank_mask:0xf bound_ctrl:1
	v_mov_b32_dpp v93, v87 row_shr:2 row_mask:0xf bank_mask:0xf bound_ctrl:1
	v_pk_mul_f32 v[126:127], v[122:123], v[126:127]
	v_mov_b32_e32 v128, 1.0
	v_mov_b32_e32 v129, 1.0
	v_pk_fma_f32 v[86:87], v[122:123], v[92:93], v[86:87]
	v_mov_b32_dpp v132, v130 row_shr:8 row_mask:0xf bank_mask:0xf
	v_mov_b32_dpp v133, v131 row_shr:8 row_mask:0xf bank_mask:0xf
	v_mov_b32_dpp v128, v126 row_shr:4 row_mask:0xf bank_mask:0xf
	v_mov_b32_dpp v129, v127 row_shr:4 row_mask:0xf bank_mask:0xf
	v_mov_b32_dpp v92, v86 row_shr:4 row_mask:0xf bank_mask:0xf bound_ctrl:1
	v_mov_b32_dpp v93, v87 row_shr:4 row_mask:0xf bank_mask:0xf bound_ctrl:1
	v_pk_mul_f32 v[134:135], v[130:131], v[132:133]
	v_pk_mul_f32 v[128:129], v[126:127], v[128:129]
	v_mov_b32_e32 v130, 1.0
	v_mov_b32_e32 v131, 1.0
	v_pk_fma_f32 v[86:87], v[126:127], v[92:93], v[86:87]
	v_mov_b32_dpp v130, v128 row_shr:8 row_mask:0xf bank_mask:0xf
	v_mov_b32_dpp v131, v129 row_shr:8 row_mask:0xf bank_mask:0xf
	v_mov_b32_dpp v92, v86 row_shr:8 row_mask:0xf bank_mask:0xf bound_ctrl:1
	v_mov_b32_dpp v93, v87 row_shr:8 row_mask:0xf bank_mask:0xf bound_ctrl:1
	v_pk_mul_f32 v[130:131], v[128:129], v[130:131]
	v_pk_fma_f32 v[86:87], v[128:129], v[92:93], v[86:87]
	v_pk_fma_f32 v[84:85], v[134:135], 0, v[84:85] op_sel_hi:[1,0,1]
	v_pk_fma_f32 v[86:87], v[130:131], 0, v[86:87] op_sel_hi:[1,0,1]
	ds_bpermute_b32 v124, v1, v84
	ds_bpermute_b32 v125, v1, v85
	v_cvt_pk_bf16_f32 v84, v84, v85
	v_cvt_pk_bf16_f32 v85, v86, v87
	v_mov_b64_e32 v[224:225], v[84:85]
	s_nop 1
	v_permlane16_swap_b32_e32 v222, v224
	v_permlane16_swap_b32_e32 v223, v225
	global_store_dwordx4 v[100:101], v[222:225], off
	v_cvt_pk_bf16_f32 v84, v134, v135
	v_cvt_pk_bf16_f32 v85, v130, v131
	ds_bpermute_b32 v122, v1, v86
	ds_bpermute_b32 v123, v1, v87
	v_mov_b64_e32 v[228:229], v[84:85]
	s_nop 1
	v_permlane16_swap_b32_e32 v226, v228
	v_permlane16_swap_b32_e32 v227, v229
	global_store_dwordx4 v[102:103], v[226:229], off
	v_mfma_f32_16x16x32_bf16 v[84:87], v[68:71], v[12:15], 0
	ds_bpermute_b32 v132, v1, v130
	ds_bpermute_b32 v133, v1, v131
	ds_bpermute_b32 v150, v1, v134
	v_mfma_f32_16x16x32_bf16 v[126:129], v[72:75], v[12:15], 0
	ds_bpermute_b32 v151, v1, v135
	v_mfma_f32_16x16x32_bf16 v[92:95], v[76:79], v[28:31], v[84:87]
	v_mfma_f32_16x16x32_bf16 v[84:87], v[80:83], v[28:31], v[126:129]
	s_nop 6
	v_add_f32_e32 v92, v40, v92
	v_mul_f32_e32 v92, 0xbfb8aa3b, v92
	v_exp_f32_e32 v92, v92
	v_add_f32_e32 v84, v36, v84
	v_mul_f32_e32 v84, 0xbfb8aa3b, v84
	v_exp_f32_e32 v84, v84
	v_add_f32_e32 v92, 1.0, v92
	v_rcp_f32_e32 v92, v92
	v_add_f32_e32 v85, v37, v85
	v_add_f32_e32 v84, 1.0, v84
	v_rcp_f32_e32 v126, v84
	v_mul_f32_e32 v84, 0xc1000000, v92
	v_add_f32_e32 v92, v41, v93
	v_mul_f32_e32 v92, 0xbfb8aa3b, v92
	v_exp_f32_e32 v92, v92
	v_mul_f32_e32 v85, 0xbfb8aa3b, v85
	v_exp_f32_e32 v85, v85
	v_mul_f32_e32 v84, v147, v84
	v_add_f32_e32 v92, 1.0, v92
	v_rcp_f32_e32 v92, v92
	v_add_f32_e32 v85, 1.0, v85
	v_rcp_f32_e32 v127, v85
	v_mul_f32_e32 v84, 0x3fb8aa3b, v84
	v_mul_f32_e32 v85, 0xc1000000, v92
	v_mul_f32_e32 v85, v149, v85
	v_mul_f32_e32 v85, 0x3fb8aa3b, v85
	v_exp_f32_e32 v128, v84
	v_exp_f32_e32 v129, v85
	v_add_f32_e32 v94, v42, v94
	v_add_f32_e32 v95, v43, v95
	v_fma_f32 v84, -v128, v128, 1.0
	v_fma_f32 v85, -v129, v129, 1.0
	v_sqrt_f32_e32 v130, v84
	v_mov_b32_e32 v84, 1.0
	v_sqrt_f32_e32 v131, v85
	v_mov_b32_e32 v85, 1.0
	v_mov_b32_dpp v84, v128 row_shr:1 row_mask:0xf bank_mask:0xf
	v_mul_f32_e32 v94, 0xbfb8aa3b, v94
	v_mov_b32_dpp v85, v129 row_shr:1 row_mask:0xf bank_mask:0xf
	v_pk_mul_f32 v[134:135], v[128:129], v[84:85]
	v_mov_b32_e32 v84, 1.0
	v_mov_b32_e32 v85, 1.0
	v_mul_f32_e32 v95, 0xbfb8aa3b, v95
	v_mov_b32_dpp v84, v134 row_shr:2 row_mask:0xf bank_mask:0xf
	v_mov_b32_dpp v85, v135 row_shr:2 row_mask:0xf bank_mask:0xf
	v_pk_mul_f32 v[136:137], v[134:135], v[84:85]
	v_mov_b32_e32 v84, 1.0
	v_mov_b32_e32 v85, 1.0
	v_exp_f32_e32 v94, v94
	v_mov_b32_dpp v84, v136 row_shr:4 row_mask:0xf bank_mask:0xf
	v_mov_b32_dpp v85, v137 row_shr:4 row_mask:0xf bank_mask:0xf
	v_pk_mul_f32 v[138:139], v[136:137], v[84:85]
	v_mov_b32_e32 v84, 1.0
	v_mov_b32_e32 v85, 1.0
	v_exp_f32_e32 v95, v95
	v_mov_b32_dpp v84, v138 row_shr:8 row_mask:0xf bank_mask:0xf
	v_mov_b32_dpp v85, v139 row_shr:8 row_mask:0xf bank_mask:0xf
	v_pk_mul_f32 v[140:141], v[138:139], v[84:85]
	v_add_u32_e32 v85, 0x1080, v145
	ds_read2_b32 v[142:143], v85 offset1:1
	v_add_f32_e32 v86, v38, v86
	v_add_f32_e32 v87, v39, v87
	v_mul_f32_e32 v86, 0xbfb8aa3b, v86
	v_mul_f32_e32 v87, 0xbfb8aa3b, v87
	s_waitcnt lgkmcnt(0)
; __device__ __forceinline__ unsigned pk2(float lo, float hi) { const f32x2_t v = {lo, hi}; const bf16x2_t b = __builtin_convertvector(v, bf16x2_t); return __builtin_bit_cast(unsigned, b); }
; __device__ __forceinline__ float sigmoidf_(float x) { return __builtin_amdgcn_rcpf(1.0f + __expf(-x)); }
; __device__ __forceinline__ float bcast15(float v, int lane) { return bperm_f((lane & 48) | 15, v); }
; __device__ __forceinline__ void w_lru_m1(const Args& a, int l, unsigned char* ws, const bf16_t* proj, bf16_t* y, LAS unsigned char* wl, int b, int ck_, int h, int lane) {
;     ...
;         for (int tb = 0; tb < 4; ++tb) { const int tok = 16 * tb + lo;
;             f32x4 ga = {0.f, 0.f, 0.f, 0.f}, gx = {0.f, 0.f, 0.f, 0.f};
; #pragma unroll
;             for (int kk = 0; kk < 2; ++kk) { ga = __builtin_amdgcn_mfma_f32_16x16x32_bf16(WaF[kk], Xf[tb][kk], ga, 0, 0, 0); gx = __builtin_amdgcn_mfma_f32_16x16x32_bf16(WxF[kk], Xf[tb][kk], gx, 0, 0, 0); }
;             float hv[4], pv[4];
; #pragma unroll
;             for (int r = 0; r < 4; ++r) {
;                 const float rg = sigmoidf_(ga[r] + bav[r]), ig = sigmoidf_(gx[r] + bxv[r]);
;                 const float la = -8.0f * rg * sp[r]; float A = __expf(la);
;                 float U = __builtin_amdgcn_sqrtf(1.0f - A * A) * (ig * xcf[tok * 65 + j0 + r]);
;                 { const float As = dpp_shr1<1>(A), Us = dpp_shr0<1>(U); U = A * Us + U; A = A * As; }
;                 { const float As = dpp_shr1<2>(A), Us = dpp_shr0<2>(U); U = A * Us + U; A = A * As; }
;                 { const float As = dpp_shr1<4>(A), Us = dpp_shr0<4>(U); U = A * Us + U; A = A * As; }
;                 { const float As = dpp_shr1<8>(A), Us = dpp_shr0<8>(U); U = A * Us + U; A = A * As; }
;                 const float hh = U + A * hc[r], PP = A * Pc[r];
;                 hc[r] = bcast15(hh, lane); Pc[r] = bcast15(PP, lane); hv[r] = hh; pv[r] = PP; }
;             *(unsigned long long*)(y + (size_t)(row0 + tok) * DM + 64 * h + j0) = (unsigned long long)pk2(hv[0], hv[1]) | ((unsigned long long)pk2(hv[2], hv[3]) << 32);
;             *(unsigned long long*)((bf16_t*)(ws + WS_P) + (size_t)(row0 + tok) * 512 + 64 * h + j0) = (unsigned long long)pk2(pv[0], pv[1]) | ((unsigned long long)pk2(pv[2], pv[3]) << 32);
	v_pk_mul_f32 v[126:127], v[142:143], v[126:127]
	v_add_f32_e32 v94, 1.0, v94
	v_pk_mul_f32 v[126:127], v[126:127], v[130:131]
	v_exp_f32_e32 v86, v86
	v_add_f32_e32 v95, 1.0, v95
	v_mov_b32_dpp v130, v126 row_shr:1 row_mask:0xf bank_mask:0xf bound_ctrl:1
	v_mov_b32_dpp v131, v127 row_shr:1 row_mask:0xf bank_mask:0xf bound_ctrl:1
	v_pk_fma_f32 v[126:127], v[128:129], v[130:131], v[126:127]
	v_exp_f32_e32 v87, v87
	v_rcp_f32_e32 v94, v94
	v_mov_b32_dpp v128, v126 row_shr:2 row_mask:0xf bank_mask:0xf bound_ctrl:1
	v_mov_b32_dpp v129, v127 row_shr:2 row_mask:0xf bank_mask:0xf bound_ctrl:1
	v_pk_fma_f32 v[126:127], v[134:135], v[128:129], v[126:127]
	v_rcp_f32_e32 v95, v95
	v_add_f32_e32 v86, 1.0, v86
	v_mov_b32_dpp v128, v126 row_shr:4 row_mask:0xf bank_mask:0xf bound_ctrl:1
	v_mov_b32_dpp v129, v127 row_shr:4 row_mask:0xf bank_mask:0xf bound_ctrl:1
	v_pk_fma_f32 v[126:127], v[136:137], v[128:129], v[126:127]
	v_add_f32_e32 v87, 1.0, v87
	v_pk_mul_f32 v[92:93], v[140:141], v[150:151]
	v_mov_b32_dpp v128, v126 row_shr:8 row_mask:0xf bank_mask:0xf bound_ctrl:1
	v_mov_b32_dpp v129, v127 row_shr:8 row_mask:0xf bank_mask:0xf bound_ctrl:1
	v_pk_fma_f32 v[126:127], v[138:139], v[128:129], v[126:127]
	v_rcp_f32_e32 v128, v86
	v_mul_f32_e32 v86, 0xc1000000, v94
	v_rcp_f32_e32 v129, v87
	v_mul_f32_e32 v87, 0xc1000000, v95
	v_mul_f32_e32 v86, v2, v86
	v_mul_f32_e32 v87, v148, v87
	v_mul_f32_e32 v86, 0x3fb8aa3b, v86
	v_mul_f32_e32 v87, 0x3fb8aa3b, v87
	v_exp_f32_e32 v94, v86
	v_exp_f32_e32 v95, v87
	v_pk_fma_f32 v[126:127], v[140:141], v[124:125], v[126:127]
	ds_bpermute_b32 v84, v1, v92
	v_fma_f32 v86, -v94, v94, 1.0
	v_fma_f32 v87, -v95, v95, 1.0
	v_sqrt_f32_e32 v130, v86
	v_mov_b32_e32 v86, 1.0
	v_sqrt_f32_e32 v131, v87
	v_mov_b32_e32 v87, 1.0
	v_mov_b32_dpp v86, v94 row_shr:1 row_mask:0xf bank_mask:0xf
	ds_bpermute_b32 v124, v1, v126
	v_mov_b32_dpp v87, v95 row_shr:1 row_mask:0xf bank_mask:0xf
	v_pk_mul_f32 v[134:135], v[94:95], v[86:87]
	v_mov_b32_e32 v86, 1.0
	v_mov_b32_e32 v87, 1.0
	ds_bpermute_b32 v125, v1, v127
	v_mov_b32_dpp v86, v134 row_shr:2 row_mask:0xf bank_mask:0xf
	v_mov_b32_dpp v87, v135 row_shr:2 row_mask:0xf bank_mask:0xf
	v_pk_mul_f32 v[136:137], v[134:135], v[86:87]
	v_mov_b32_e32 v86, 1.0
	v_mov_b32_e32 v87, 1.0
	ds_bpermute_b32 v85, v1, v93
	v_mov_b32_dpp v86, v136 row_shr:4 row_mask:0xf bank_mask:0xf
	v_mov_b32_dpp v87, v137 row_shr:4 row_mask:0xf bank_mask:0xf
	v_pk_mul_f32 v[138:139], v[136:137], v[86:87]
	v_mov_b32_e32 v86, 1.0
	v_mov_b32_e32 v87, 1.0
	v_cvt_pk_bf16_f32 v126, v126, v127
	v_mov_b32_dpp v86, v138 row_shr:8 row_mask:0xf bank_mask:0xf
	v_mov_b32_dpp v87, v139 row_shr:8 row_mask:0xf bank_mask:0xf
	v_pk_mul_f32 v[140:141], v[138:139], v[86:87]
	v_add_u32_e32 v87, 0x1088, v145
	ds_read2_b32 v[142:143], v87 offset1:1
	v_pk_mul_f32 v[132:133], v[140:141], v[132:133]
	v_cvt_pk_bf16_f32 v92, v92, v93
	v_cvt_pk_bf16_f32 v93, v132, v133
	ds_bpermute_b32 v86, v1, v132
	s_waitcnt lgkmcnt(0)
	v_pk_mul_f32 v[128:129], v[128:129], v[142:143]
	ds_bpermute_b32 v87, v1, v133
	v_pk_mul_f32 v[128:129], v[130:131], v[128:129]
	s_nop 1
	v_mov_b32_dpp v130, v128 row_shr:1 row_mask:0xf bank_mask:0xf bound_ctrl:1
	v_mov_b32_dpp v131, v129 row_shr:1 row_mask:0xf bank_mask:0xf bound_ctrl:1
	v_pk_fma_f32 v[94:95], v[94:95], v[130:131], v[128:129]
	s_nop 1
	v_mov_b32_dpp v128, v94 row_shr:2 row_mask:0xf bank_mask:0xf bound_ctrl:1
	v_mov_b32_dpp v129, v95 row_shr:2 row_mask:0xf bank_mask:0xf bound_ctrl:1
	v_pk_fma_f32 v[94:95], v[134:135], v[128:129], v[94:95]
	s_nop 1
	v_mov_b32_dpp v128, v94 row_shr:4 row_mask:0xf bank_mask:0xf bound_ctrl:1
	v_mov_b32_dpp v129, v95 row_shr:4 row_mask:0xf bank_mask:0xf bound_ctrl:1
	v_pk_fma_f32 v[94:95], v[136:137], v[128:129], v[94:95]
	s_nop 1
	v_mov_b32_dpp v128, v94 row_shr:8 row_mask:0xf bank_mask:0xf bound_ctrl:1
	v_mov_b32_dpp v129, v95 row_shr:8 row_mask:0xf bank_mask:0xf bound_ctrl:1
	v_pk_fma_f32 v[94:95], v[138:139], v[128:129], v[94:95]
	s_nop 0
	v_pk_fma_f32 v[94:95], v[140:141], v[122:123], v[94:95]
	ds_bpermute_b32 v122, v1, v94
	v_cvt_pk_bf16_f32 v127, v94, v95
	ds_bpermute_b32 v123, v1, v95
	v_mov_b64_e32 v[232:233], v[126:127]
	s_nop 1
	v_permlane16_swap_b32_e32 v230, v232
	v_permlane16_swap_b32_e32 v231, v233
	global_store_dwordx4 v[104:105], v[230:233], off
	v_mov_b64_e32 v[236:237], v[92:93]
	s_nop 1
	v_permlane16_swap_b32_e32 v234, v236
	v_permlane16_swap_b32_e32 v235, v237
	global_store_dwordx4 v[106:107], v[234:237], off
	v_mfma_f32_16x16x32_bf16 v[92:95], v[68:71], v[8:11], 0
	v_mfma_f32_16x16x32_bf16 v[130:133], v[76:79], v[24:27], v[92:95]
	v_mfma_f32_16x16x32_bf16 v[126:129], v[72:75], v[8:11], 0
	v_mfma_f32_16x16x32_bf16 v[134:137], v[80:83], v[24:27], v[126:129]
	s_nop 5
	v_add_f32_e32 v92, v40, v130
	v_mul_f32_e32 v92, 0xbfb8aa3b, v92
	v_exp_f32_e32 v92, v92
	v_mov_b32_e32 v126, 1.0
	v_mfma_f32_16x16x32_bf16 v[68:71], v[68:71], v[4:7], 0
	v_add_f32_e32 v92, 1.0, v92
	v_rcp_f32_e32 v93, v92
	v_add_f32_e32 v92, v36, v134
	v_mul_f32_e32 v92, 0xbfb8aa3b, v92
	v_exp_f32_e32 v92, v92
	v_mul_f32_e32 v93, 0xc1000000, v93
	v_mul_f32_e32 v93, v147, v93
	v_mul_f32_e32 v93, 0x3fb8aa3b, v93
	v_exp_f32_e32 v94, v93
	v_add_f32_e32 v92, 1.0, v92
	v_rcp_f32_e32 v92, v92
	v_fma_f32 v93, -v94, v94, 1.0
	v_sqrt_f32_e32 v130, v93
	v_add_f32_e32 v93, v41, v131
	v_mul_f32_e32 v93, 0xbfb8aa3b, v93
	v_exp_f32_e32 v93, v93
	v_mov_b32_dpp v126, v94 row_shr:1 row_mask:0xf bank_mask:0xf
	v_add_f32_e32 v93, 1.0, v93
	v_rcp_f32_e32 v95, v93
	v_add_f32_e32 v93, v37, v135
	v_mul_f32_e32 v93, 0xbfb8aa3b, v93
	v_exp_f32_e32 v93, v93
	v_mul_f32_e32 v95, 0xc1000000, v95
	v_mul_f32_e32 v95, v149, v95
	v_mul_f32_e32 v95, 0x3fb8aa3b, v95
	v_exp_f32_e32 v95, v95
	v_add_f32_e32 v93, 1.0, v93
	v_rcp_f32_e32 v93, v93
	v_fma_f32 v127, -v95, v95, 1.0
	v_sqrt_f32_e32 v131, v127
	v_mov_b32_e32 v127, 1.0
	s_nop 1
	v_mov_b32_dpp v127, v95 row_shr:1 row_mask:0xf bank_mask:0xf
	v_pk_mul_f32 v[134:135], v[94:95], v[126:127]
	v_mov_b32_e32 v126, 1.0
	v_mov_b32_e32 v127, 1.0
	s_nop 0
	v_mov_b32_dpp v126, v134 row_shr:2 row_mask:0xf bank_mask:0xf
	v_mov_b32_dpp v127, v135 row_shr:2 row_mask:0xf bank_mask:0xf
	v_pk_mul_f32 v[138:139], v[134:135], v[126:127]
	v_mov_b32_e32 v126, 1.0
	v_mov_b32_e32 v127, 1.0
	s_nop 0
	v_mov_b32_dpp v126, v138 row_shr:4 row_mask:0xf bank_mask:0xf
	v_mov_b32_dpp v127, v139 row_shr:4 row_mask:0xf bank_mask:0xf
	v_pk_mul_f32 v[140:141], v[138:139], v[126:127]
	v_mov_b32_e32 v126, 1.0
	v_mov_b32_e32 v127, 1.0
	s_nop 0
	v_mov_b32_dpp v126, v140 row_shr:8 row_mask:0xf bank_mask:0xf
	v_mov_b32_dpp v127, v141 row_shr:8 row_mask:0xf bank_mask:0xf
	v_pk_mul_f32 v[142:143], v[140:141], v[126:127]
	s_nop 0
	v_pk_mul_f32 v[128:129], v[142:143], v[84:85]
	v_add_u32_e32 v84, 0x20c0, v145
	ds_read2_b32 v[84:85], v84 offset1:1
	ds_bpermute_b32 v126, v1, v128
	ds_bpermute_b32 v127, v1, v129
	s_waitcnt lgkmcnt(0)
; __device__ __forceinline__ unsigned pk2(float lo, float hi) { const f32x2_t v = {lo, hi}; const bf16x2_t b = __builtin_convertvector(v, bf16x2_t); return __builtin_bit_cast(unsigned, b); }
; __device__ __forceinline__ float sigmoidf_(float x) { return __builtin_amdgcn_rcpf(1.0f + __expf(-x)); }
; __device__ __forceinline__ float bcast15(float v, int lane) { return bperm_f((lane & 48) | 15, v); }
; __device__ __forceinline__ void w_lru_m1(const Args& a, int l, unsigned char* ws, const bf16_t* proj, bf16_t* y, LAS unsigned char* wl, int b, int ck_, int h, int lane) {
;     ...
;         for (int tb = 0; tb < 4; ++tb) { const int tok = 16 * tb + lo;
;             f32x4 ga = {0.f, 0.f, 0.f, 0.f}, gx = {0.f, 0.f, 0.f, 0.f};
; #pragma unroll
;             for (int kk = 0; kk < 2; ++kk) { ga = __builtin_amdgcn_mfma_f32_16x16x32_bf16(WaF[kk], Xf[tb][kk], ga, 0, 0, 0); gx = __builtin_amdgcn_mfma_f32_16x16x32_bf16(WxF[kk], Xf[tb][kk], gx, 0, 0, 0); }
;             float hv[4], pv[4];
; #pragma unroll
;             for (int r = 0; r < 4; ++r) {
;                 const float rg = sigmoidf_(ga[r] + bav[r]), ig = sigmoidf_(gx[r] + bxv[r]);
;                 const float la = -8.0f * rg * sp[r]; float A = __expf(la);
;                 float U = __builtin_amdgcn_sqrtf(1.0f - A * A) * (ig * xcf[tok * 65 + j0 + r]);
;                 { const float As = dpp_shr1<1>(A), Us = dpp_shr0<1>(U); U = A * Us + U; A = A * As; }
;                 { const float As = dpp_shr1<2>(A), Us = dpp_shr0<2>(U); U = A * Us + U; A = A * As; }
;                 { const float As = dpp_shr1<4>(A), Us = dpp_shr0<4>(U); U = A * Us + U; A = A * As; }
;                 { const float As = dpp_shr1<8>(A), Us = dpp_shr0<8>(U); U = A * Us + U; A = A * As; }
;                 const float hh = U + A * hc[r], PP = A * Pc[r];
;                 hc[r] = bcast15(hh, lane); Pc[r] = bcast15(PP, lane); hv[r] = hh; pv[r] = PP; }
;             *(unsigned long long*)(y + (size_t)(row0 + tok) * DM + 64 * h + j0) = (unsigned long long)pk2(hv[0], hv[1]) | ((unsigned long long)pk2(hv[2], hv[3]) << 32);
;             *(unsigned long long*)((bf16_t*)(ws + WS_P) + (size_t)(row0 + tok) * 512 + 64 * h + j0) = (unsigned long long)pk2(pv[0], pv[1]) | ((unsigned long long)pk2(pv[2], pv[3]) << 32);
	v_pk_mul_f32 v[84:85], v[84:85], v[92:93]
	s_nop 0
	v_pk_mul_f32 v[84:85], v[84:85], v[130:131]
	s_nop 1
	v_mov_b32_dpp v92, v84 row_shr:1 row_mask:0xf bank_mask:0xf bound_ctrl:1
	v_mov_b32_dpp v93, v85 row_shr:1 row_mask:0xf bank_mask:0xf bound_ctrl:1
	v_pk_fma_f32 v[84:85], v[94:95], v[92:93], v[84:85]
	s_nop 1
	v_mov_b32_dpp v92, v84 row_shr:2 row_mask:0xf bank_mask:0xf bound_ctrl:1
	v_mov_b32_dpp v93, v85 row_shr:2 row_mask:0xf bank_mask:0xf bound_ctrl:1
	v_pk_fma_f32 v[84:85], v[134:135], v[92:93], v[84:85]
	s_nop 1
	v_mov_b32_dpp v92, v84 row_shr:4 row_mask:0xf bank_mask:0xf bound_ctrl:1
	v_mov_b32_dpp v93, v85 row_shr:4 row_mask:0xf bank_mask:0xf bound_ctrl:1
	v_pk_fma_f32 v[84:85], v[138:139], v[92:93], v[84:85]
	s_nop 1
	v_mov_b32_dpp v92, v84 row_shr:8 row_mask:0xf bank_mask:0xf bound_ctrl:1
	v_mov_b32_dpp v93, v85 row_shr:8 row_mask:0xf bank_mask:0xf bound_ctrl:1
	v_pk_fma_f32 v[84:85], v[140:141], v[92:93], v[84:85]
	v_mov_b32_e32 v92, 1.0
	v_pk_fma_f32 v[124:125], v[142:143], v[124:125], v[84:85]
	v_add_f32_e32 v84, v42, v132
	v_mul_f32_e32 v84, 0xbfb8aa3b, v84
	v_exp_f32_e32 v84, v84
	ds_bpermute_b32 v94, v1, v124
	ds_bpermute_b32 v95, v1, v125
	v_cvt_pk_bf16_f32 v124, v124, v125
	v_add_f32_e32 v84, 1.0, v84
	v_rcp_f32_e32 v85, v84
	v_add_f32_e32 v84, v38, v136
	v_mul_f32_e32 v84, 0xbfb8aa3b, v84
	v_exp_f32_e32 v84, v84
	v_mul_f32_e32 v85, 0xc1000000, v85
	v_mul_f32_e32 v85, v2, v85
	v_mul_f32_e32 v85, 0x3fb8aa3b, v85
	v_exp_f32_e32 v130, v85
	v_add_f32_e32 v84, 1.0, v84
	v_rcp_f32_e32 v84, v84
	v_fma_f32 v85, -v130, v130, 1.0
	v_sqrt_f32_e32 v132, v85
	v_add_f32_e32 v85, v43, v133
	v_mul_f32_e32 v85, 0xbfb8aa3b, v85
	v_exp_f32_e32 v85, v85
	v_mov_b32_dpp v92, v130 row_shr:1 row_mask:0xf bank_mask:0xf
	v_add_f32_e32 v85, 1.0, v85
	v_rcp_f32_e32 v93, v85
	v_add_f32_e32 v85, v39, v137
	v_mul_f32_e32 v85, 0xbfb8aa3b, v85
	v_exp_f32_e32 v85, v85
	v_mul_f32_e32 v93, 0xc1000000, v93
	v_mul_f32_e32 v93, v148, v93
	v_mul_f32_e32 v93, 0x3fb8aa3b, v93
	v_exp_f32_e32 v131, v93
	v_add_f32_e32 v85, 1.0, v85
	v_rcp_f32_e32 v85, v85
	v_fma_f32 v93, -v131, v131, 1.0
	v_sqrt_f32_e32 v133, v93
	v_mov_b32_e32 v93, 1.0
	s_nop 1
	v_mov_b32_dpp v93, v131 row_shr:1 row_mask:0xf bank_mask:0xf
	v_pk_mul_f32 v[134:135], v[130:131], v[92:93]
	v_mov_b32_e32 v92, 1.0
	v_mov_b32_e32 v93, 1.0
	s_nop 0
	v_mov_b32_dpp v92, v134 row_shr:2 row_mask:0xf bank_mask:0xf
	v_mov_b32_dpp v93, v135 row_shr:2 row_mask:0xf bank_mask:0xf
	v_pk_mul_f32 v[136:137], v[134:135], v[92:93]
	v_mov_b32_e32 v92, 1.0
	v_mov_b32_e32 v93, 1.0
	s_nop 0
	v_mov_b32_dpp v92, v136 row_shr:4 row_mask:0xf bank_mask:0xf
	v_mov_b32_dpp v93, v137 row_shr:4 row_mask:0xf bank_mask:0xf
	v_pk_mul_f32 v[138:139], v[136:137], v[92:93]
	v_mov_b32_e32 v92, 1.0
	v_mov_b32_e32 v93, 1.0
	s_nop 0
	v_mov_b32_dpp v92, v138 row_shr:8 row_mask:0xf bank_mask:0xf
	v_mov_b32_dpp v93, v139 row_shr:8 row_mask:0xf bank_mask:0xf
	v_pk_mul_f32 v[140:141], v[138:139], v[92:93]
	v_add_u32_e32 v93, 0x20c8, v145
	ds_read2_b32 v[142:143], v93 offset1:1
	v_pk_mul_f32 v[86:87], v[140:141], v[86:87]
	ds_bpermute_b32 v92, v1, v86
	ds_bpermute_b32 v93, v1, v87
	s_waitcnt lgkmcnt(0)
	v_pk_mul_f32 v[84:85], v[84:85], v[142:143]
	s_nop 0
	v_pk_mul_f32 v[84:85], v[132:133], v[84:85]
	s_nop 1
	v_mov_b32_dpp v132, v84 row_shr:1 row_mask:0xf bank_mask:0xf bound_ctrl:1
	v_mov_b32_dpp v133, v85 row_shr:1 row_mask:0xf bank_mask:0xf bound_ctrl:1
	v_pk_fma_f32 v[84:85], v[130:131], v[132:133], v[84:85]
	s_nop 1
	v_mov_b32_dpp v130, v84 row_shr:2 row_mask:0xf bank_mask:0xf bound_ctrl:1
	v_mov_b32_dpp v131, v85 row_shr:2 row_mask:0xf bank_mask:0xf bound_ctrl:1
	v_pk_fma_f32 v[84:85], v[134:135], v[130:131], v[84:85]
	s_nop 1
	v_mov_b32_dpp v130, v84 row_shr:4 row_mask:0xf bank_mask:0xf bound_ctrl:1
	v_mov_b32_dpp v131, v85 row_shr:4 row_mask:0xf bank_mask:0xf bound_ctrl:1
	v_pk_fma_f32 v[84:85], v[136:137], v[130:131], v[84:85]
	s_nop 1
	v_mov_b32_dpp v130, v84 row_shr:8 row_mask:0xf bank_mask:0xf bound_ctrl:1
	v_mov_b32_dpp v131, v85 row_shr:8 row_mask:0xf bank_mask:0xf bound_ctrl:1
	v_pk_fma_f32 v[84:85], v[138:139], v[130:131], v[84:85]
	s_nop 0
	v_pk_fma_f32 v[122:123], v[140:141], v[122:123], v[84:85]
	ds_bpermute_b32 v84, v1, v122
	ds_bpermute_b32 v85, v1, v123
	v_cvt_pk_bf16_f32 v125, v122, v123
	v_cvt_pk_bf16_f32 v122, v128, v129
	v_cvt_pk_bf16_f32 v123, v86, v87
	v_mov_b64_e32 v[240:241], v[124:125]
	s_nop 1
	v_permlane16_swap_b32_e32 v238, v240
	v_permlane16_swap_b32_e32 v239, v241
	global_store_dwordx4 v[96:97], v[238:241], off
	v_mov_b64_e32 v[244:245], v[122:123]
	s_nop 1
	v_permlane16_swap_b32_e32 v242, v244
	v_permlane16_swap_b32_e32 v243, v245
	global_store_dwordx4 v[98:99], v[242:245], off
	v_mfma_f32_16x16x32_bf16 v[122:125], v[72:75], v[4:7], 0
	v_mfma_f32_16x16x32_bf16 v[72:75], v[76:79], v[20:23], v[68:71]
	v_mfma_f32_16x16x32_bf16 v[68:71], v[80:83], v[20:23], v[122:125]
	s_nop 6
	v_add_f32_e32 v40, v40, v72
	v_add_f32_e32 v41, v41, v73
	v_add_f32_e32 v42, v42, v74
	v_mul_f32_e32 v40, 0xbfb8aa3b, v40
	v_mul_f32_e32 v41, 0xbfb8aa3b, v41
	v_mul_f32_e32 v42, 0xbfb8aa3b, v42
	v_exp_f32_e32 v40, v40
	v_exp_f32_e32 v41, v41
	v_exp_f32_e32 v42, v42
	v_add_f32_e32 v36, v36, v68
	v_add_f32_e32 v37, v37, v69
	v_add_f32_e32 v38, v38, v70
	v_mul_f32_e32 v36, 0xbfb8aa3b, v36
	v_mul_f32_e32 v37, 0xbfb8aa3b, v37
	v_mul_f32_e32 v38, 0xbfb8aa3b, v38
	v_add_f32_e32 v40, 1.0, v40
	v_exp_f32_e32 v36, v36
	v_add_f32_e32 v41, 1.0, v41
	v_exp_f32_e32 v37, v37
	v_add_f32_e32 v42, 1.0, v42
	v_exp_f32_e32 v38, v38
	v_rcp_f32_e32 v72, v40
	v_rcp_f32_e32 v68, v41
	v_rcp_f32_e32 v42, v42
	v_add_f32_e32 v36, 1.0, v36
	v_add_f32_e32 v37, 1.0, v37
; __device__ __forceinline__ unsigned pk2(float lo, float hi) { const f32x2_t v = {lo, hi}; const bf16x2_t b = __builtin_convertvector(v, bf16x2_t); return __builtin_bit_cast(unsigned, b); }
; __device__ __forceinline__ float sigmoidf_(float x) { return __builtin_amdgcn_rcpf(1.0f + __expf(-x)); }
; __device__ __forceinline__ void w_lru_m1(const Args& a, int l, unsigned char* ws, const bf16_t* proj, bf16_t* y, LAS unsigned char* wl, int b, int ck_, int h, int lane) {
;     ...
;         for (int tb = 0; tb < 4; ++tb) { const int tok = 16 * tb + lo;
;             f32x4 ga = {0.f, 0.f, 0.f, 0.f}, gx = {0.f, 0.f, 0.f, 0.f};
; #pragma unroll
;             for (int kk = 0; kk < 2; ++kk) { ga = __builtin_amdgcn_mfma_f32_16x16x32_bf16(WaF[kk], Xf[tb][kk], ga, 0, 0, 0); gx = __builtin_amdgcn_mfma_f32_16x16x32_bf16(WxF[kk], Xf[tb][kk], gx, 0, 0, 0); }
;             float hv[4], pv[4];
; #pragma unroll
;             for (int r = 0; r < 4; ++r) {
;                 const float rg = sigmoidf_(ga[r] + bav[r]), ig = sigmoidf_(gx[r] + bxv[r]);
;                 const float la = -8.0f * rg * sp[r]; float A = __expf(la);
;                 float U = __builtin_amdgcn_sqrtf(1.0f - A * A) * (ig * xcf[tok * 65 + j0 + r]);
;                 { const float As = dpp_shr1<1>(A), Us = dpp_shr0<1>(U); U = A * Us + U; A = A * As; }
;                 { const float As = dpp_shr1<2>(A), Us = dpp_shr0<2>(U); U = A * Us + U; A = A * As; }
;                 { const float As = dpp_shr1<4>(A), Us = dpp_shr0<4>(U); U = A * Us + U; A = A * As; }
;                 { const float As = dpp_shr1<8>(A), Us = dpp_shr0<8>(U); U = A * Us + U; A = A * As; }
;                 const float hh = U + A * hc[r], PP = A * Pc[r];
;                 hc[r] = bcast15(hh, lane); Pc[r] = bcast15(PP, lane); hv[r] = hh; pv[r] = PP; }
;             *(unsigned long long*)(y + (size_t)(row0 + tok) * DM + 64 * h + j0) = (unsigned long long)pk2(hv[0], hv[1]) | ((unsigned long long)pk2(hv[2], hv[3]) << 32);
;             *(unsigned long long*)((bf16_t*)(ws + WS_P) + (size_t)(row0 + tok) * 512 + 64 * h + j0) = (unsigned long long)pk2(pv[0], pv[1]) | ((unsigned long long)pk2(pv[2], pv[3]) << 32);
;         }
;         if (lo == 0) { const size_t so = (size_t)(b * NCH + ck_) * 512 + 64 * h + j0;
; #pragma unroll
;             for (int r = 0; r < 4; ++r) { ((float*)(ws + WS_LRUA))[so + r] = Pc[r]; ((float*)(ws + WS_LRUH))[so + r] = hc[r]; } }
	v_add_f32_e32 v38, 1.0, v38
	v_rcp_f32_e32 v40, v36
	v_mul_f32_e32 v36, 0xc1000000, v72
	v_rcp_f32_e32 v41, v37
	v_mul_f32_e32 v37, 0xc1000000, v68
	v_rcp_f32_e32 v70, v38
	v_mul_f32_e32 v38, 0xc1000000, v42
	v_mul_f32_e32 v36, v147, v36
	v_mul_f32_e32 v37, v149, v37
	v_mul_f32_e32 v2, v2, v38
	v_mul_f32_e32 v36, 0x3fb8aa3b, v36
	v_mul_f32_e32 v37, 0x3fb8aa3b, v37
	v_mul_f32_e32 v2, 0x3fb8aa3b, v2
	v_exp_f32_e32 v72, v36
	v_exp_f32_e32 v73, v37
	v_exp_f32_e32 v42, v2
	v_add_f32_e32 v39, v39, v71
	v_fma_f32 v36, -v72, v72, 1.0
	v_fma_f32 v37, -v73, v73, 1.0
	v_fma_f32 v2, -v42, v42, 1.0
	v_sqrt_f32_e32 v76, v36
	v_mov_b32_e32 v36, 1.0
	v_sqrt_f32_e32 v77, v37
	v_mov_b32_e32 v37, 1.0
	v_sqrt_f32_e32 v74, v2
	v_add_f32_e32 v2, v43, v75
	v_mov_b32_dpp v36, v72 row_shr:1 row_mask:0xf bank_mask:0xf
	v_mov_b32_dpp v37, v73 row_shr:1 row_mask:0xf bank_mask:0xf
	v_mul_f32_e32 v2, 0xbfb8aa3b, v2
	v_pk_mul_f32 v[78:79], v[72:73], v[36:37]
	v_mov_b32_e32 v36, 1.0
	v_mov_b32_e32 v37, 1.0
	v_exp_f32_e32 v2, v2
	v_mov_b32_dpp v36, v78 row_shr:2 row_mask:0xf bank_mask:0xf
	v_mov_b32_dpp v37, v79 row_shr:2 row_mask:0xf bank_mask:0xf
	v_pk_mul_f32 v[80:81], v[78:79], v[36:37]
	v_mov_b32_e32 v36, 1.0
	v_mov_b32_e32 v37, 1.0
	v_add_f32_e32 v2, 1.0, v2
	v_mov_b32_dpp v36, v80 row_shr:4 row_mask:0xf bank_mask:0xf
	v_mov_b32_dpp v37, v81 row_shr:4 row_mask:0xf bank_mask:0xf
	v_pk_mul_f32 v[82:83], v[80:81], v[36:37]
	v_mov_b32_e32 v36, 1.0
	v_mov_b32_e32 v37, 1.0
	v_rcp_f32_e32 v2, v2
	v_mov_b32_dpp v36, v82 row_shr:8 row_mask:0xf bank_mask:0xf
	v_mov_b32_dpp v37, v83 row_shr:8 row_mask:0xf bank_mask:0xf
	v_pk_mul_f32 v[86:87], v[82:83], v[36:37]
	v_add_u32_e32 v37, 0x3100, v145
	ds_read2_b32 v[122:123], v37 offset1:1
	v_mul_f32_e32 v39, 0xbfb8aa3b, v39
	v_mul_f32_e32 v2, 0xc1000000, v2
	v_exp_f32_e32 v39, v39
	v_mul_f32_e32 v2, v148, v2
	v_mul_f32_e32 v2, 0x3fb8aa3b, v2
	s_waitcnt lgkmcnt(0)
	v_pk_mul_f32 v[40:41], v[122:123], v[40:41]
	v_exp_f32_e32 v43, v2
	v_pk_mul_f32 v[40:41], v[40:41], v[76:77]
	v_add_f32_e32 v39, 1.0, v39
	v_mov_b32_e32 v38, 1.0
	v_mov_b32_dpp v76, v40 row_shr:1 row_mask:0xf bank_mask:0xf bound_ctrl:1
	v_mov_b32_dpp v77, v41 row_shr:1 row_mask:0xf bank_mask:0xf bound_ctrl:1
	v_pk_fma_f32 v[40:41], v[72:73], v[76:77], v[40:41]
	v_rcp_f32_e32 v71, v39
	v_mov_b32_e32 v39, 1.0
	v_mov_b32_dpp v72, v40 row_shr:2 row_mask:0xf bank_mask:0xf bound_ctrl:1
	v_mov_b32_dpp v73, v41 row_shr:2 row_mask:0xf bank_mask:0xf bound_ctrl:1
	v_mov_b32_dpp v38, v42 row_shr:1 row_mask:0xf bank_mask:0xf
	v_mov_b32_dpp v39, v43 row_shr:1 row_mask:0xf bank_mask:0xf
	v_pk_fma_f32 v[40:41], v[78:79], v[72:73], v[40:41]
	v_pk_mul_f32 v[78:79], v[42:43], v[38:39]
	v_mov_b32_e32 v38, 1.0
	v_mov_b32_e32 v39, 1.0
	v_mov_b32_dpp v72, v40 row_shr:4 row_mask:0xf bank_mask:0xf bound_ctrl:1
	v_mov_b32_dpp v73, v41 row_shr:4 row_mask:0xf bank_mask:0xf bound_ctrl:1
	v_mov_b32_dpp v38, v78 row_shr:2 row_mask:0xf bank_mask:0xf
	v_mov_b32_dpp v39, v79 row_shr:2 row_mask:0xf bank_mask:0xf
	v_pk_fma_f32 v[40:41], v[80:81], v[72:73], v[40:41]
	v_pk_mul_f32 v[80:81], v[78:79], v[38:39]
	v_mov_b32_e32 v38, 1.0
	v_mov_b32_e32 v39, 1.0
	v_mov_b32_dpp v72, v40 row_shr:8 row_mask:0xf bank_mask:0xf bound_ctrl:1
	v_mov_b32_dpp v73, v41 row_shr:8 row_mask:0xf bank_mask:0xf bound_ctrl:1
	v_mov_b32_dpp v38, v80 row_shr:4 row_mask:0xf bank_mask:0xf
	v_mov_b32_dpp v39, v81 row_shr:4 row_mask:0xf bank_mask:0xf
	v_pk_fma_f32 v[40:41], v[82:83], v[72:73], v[40:41]
	v_pk_mul_f32 v[82:83], v[80:81], v[38:39]
	v_mov_b32_e32 v38, 1.0
	v_mov_b32_e32 v39, 1.0
	v_fma_f32 v2, -v43, v43, 1.0
	v_mov_b32_dpp v38, v82 row_shr:8 row_mask:0xf bank_mask:0xf
	v_mov_b32_dpp v39, v83 row_shr:8 row_mask:0xf bank_mask:0xf
	v_pk_mul_f32 v[68:69], v[86:87], v[126:127]
	v_pk_fma_f32 v[72:73], v[86:87], v[94:95], v[40:41]
	v_sqrt_f32_e32 v75, v2
	v_pk_mul_f32 v[86:87], v[82:83], v[38:39]
	v_add_u32_e32 v2, 0x3108, v145
	v_pk_mul_f32 v[76:77], v[86:87], v[92:93]
	ds_read2_b32 v[92:93], v2 offset1:1
	ds_bpermute_b32 v36, v1, v68
	ds_bpermute_b32 v40, v1, v72
	ds_bpermute_b32 v41, v1, v73
	ds_bpermute_b32 v37, v1, v69
	s_waitcnt lgkmcnt(0)
	v_pk_mul_f32 v[70:71], v[70:71], v[92:93]
	ds_bpermute_b32 v38, v1, v76
	v_pk_mul_f32 v[70:71], v[74:75], v[70:71]
	ds_bpermute_b32 v39, v1, v77
	v_cvt_pk_bf16_f32 v72, v72, v73
	v_mov_b32_dpp v74, v70 row_shr:1 row_mask:0xf bank_mask:0xf bound_ctrl:1
	v_mov_b32_dpp v75, v71 row_shr:1 row_mask:0xf bank_mask:0xf bound_ctrl:1
	v_pk_fma_f32 v[42:43], v[42:43], v[74:75], v[70:71]
	v_cvt_pk_bf16_f32 v68, v68, v69
	v_cvt_pk_bf16_f32 v69, v76, v77
	v_mov_b32_dpp v70, v42 row_shr:2 row_mask:0xf bank_mask:0xf bound_ctrl:1
	v_mov_b32_dpp v71, v43 row_shr:2 row_mask:0xf bank_mask:0xf bound_ctrl:1
	v_pk_fma_f32 v[42:43], v[78:79], v[70:71], v[42:43]
	s_nop 1
	v_mov_b32_dpp v70, v42 row_shr:4 row_mask:0xf bank_mask:0xf bound_ctrl:1
	v_mov_b32_dpp v71, v43 row_shr:4 row_mask:0xf bank_mask:0xf bound_ctrl:1
	v_pk_fma_f32 v[42:43], v[80:81], v[70:71], v[42:43]
	s_nop 1
	v_mov_b32_dpp v70, v42 row_shr:8 row_mask:0xf bank_mask:0xf bound_ctrl:1
	v_mov_b32_dpp v71, v43 row_shr:8 row_mask:0xf bank_mask:0xf bound_ctrl:1
	v_pk_fma_f32 v[42:43], v[82:83], v[70:71], v[42:43]
	s_nop 0
	v_pk_fma_f32 v[70:71], v[86:87], v[84:85], v[42:43]
	ds_bpermute_b32 v42, v1, v70
	ds_bpermute_b32 v43, v1, v71
	v_cvt_pk_bf16_f32 v73, v70, v71
	v_mov_b64_e32 v[248:249], v[72:73]
	s_nop 1
	v_permlane16_swap_b32_e32 v246, v248
	v_permlane16_swap_b32_e32 v247, v249
	global_store_dwordx4 v[114:115], v[246:249], off
	v_mov_b64_e32 v[252:253], v[68:69]
	s_nop 1
	v_permlane16_swap_b32_e32 v250, v252
	v_permlane16_swap_b32_e32 v251, v253
	global_store_dwordx4 v[116:117], v[250:253], off
	s_and_saveexec_b64 s[34:35], vcc
	s_cbranch_execz .LBB0_525
	v_add_u32_e32 v68, 16, v0
	v_ashrrev_i32_e32 v69, 31, v68
	v_lshl_add_u64 v[68:69], s[42:43], 0, v[68:69]
	v_lshlrev_b64 v[68:69], 2, v[68:69]
	v_lshl_add_u64 v[70:71], s[84:85], 0, v[68:69]
	v_lshl_add_u64 v[68:69], s[86:87], 0, v[68:69]
	s_waitcnt lgkmcnt(0)
	global_store_dwordx4 v[70:71], v[36:39], off
	global_store_dwordx4 v[68:69], v[40:43], off
; __device__ __forceinline__ float sigmoidf_(float x) { return __builtin_amdgcn_rcpf(1.0f + __expf(-x)); }
; __device__ __forceinline__ void w_lru_m1(const Args& a, int l, unsigned char* ws, const bf16_t* proj, bf16_t* y, LAS unsigned char* wl, int b, int ck_, int h, int lane) {
;     ...
;     for (int jb = 0; jb < 4; ++jb) {
;         bf16x8 WaF[2], WxF[2]; f32x4 pba, pbx, plam;
; #pragma unroll
;         for (int kk = 0; kk < 2; ++kk) { WaF[kk] = nWa[kk]; WxF[kk] = nWx[kk]; }
;         pba = nba; pbx = nbx; plam = nlam;
;         if (jb < 3) {
; #pragma unroll
;             for (int kk = 0; kk < 2; ++kk) { nWa[kk] = *(const bf16x8*)(waT + (16 * (jb + 1) + lo) * 64 + 32 * kk + 8 * fq); nWx[kk] = *(const bf16x8*)(wxT + (16 * (jb + 1) + lo) * 64 + 32 * kk + 8 * fq); }
;             nba = *(const f32x4*)(ba + 16 * (jb + 1) + 4 * fq); nbx = *(const f32x4*)(bx + 16 * (jb + 1) + 4 * fq); nlam = *(const f32x4*)(lam + 16 * (jb + 1) + 4 * fq);
;         }
;         const int j0 = 16 * jb + 4 * fq;
;         float bav[4], bxv[4], sp[4], hc[4], Pc[4];
; #pragma unroll
;         for (int r = 0; r < 4; ++r) { bav[r] = pba[r]; bxv[r] = pbx[r]; sp[r] = log1pf(__expf(-plam[r])); hc[r] = 0.f; Pc[r] = 1.f; }
; #pragma unroll
;         for (int tb = 0; tb < 4; ++tb) { const int tok = 16 * tb + lo;
;             f32x4 ga = {0.f, 0.f, 0.f, 0.f}, gx = {0.f, 0.f, 0.f, 0.f};
; #pragma unroll
;             for (int kk = 0; kk < 2; ++kk) { ga = __builtin_amdgcn_mfma_f32_16x16x32_bf16(WaF[kk], Xf[tb][kk], ga, 0, 0, 0); gx = __builtin_amdgcn_mfma_f32_16x16x32_bf16(WxF[kk], Xf[tb][kk], gx, 0, 0, 0); }
;             float hv[4], pv[4];
; #pragma unroll
;             for (int r = 0; r < 4; ++r) {
;                 const float rg = sigmoidf_(ga[r] + bav[r]), ig = sigmoidf_(gx[r] + bxv[r]);
;                 const float la = -8.0f * rg * sp[r]; float A = __expf(la);
;                 float U = __builtin_amdgcn_sqrtf(1.0f - A * A) * (ig * xcf[tok * 65 + j0 + r]);
.LBB0_525:
	s_or_b64 exec, exec, s[34:35]
	v_lshl_or_b32 v2, v146, 1, v210
	v_lshl_add_u64 v[36:37], v[118:119], 0, v[2:3]
	s_waitcnt lgkmcnt(0)
	v_lshl_add_u64 v[38:39], v[120:121], 0, v[2:3]
	s_waitcnt vmcnt(10)
	s_nop 7
	global_load_dwordx4 v[68:71], v[36:37], off
	global_load_dwordx4 v[72:75], v[38:39], off
	global_load_dwordx4 v[76:79], v[36:37], off offset:64
	global_load_dwordx4 v[80:83], v[38:39], off offset:64
	global_load_dwordx4 v[40:43], v[108:109], off offset:192
	s_nop 0
	global_load_dwordx4 v[36:39], v[110:111], off offset:192
	global_load_dwordx4 v[84:87], v[112:113], off offset:192
	ds_read2_b32 v[124:125], v145 offset0:32 offset1:33
	ds_read2_b32 v[128:129], v145 offset0:34 offset1:35
	s_nop 7
	s_nop 0
	s_nop 7
	s_nop 0
	s_nop 7
	s_nop 0
	s_nop 7
	s_nop 1
	s_nop 7
	s_nop 1
	s_nop 7
	s_nop 1
	s_nop 7
	v_mov_b32_e32 v2, v88
	s_nop 7
	s_nop 0
	s_nop 7
	s_nop 0
	s_nop 7
	s_nop 0
	s_nop 7
	s_nop 0
	s_nop 7
	s_nop 0
	s_nop 7
	s_nop 0
	s_nop 7
	s_nop 1
	s_nop 7
	s_nop 1
	s_nop 7
	s_nop 1
	s_nop 7
	v_mov_b32_e32 v134, v89
	s_nop 7
	s_nop 0
	s_nop 7
	s_nop 0
	s_nop 7
	s_nop 0
	s_nop 7
	s_nop 0
	s_nop 7
	s_nop 0
	s_nop 7
	s_nop 0
	s_nop 7
	s_nop 1
	s_nop 7
	s_nop 1
	s_nop 7
	s_nop 1
	s_nop 7
	v_mov_b32_e32 v135, v90
	s_nop 7
	s_nop 0
	s_nop 7
	s_nop 0
	s_nop 7
	s_nop 0
	s_nop 7
	s_nop 0
	s_nop 7
	s_nop 0
	s_nop 7
	s_nop 0
	s_nop 7
	v_mfma_f32_16x16x32_bf16 v[92:95], v[60:63], v[16:19], 0
	s_nop 0
	s_nop 7
	v_mfma_f32_16x16x32_bf16 v[110:113], v[52:55], v[32:35], v[92:95]
	s_nop 0
	s_nop 7
	s_nop 1
	s_nop 7
	v_mov_b32_e32 v136, v91
	v_mfma_f32_16x16x32_bf16 v[88:91], v[64:67], v[16:19], 0
	s_nop 0
	v_add_f32_e32 v92, v44, v110
	v_add_f32_e32 v93, v45, v111
	v_mul_f32_e32 v92, 0xbfb8aa3b, v92
	v_mfma_f32_16x16x32_bf16 v[88:91], v[56:59], v[32:35], v[88:91]
	v_mul_f32_e32 v93, 0xbfb8aa3b, v93
	v_exp_f32_e32 v92, v92
	v_exp_f32_e32 v93, v93
	v_add_f32_e32 v92, 1.0, v92
	v_add_f32_e32 v93, 1.0, v93
	s_nop 2
	v_add_f32_e32 v88, v48, v88
	v_add_f32_e32 v89, v49, v89
	v_mul_f32_e32 v88, 0xbfb8aa3b, v88
	v_mul_f32_e32 v89, 0xbfb8aa3b, v89
	v_exp_f32_e32 v88, v88
	v_exp_f32_e32 v89, v89
	v_rcp_f32_e32 v92, v92
	v_rcp_f32_e32 v93, v93
	v_add_f32_e32 v88, 1.0, v88
	v_add_f32_e32 v89, 1.0, v89
	v_rcp_f32_e32 v88, v88
	v_rcp_f32_e32 v89, v89
	s_waitcnt lgkmcnt(0)
	v_pk_mul_f32 v[92:93], v[124:125], v[92:93]
	v_add_f32_e32 v90, v50, v90
	v_mul_f32_e32 v88, 0xc1000000, v88
	v_mul_f32_e32 v89, 0xc1000000, v89
	v_mul_f32_e32 v88, v2, v88
	v_mul_f32_e32 v89, v134, v89
	v_mul_f32_e32 v88, 0x3fb8aa3b, v88
	v_mul_f32_e32 v89, 0x3fb8aa3b, v89
	v_exp_f32_e32 v108, v88
	v_exp_f32_e32 v109, v89
	v_add_f32_e32 v91, v51, v91
	v_mul_f32_e32 v90, 0xbfb8aa3b, v90
	v_fma_f32 v88, -v108, v108, 1.0
	v_fma_f32 v89, -v109, v109, 1.0
	v_sqrt_f32_e32 v110, v88
	v_sqrt_f32_e32 v111, v89
	v_mov_b32_e32 v88, 1.0
	v_mov_b32_e32 v89, 1.0
	v_mul_f32_e32 v91, 0xbfb8aa3b, v91
	v_pk_mul_f32 v[92:93], v[92:93], v[110:111]
	v_mov_b32_dpp v88, v108 row_shr:1 row_mask:0xf bank_mask:0xf
	v_mov_b32_dpp v89, v109 row_shr:1 row_mask:0xf bank_mask:0xf
	v_mov_b32_dpp v110, v92 row_shr:1 row_mask:0xf bank_mask:0xf bound_ctrl:1
	v_mov_b32_dpp v111, v93 row_shr:1 row_mask:0xf bank_mask:0xf bound_ctrl:1
	v_pk_fma_f32 v[92:93], v[108:109], v[110:111], v[92:93]
	v_pk_mul_f32 v[118:119], v[108:109], v[88:89]
	v_mov_b32_e32 v88, 1.0
	v_mov_b32_e32 v89, 1.0
	v_mov_b32_dpp v108, v92 row_shr:2 row_mask:0xf bank_mask:0xf bound_ctrl:1
	v_mov_b32_dpp v109, v93 row_shr:2 row_mask:0xf bank_mask:0xf bound_ctrl:1
	v_exp_f32_e32 v90, v90
	v_exp_f32_e32 v91, v91
	v_mov_b32_dpp v88, v118 row_shr:2 row_mask:0xf bank_mask:0xf
	v_mov_b32_dpp v89, v119 row_shr:2 row_mask:0xf bank_mask:0xf
	v_pk_fma_f32 v[92:93], v[118:119], v[108:109], v[92:93]
	v_pk_mul_f32 v[120:121], v[118:119], v[88:89]
	v_mov_b32_e32 v88, 1.0
	v_mov_b32_e32 v89, 1.0
	v_mov_b32_dpp v108, v92 row_shr:4 row_mask:0xf bank_mask:0xf bound_ctrl:1
	v_mov_b32_dpp v109, v93 row_shr:4 row_mask:0xf bank_mask:0xf bound_ctrl:1
	v_mov_b32_dpp v88, v120 row_shr:4 row_mask:0xf bank_mask:0xf
	v_mov_b32_dpp v89, v121 row_shr:4 row_mask:0xf bank_mask:0xf
	v_pk_fma_f32 v[92:93], v[120:121], v[108:109], v[92:93]
	v_pk_mul_f32 v[122:123], v[120:121], v[88:89]
	v_add_f32_e32 v90, 1.0, v90
	v_mov_b32_dpp v108, v92 row_shr:8 row_mask:0xf bank_mask:0xf bound_ctrl:1
	v_mov_b32_dpp v109, v93 row_shr:8 row_mask:0xf bank_mask:0xf bound_ctrl:1
	v_add_f32_e32 v91, 1.0, v91
	v_pk_fma_f32 v[92:93], v[122:123], v[108:109], v[92:93]
	v_rcp_f32_e32 v90, v90
	v_add_f32_e32 v108, v46, v112
	v_rcp_f32_e32 v91, v91
	v_add_f32_e32 v109, v47, v113
	v_mul_f32_e32 v108, 0xbfb8aa3b, v108
	v_mul_f32_e32 v109, 0xbfb8aa3b, v109
	v_exp_f32_e32 v108, v108
	v_exp_f32_e32 v109, v109
	v_mul_f32_e32 v90, 0xc1000000, v90
	v_mul_f32_e32 v91, 0xc1000000, v91
	v_mul_f32_e32 v90, v135, v90
	v_mul_f32_e32 v91, v136, v91
	v_add_f32_e32 v108, 1.0, v108
	v_mul_f32_e32 v90, 0x3fb8aa3b, v90
	v_add_f32_e32 v109, 1.0, v109
	v_mul_f32_e32 v91, 0x3fb8aa3b, v91
	v_rcp_f32_e32 v112, v108
	v_exp_f32_e32 v108, v90
	v_rcp_f32_e32 v113, v109
	v_exp_f32_e32 v109, v91
	v_mov_b32_e32 v88, 1.0
	v_fma_f32 v90, -v108, v108, 1.0
	v_sqrt_f32_e32 v118, v90
	v_fma_f32 v91, -v109, v109, 1.0
	v_sqrt_f32_e32 v119, v91
	v_pk_mul_f32 v[112:113], v[112:113], v[128:129]
	v_mov_b32_e32 v89, 1.0
	v_mov_b32_e32 v90, 1.0
	v_mov_b32_e32 v91, 1.0
	v_pk_mul_f32 v[112:113], v[118:119], v[112:113]
	v_mov_b32_dpp v88, v122 row_shr:8 row_mask:0xf bank_mask:0xf
	v_mov_b32_dpp v89, v123 row_shr:8 row_mask:0xf bank_mask:0xf
	v_mov_b32_dpp v90, v108 row_shr:1 row_mask:0xf bank_mask:0xf
	v_mov_b32_dpp v91, v109 row_shr:1 row_mask:0xf bank_mask:0xf
; __device__ __forceinline__ unsigned pk2(float lo, float hi) { const f32x2_t v = {lo, hi}; const bf16x2_t b = __builtin_convertvector(v, bf16x2_t); return __builtin_bit_cast(unsigned, b); }
; __device__ __forceinline__ float sigmoidf_(float x) { return __builtin_amdgcn_rcpf(1.0f + __expf(-x)); }
; __device__ __forceinline__ float bcast15(float v, int lane) { return bperm_f((lane & 48) | 15, v); }
; __device__ __forceinline__ void w_lru_m1(const Args& a, int l, unsigned char* ws, const bf16_t* proj, bf16_t* y, LAS unsigned char* wl, int b, int ck_, int h, int lane) {
;     ...
;         for (int tb = 0; tb < 4; ++tb) { const int tok = 16 * tb + lo;
;             f32x4 ga = {0.f, 0.f, 0.f, 0.f}, gx = {0.f, 0.f, 0.f, 0.f};
; #pragma unroll
;             for (int kk = 0; kk < 2; ++kk) { ga = __builtin_amdgcn_mfma_f32_16x16x32_bf16(WaF[kk], Xf[tb][kk], ga, 0, 0, 0); gx = __builtin_amdgcn_mfma_f32_16x16x32_bf16(WxF[kk], Xf[tb][kk], gx, 0, 0, 0); }
;             float hv[4], pv[4];
; #pragma unroll
;             for (int r = 0; r < 4; ++r) {
;                 const float rg = sigmoidf_(ga[r] + bav[r]), ig = sigmoidf_(gx[r] + bxv[r]);
;                 const float la = -8.0f * rg * sp[r]; float A = __expf(la);
;                 float U = __builtin_amdgcn_sqrtf(1.0f - A * A) * (ig * xcf[tok * 65 + j0 + r]);
;                 { const float As = dpp_shr1<1>(A), Us = dpp_shr0<1>(U); U = A * Us + U; A = A * As; }
;                 { const float As = dpp_shr1<2>(A), Us = dpp_shr0<2>(U); U = A * Us + U; A = A * As; }
;                 { const float As = dpp_shr1<4>(A), Us = dpp_shr0<4>(U); U = A * Us + U; A = A * As; }
;                 { const float As = dpp_shr1<8>(A), Us = dpp_shr0<8>(U); U = A * Us + U; A = A * As; }
;                 const float hh = U + A * hc[r], PP = A * Pc[r];
;                 hc[r] = bcast15(hh, lane); Pc[r] = bcast15(PP, lane); hv[r] = hh; pv[r] = PP; }
;             *(unsigned long long*)(y + (size_t)(row0 + tok) * DM + 64 * h + j0) = (unsigned long long)pk2(hv[0], hv[1]) | ((unsigned long long)pk2(hv[2], hv[3]) << 32);
;             *(unsigned long long*)((bf16_t*)(ws + WS_P) + (size_t)(row0 + tok) * 512 + 64 * h + j0) = (unsigned long long)pk2(pv[0], pv[1]) | ((unsigned long long)pk2(pv[2], pv[3]) << 32);
	v_mov_b32_dpp v118, v112 row_shr:1 row_mask:0xf bank_mask:0xf bound_ctrl:1
	v_mov_b32_dpp v119, v113 row_shr:1 row_mask:0xf bank_mask:0xf bound_ctrl:1
	v_pk_mul_f32 v[94:95], v[122:123], v[88:89]
	v_pk_mul_f32 v[122:123], v[108:109], v[90:91]
	v_mov_b32_e32 v90, 1.0
	v_mov_b32_e32 v91, 1.0
	v_pk_fma_f32 v[108:109], v[108:109], v[118:119], v[112:113]
	v_mov_b32_dpp v90, v122 row_shr:2 row_mask:0xf bank_mask:0xf
	v_mov_b32_dpp v91, v123 row_shr:2 row_mask:0xf bank_mask:0xf
	v_mov_b32_dpp v112, v108 row_shr:2 row_mask:0xf bank_mask:0xf bound_ctrl:1
	v_mov_b32_dpp v113, v109 row_shr:2 row_mask:0xf bank_mask:0xf bound_ctrl:1
	v_pk_mul_f32 v[124:125], v[122:123], v[90:91]
	v_mov_b32_e32 v90, 1.0
	v_mov_b32_e32 v91, 1.0
	v_pk_fma_f32 v[108:109], v[122:123], v[112:113], v[108:109]
	v_mov_b32_dpp v90, v124 row_shr:4 row_mask:0xf bank_mask:0xf
	v_mov_b32_dpp v91, v125 row_shr:4 row_mask:0xf bank_mask:0xf
	v_mov_b32_dpp v112, v108 row_shr:4 row_mask:0xf bank_mask:0xf bound_ctrl:1
	v_mov_b32_dpp v113, v109 row_shr:4 row_mask:0xf bank_mask:0xf bound_ctrl:1
	v_pk_mul_f32 v[126:127], v[124:125], v[90:91]
	v_mov_b32_e32 v90, 1.0
	v_mov_b32_e32 v91, 1.0
	v_pk_fma_f32 v[108:109], v[124:125], v[112:113], v[108:109]
	v_mov_b32_dpp v90, v126 row_shr:8 row_mask:0xf bank_mask:0xf
	v_mov_b32_dpp v91, v127 row_shr:8 row_mask:0xf bank_mask:0xf
	v_mov_b32_dpp v112, v108 row_shr:8 row_mask:0xf bank_mask:0xf bound_ctrl:1
	v_mov_b32_dpp v113, v109 row_shr:8 row_mask:0xf bank_mask:0xf bound_ctrl:1
	v_pk_mul_f32 v[120:121], v[126:127], v[90:91]
	v_pk_fma_f32 v[108:109], v[126:127], v[112:113], v[108:109]
	v_pk_fma_f32 v[110:111], v[94:95], 0, v[92:93] op_sel_hi:[1,0,1]
	v_pk_fma_f32 v[112:113], v[120:121], 0, v[108:109] op_sel_hi:[1,0,1]
	ds_bpermute_b32 v92, v1, v110
	ds_bpermute_b32 v93, v1, v111
	v_cvt_pk_bf16_f32 v110, v110, v111
	v_cvt_pk_bf16_f32 v111, v112, v113
	ds_bpermute_b32 v108, v1, v112
	ds_bpermute_b32 v109, v1, v113
	v_mov_b64_e32 v[222:223], v[110:111]
	v_mfma_f32_16x16x32_bf16 v[110:113], v[64:67], v[12:15], 0
	ds_bpermute_b32 v88, v1, v94
	ds_bpermute_b32 v89, v1, v95
	v_cvt_pk_bf16_f32 v94, v94, v95
	v_mfma_f32_16x16x32_bf16 v[122:125], v[56:59], v[28:31], v[110:113]
	v_cvt_pk_bf16_f32 v95, v120, v121
	v_mov_b64_e32 v[226:227], v[94:95]
	ds_bpermute_b32 v90, v1, v120
	ds_bpermute_b32 v91, v1, v121
	v_mfma_f32_16x16x32_bf16 v[118:121], v[60:63], v[12:15], 0
	s_nop 2
	v_add_f32_e32 v94, v48, v122
	v_mul_f32_e32 v94, 0xbfb8aa3b, v94
	v_exp_f32_e32 v94, v94
	v_mfma_f32_16x16x32_bf16 v[118:121], v[52:55], v[28:31], v[118:121]
	v_mov_b32_e32 v112, 1.0
	v_add_f32_e32 v94, 1.0, v94
	v_rcp_f32_e32 v95, v94
	s_nop 0
	v_mul_f32_e32 v95, 0xc1000000, v95
	v_mul_f32_e32 v95, v2, v95
	v_mul_f32_e32 v95, 0x3fb8aa3b, v95
	v_exp_f32_e32 v110, v95
	v_add_f32_e32 v94, v44, v118
	v_mul_f32_e32 v94, 0xbfb8aa3b, v94
	v_exp_f32_e32 v94, v94
	v_fma_f32 v95, -v110, v110, 1.0
	v_sqrt_f32_e32 v118, v95
	v_add_f32_e32 v95, v49, v123
	v_mul_f32_e32 v95, 0xbfb8aa3b, v95
	v_exp_f32_e32 v95, v95
	v_mov_b32_dpp v112, v110 row_shr:1 row_mask:0xf bank_mask:0xf
	v_add_f32_e32 v94, 1.0, v94
	v_rcp_f32_e32 v94, v94
	v_add_f32_e32 v95, 1.0, v95
	v_rcp_f32_e32 v111, v95
	v_add_f32_e32 v95, v45, v119
	v_mul_f32_e32 v95, 0xbfb8aa3b, v95
	v_exp_f32_e32 v95, v95
	v_mul_f32_e32 v111, 0xc1000000, v111
	v_mul_f32_e32 v111, v134, v111
	v_mul_f32_e32 v111, 0x3fb8aa3b, v111
	v_exp_f32_e32 v111, v111
	v_add_f32_e32 v95, 1.0, v95
	v_rcp_f32_e32 v95, v95
	v_fma_f32 v113, -v111, v111, 1.0
	v_sqrt_f32_e32 v119, v113
	v_mov_b32_e32 v113, 1.0
	s_nop 1
	v_mov_b32_dpp v113, v111 row_shr:1 row_mask:0xf bank_mask:0xf
	v_pk_mul_f32 v[122:123], v[110:111], v[112:113]
	v_mov_b32_e32 v112, 1.0
	v_mov_b32_e32 v113, 1.0
	s_nop 0
	v_mov_b32_dpp v112, v122 row_shr:2 row_mask:0xf bank_mask:0xf
	v_mov_b32_dpp v113, v123 row_shr:2 row_mask:0xf bank_mask:0xf
	v_pk_mul_f32 v[126:127], v[122:123], v[112:113]
	v_mov_b32_e32 v112, 1.0
	v_mov_b32_e32 v113, 1.0
	s_nop 0
	v_mov_b32_dpp v112, v126 row_shr:4 row_mask:0xf bank_mask:0xf
	v_mov_b32_dpp v113, v127 row_shr:4 row_mask:0xf bank_mask:0xf
	v_pk_mul_f32 v[128:129], v[126:127], v[112:113]
	v_mov_b32_e32 v112, 1.0
	v_mov_b32_e32 v113, 1.0
	s_nop 0
	v_mov_b32_dpp v112, v128 row_shr:8 row_mask:0xf bank_mask:0xf
	v_mov_b32_dpp v113, v129 row_shr:8 row_mask:0xf bank_mask:0xf
	v_pk_mul_f32 v[130:131], v[128:129], v[112:113]
	v_add_u32_e32 v113, 0x10c0, v145
	ds_read2_b32 v[132:133], v113 offset1:1
	s_waitcnt lgkmcnt(0)
; __device__ __forceinline__ unsigned pk2(float lo, float hi) { const f32x2_t v = {lo, hi}; const bf16x2_t b = __builtin_convertvector(v, bf16x2_t); return __builtin_bit_cast(unsigned, b); }
; __device__ __forceinline__ float sigmoidf_(float x) { return __builtin_amdgcn_rcpf(1.0f + __expf(-x)); }
; __device__ __forceinline__ float bcast15(float v, int lane) { return bperm_f((lane & 48) | 15, v); }
; __device__ __forceinline__ void w_lru_m1(const Args& a, int l, unsigned char* ws, const bf16_t* proj, bf16_t* y, LAS unsigned char* wl, int b, int ck_, int h, int lane) {
;     ...
;         for (int tb = 0; tb < 4; ++tb) { const int tok = 16 * tb + lo;
;             f32x4 ga = {0.f, 0.f, 0.f, 0.f}, gx = {0.f, 0.f, 0.f, 0.f};
; #pragma unroll
;             for (int kk = 0; kk < 2; ++kk) { ga = __builtin_amdgcn_mfma_f32_16x16x32_bf16(WaF[kk], Xf[tb][kk], ga, 0, 0, 0); gx = __builtin_amdgcn_mfma_f32_16x16x32_bf16(WxF[kk], Xf[tb][kk], gx, 0, 0, 0); }
;             float hv[4], pv[4];
; #pragma unroll
;             for (int r = 0; r < 4; ++r) {
;                 const float rg = sigmoidf_(ga[r] + bav[r]), ig = sigmoidf_(gx[r] + bxv[r]);
;                 const float la = -8.0f * rg * sp[r]; float A = __expf(la);
;                 float U = __builtin_amdgcn_sqrtf(1.0f - A * A) * (ig * xcf[tok * 65 + j0 + r]);
;                 { const float As = dpp_shr1<1>(A), Us = dpp_shr0<1>(U); U = A * Us + U; A = A * As; }
;                 { const float As = dpp_shr1<2>(A), Us = dpp_shr0<2>(U); U = A * Us + U; A = A * As; }
;                 { const float As = dpp_shr1<4>(A), Us = dpp_shr0<4>(U); U = A * Us + U; A = A * As; }
;                 { const float As = dpp_shr1<8>(A), Us = dpp_shr0<8>(U); U = A * Us + U; A = A * As; }
;                 const float hh = U + A * hc[r], PP = A * Pc[r];
;                 hc[r] = bcast15(hh, lane); Pc[r] = bcast15(PP, lane); hv[r] = hh; pv[r] = PP; }
;             *(unsigned long long*)(y + (size_t)(row0 + tok) * DM + 64 * h + j0) = (unsigned long long)pk2(hv[0], hv[1]) | ((unsigned long long)pk2(hv[2], hv[3]) << 32);
;             *(unsigned long long*)((bf16_t*)(ws + WS_P) + (size_t)(row0 + tok) * 512 + 64 * h + j0) = (unsigned long long)pk2(pv[0], pv[1]) | ((unsigned long long)pk2(pv[2], pv[3]) << 32);
	v_pk_mul_f32 v[88:89], v[130:131], v[88:89]
	ds_bpermute_b32 v112, v1, v88
	ds_bpermute_b32 v113, v1, v89
	v_cvt_pk_bf16_f32 v88, v88, v89
	v_pk_mul_f32 v[94:95], v[132:133], v[94:95]
	s_nop 0
	v_pk_mul_f32 v[94:95], v[94:95], v[118:119]
	s_nop 1
	v_mov_b32_dpp v118, v94 row_shr:1 row_mask:0xf bank_mask:0xf bound_ctrl:1
	v_mov_b32_dpp v119, v95 row_shr:1 row_mask:0xf bank_mask:0xf bound_ctrl:1
	v_pk_fma_f32 v[94:95], v[110:111], v[118:119], v[94:95]
	s_nop 1
	v_mov_b32_dpp v110, v94 row_shr:2 row_mask:0xf bank_mask:0xf bound_ctrl:1
	v_mov_b32_dpp v111, v95 row_shr:2 row_mask:0xf bank_mask:0xf bound_ctrl:1
	v_pk_fma_f32 v[94:95], v[122:123], v[110:111], v[94:95]
	v_mov_b32_e32 v122, 1.0
	v_mov_b32_e32 v123, 1.0
	v_mov_b32_dpp v110, v94 row_shr:4 row_mask:0xf bank_mask:0xf bound_ctrl:1
	v_mov_b32_dpp v111, v95 row_shr:4 row_mask:0xf bank_mask:0xf bound_ctrl:1
	v_pk_fma_f32 v[94:95], v[126:127], v[110:111], v[94:95]
	s_nop 1
	v_mov_b32_dpp v110, v94 row_shr:8 row_mask:0xf bank_mask:0xf bound_ctrl:1
	v_mov_b32_dpp v111, v95 row_shr:8 row_mask:0xf bank_mask:0xf bound_ctrl:1
	v_pk_fma_f32 v[94:95], v[128:129], v[110:111], v[94:95]
	s_nop 0
	v_pk_fma_f32 v[92:93], v[130:131], v[92:93], v[94:95]
	v_add_f32_e32 v94, v50, v124
	v_mul_f32_e32 v94, 0xbfb8aa3b, v94
	v_exp_f32_e32 v94, v94
	ds_bpermute_b32 v110, v1, v92
	ds_bpermute_b32 v111, v1, v93
	v_cvt_pk_bf16_f32 v92, v92, v93
	v_add_f32_e32 v94, 1.0, v94
	v_rcp_f32_e32 v95, v94
	v_add_f32_e32 v94, v46, v120
	v_mul_f32_e32 v94, 0xbfb8aa3b, v94
	v_exp_f32_e32 v94, v94
	v_mul_f32_e32 v95, 0xc1000000, v95
	v_mul_f32_e32 v95, v135, v95
	v_mul_f32_e32 v95, 0x3fb8aa3b, v95
	v_exp_f32_e32 v118, v95
	v_add_f32_e32 v94, 1.0, v94
	v_rcp_f32_e32 v94, v94
	v_fma_f32 v95, -v118, v118, 1.0
	v_sqrt_f32_e32 v120, v95
	v_add_f32_e32 v95, v51, v125
	v_mul_f32_e32 v95, 0xbfb8aa3b, v95
	v_exp_f32_e32 v95, v95
	v_mov_b32_dpp v122, v118 row_shr:1 row_mask:0xf bank_mask:0xf
	v_add_f32_e32 v95, 1.0, v95
	v_rcp_f32_e32 v119, v95
	v_add_f32_e32 v95, v47, v121
	v_mul_f32_e32 v95, 0xbfb8aa3b, v95
	v_exp_f32_e32 v95, v95
	v_mul_f32_e32 v119, 0xc1000000, v119
	v_mul_f32_e32 v119, v136, v119
	v_mul_f32_e32 v119, 0x3fb8aa3b, v119
	v_exp_f32_e32 v119, v119
	v_add_f32_e32 v95, 1.0, v95
	v_rcp_f32_e32 v95, v95
	v_mov_b32_dpp v123, v119 row_shr:1 row_mask:0xf bank_mask:0xf
	v_pk_mul_f32 v[124:125], v[118:119], v[122:123]
	v_mov_b32_e32 v122, 1.0
	v_mov_b32_e32 v123, 1.0
	v_fma_f32 v121, -v119, v119, 1.0
	v_mov_b32_dpp v122, v124 row_shr:2 row_mask:0xf bank_mask:0xf
	v_mov_b32_dpp v123, v125 row_shr:2 row_mask:0xf bank_mask:0xf
	v_pk_mul_f32 v[126:127], v[124:125], v[122:123]
	v_mov_b32_e32 v122, 1.0
	v_mov_b32_e32 v123, 1.0
	v_sqrt_f32_e32 v121, v121
	v_mov_b32_dpp v122, v126 row_shr:4 row_mask:0xf bank_mask:0xf
	v_mov_b32_dpp v123, v127 row_shr:4 row_mask:0xf bank_mask:0xf
	v_pk_mul_f32 v[128:129], v[126:127], v[122:123]
	v_mov_b32_e32 v122, 1.0
	v_mov_b32_e32 v123, 1.0
	s_nop 0
	v_mov_b32_dpp v122, v128 row_shr:8 row_mask:0xf bank_mask:0xf
	v_mov_b32_dpp v123, v129 row_shr:8 row_mask:0xf bank_mask:0xf
	v_pk_mul_f32 v[130:131], v[128:129], v[122:123]
	v_add_u32_e32 v123, 0x10c8, v145
	ds_read2_b32 v[132:133], v123 offset1:1
	v_pk_mul_f32 v[90:91], v[130:131], v[90:91]
	ds_bpermute_b32 v122, v1, v90
	v_cvt_pk_bf16_f32 v89, v90, v91
	ds_bpermute_b32 v123, v1, v91
	s_waitcnt lgkmcnt(0)
	v_pk_mul_f32 v[94:95], v[94:95], v[132:133]
	s_nop 0
	v_pk_mul_f32 v[94:95], v[120:121], v[94:95]
	s_nop 1
	v_mov_b32_dpp v120, v94 row_shr:1 row_mask:0xf bank_mask:0xf bound_ctrl:1
	v_mov_b32_dpp v121, v95 row_shr:1 row_mask:0xf bank_mask:0xf bound_ctrl:1
	v_pk_fma_f32 v[94:95], v[118:119], v[120:121], v[94:95]
	s_nop 1
	v_mov_b32_dpp v118, v94 row_shr:2 row_mask:0xf bank_mask:0xf bound_ctrl:1
	v_mov_b32_dpp v119, v95 row_shr:2 row_mask:0xf bank_mask:0xf bound_ctrl:1
	v_pk_fma_f32 v[94:95], v[124:125], v[118:119], v[94:95]
	s_nop 1
	v_mov_b32_dpp v118, v94 row_shr:4 row_mask:0xf bank_mask:0xf bound_ctrl:1
	v_mov_b32_dpp v119, v95 row_shr:4 row_mask:0xf bank_mask:0xf bound_ctrl:1
	v_pk_fma_f32 v[94:95], v[126:127], v[118:119], v[94:95]
	s_nop 1
	v_mov_b32_dpp v118, v94 row_shr:8 row_mask:0xf bank_mask:0xf bound_ctrl:1
	v_mov_b32_dpp v119, v95 row_shr:8 row_mask:0xf bank_mask:0xf bound_ctrl:1
	v_pk_fma_f32 v[94:95], v[128:129], v[118:119], v[94:95]
	v_mfma_f32_16x16x32_bf16 v[118:121], v[60:63], v[8:11], 0
	v_fma_f32 v94, v130, v108, v94
	v_fma_f32 v95, v131, v109, v95
	ds_bpermute_b32 v108, v1, v94
	v_cvt_pk_bf16_f32 v93, v94, v95
	v_mov_b64_e32 v[230:231], v[92:93]
	v_mov_b64_e32 v[234:235], v[88:89]
	v_mfma_f32_16x16x32_bf16 v[88:91], v[64:67], v[8:11], 0
	ds_bpermute_b32 v109, v1, v95
	v_mfma_f32_16x16x32_bf16 v[92:95], v[56:59], v[24:27], v[88:91]
	v_mfma_f32_16x16x32_bf16 v[88:91], v[52:55], v[24:27], v[118:121]
	v_mfma_f32_16x16x32_bf16 v[64:67], v[64:67], v[4:7], 0
	s_nop 5
	v_add_f32_e32 v92, v48, v92
	v_mul_f32_e32 v92, 0xbfb8aa3b, v92
	v_exp_f32_e32 v92, v92
	v_add_f32_e32 v88, v44, v88
	v_mul_f32_e32 v88, 0xbfb8aa3b, v88
	v_exp_f32_e32 v88, v88
	v_add_f32_e32 v92, 1.0, v92
	v_rcp_f32_e32 v92, v92
	v_add_f32_e32 v89, v45, v89
	v_add_f32_e32 v88, 1.0, v88
	v_rcp_f32_e32 v118, v88
	v_mul_f32_e32 v88, 0xc1000000, v92
	v_add_f32_e32 v92, v49, v93
	v_mul_f32_e32 v92, 0xbfb8aa3b, v92
	v_exp_f32_e32 v92, v92
	v_mul_f32_e32 v89, 0xbfb8aa3b, v89
	v_exp_f32_e32 v89, v89
	v_mul_f32_e32 v88, v2, v88
	v_add_f32_e32 v92, 1.0, v92
	v_rcp_f32_e32 v92, v92
	v_add_f32_e32 v89, 1.0, v89
	v_rcp_f32_e32 v119, v89
	v_mul_f32_e32 v88, 0x3fb8aa3b, v88
	v_mul_f32_e32 v89, 0xc1000000, v92
	v_mul_f32_e32 v89, v134, v89
	v_mul_f32_e32 v89, 0x3fb8aa3b, v89
; __device__ __forceinline__ float sigmoidf_(float x) { return __builtin_amdgcn_rcpf(1.0f + __expf(-x)); }
; __device__ __forceinline__ float bcast15(float v, int lane) { return bperm_f((lane & 48) | 15, v); }
; __device__ __forceinline__ void w_lru_m1(const Args& a, int l, unsigned char* ws, const bf16_t* proj, bf16_t* y, LAS unsigned char* wl, int b, int ck_, int h, int lane) {
;     ...
;         for (int tb = 0; tb < 4; ++tb) { const int tok = 16 * tb + lo;
;             f32x4 ga = {0.f, 0.f, 0.f, 0.f}, gx = {0.f, 0.f, 0.f, 0.f};
; #pragma unroll
;             for (int kk = 0; kk < 2; ++kk) { ga = __builtin_amdgcn_mfma_f32_16x16x32_bf16(WaF[kk], Xf[tb][kk], ga, 0, 0, 0); gx = __builtin_amdgcn_mfma_f32_16x16x32_bf16(WxF[kk], Xf[tb][kk], gx, 0, 0, 0); }
;             float hv[4], pv[4];
; #pragma unroll
;             for (int r = 0; r < 4; ++r) {
;                 const float rg = sigmoidf_(ga[r] + bav[r]), ig = sigmoidf_(gx[r] + bxv[r]);
;                 const float la = -8.0f * rg * sp[r]; float A = __expf(la);
;                 float U = __builtin_amdgcn_sqrtf(1.0f - A * A) * (ig * xcf[tok * 65 + j0 + r]);
;                 { const float As = dpp_shr1<1>(A), Us = dpp_shr0<1>(U); U = A * Us + U; A = A * As; }
;                 { const float As = dpp_shr1<2>(A), Us = dpp_shr0<2>(U); U = A * Us + U; A = A * As; }
;                 { const float As = dpp_shr1<4>(A), Us = dpp_shr0<4>(U); U = A * Us + U; A = A * As; }
;                 { const float As = dpp_shr1<8>(A), Us = dpp_shr0<8>(U); U = A * Us + U; A = A * As; }
;                 const float hh = U + A * hc[r], PP = A * Pc[r];
;                 hc[r] = bcast15(hh, lane); Pc[r] = bcast15(PP, lane); hv[r] = hh; pv[r] = PP; }
	v_exp_f32_e32 v120, v88
	v_exp_f32_e32 v121, v89
	v_mfma_f32_16x16x32_bf16 v[60:63], v[60:63], v[4:7], 0
	v_add_f32_e32 v94, v50, v94
	v_fma_f32 v88, -v120, v120, 1.0
	v_fma_f32 v89, -v121, v121, 1.0
	v_sqrt_f32_e32 v124, v88
	v_mov_b32_e32 v88, 1.0
	v_sqrt_f32_e32 v125, v89
	v_mov_b32_e32 v89, 1.0
	v_mov_b32_dpp v88, v120 row_shr:1 row_mask:0xf bank_mask:0xf
	v_mfma_f32_16x16x32_bf16 v[56:59], v[56:59], v[20:23], v[64:67]
	v_mov_b32_dpp v89, v121 row_shr:1 row_mask:0xf bank_mask:0xf
	v_pk_mul_f32 v[126:127], v[120:121], v[88:89]
	v_mov_b32_e32 v88, 1.0
	v_mov_b32_e32 v89, 1.0
	v_add_f32_e32 v95, v51, v95
	v_mov_b32_dpp v88, v126 row_shr:2 row_mask:0xf bank_mask:0xf
	v_mov_b32_dpp v89, v127 row_shr:2 row_mask:0xf bank_mask:0xf
	v_pk_mul_f32 v[128:129], v[126:127], v[88:89]
	v_mov_b32_e32 v88, 1.0
	v_mov_b32_e32 v89, 1.0
	v_mul_f32_e32 v94, 0xbfb8aa3b, v94
	v_mov_b32_dpp v88, v128 row_shr:4 row_mask:0xf bank_mask:0xf
	v_mov_b32_dpp v89, v129 row_shr:4 row_mask:0xf bank_mask:0xf
	v_pk_mul_f32 v[130:131], v[128:129], v[88:89]
	v_mov_b32_e32 v88, 1.0
	v_mov_b32_e32 v89, 1.0
	v_mul_f32_e32 v95, 0xbfb8aa3b, v95
	v_mov_b32_dpp v88, v130 row_shr:8 row_mask:0xf bank_mask:0xf
	v_mov_b32_dpp v89, v131 row_shr:8 row_mask:0xf bank_mask:0xf
	v_pk_mul_f32 v[132:133], v[130:131], v[88:89]
	v_add_u32_e32 v89, 0x2100, v145
	v_pk_mul_f32 v[92:93], v[132:133], v[112:113]
	ds_read2_b32 v[112:113], v89 offset1:1
	v_mfma_f32_16x16x32_bf16 v[60:63], v[52:55], v[20:23], v[60:63]
	v_add_f32_e32 v48, v48, v56
	v_exp_f32_e32 v94, v94
	v_exp_f32_e32 v95, v95
	s_waitcnt lgkmcnt(0)
	v_pk_mul_f32 v[112:113], v[112:113], v[118:119]
	v_mul_f32_e32 v48, 0xbfb8aa3b, v48
	v_pk_mul_f32 v[112:113], v[112:113], v[124:125]
	v_exp_f32_e32 v48, v48
	v_add_f32_e32 v90, v46, v90
	v_mov_b32_dpp v118, v112 row_shr:1 row_mask:0xf bank_mask:0xf bound_ctrl:1
	v_mov_b32_dpp v119, v113 row_shr:1 row_mask:0xf bank_mask:0xf bound_ctrl:1
	v_add_f32_e32 v91, v47, v91
	v_pk_fma_f32 v[112:113], v[120:121], v[118:119], v[112:113]
	v_mul_f32_e32 v90, 0xbfb8aa3b, v90
	v_mul_f32_e32 v91, 0xbfb8aa3b, v91
	v_add_f32_e32 v44, v44, v60
	v_mov_b32_dpp v118, v112 row_shr:2 row_mask:0xf bank_mask:0xf bound_ctrl:1
	v_mov_b32_dpp v119, v113 row_shr:2 row_mask:0xf bank_mask:0xf bound_ctrl:1
	v_add_f32_e32 v94, 1.0, v94
	v_exp_f32_e32 v90, v90
	v_add_f32_e32 v95, 1.0, v95
	v_exp_f32_e32 v91, v91
	v_mul_f32_e32 v44, 0xbfb8aa3b, v44
	v_pk_fma_f32 v[112:113], v[126:127], v[118:119], v[112:113]
	v_rcp_f32_e32 v94, v94
	v_rcp_f32_e32 v95, v95
	v_add_f32_e32 v48, 1.0, v48
	v_exp_f32_e32 v44, v44
	v_mov_b32_dpp v118, v112 row_shr:4 row_mask:0xf bank_mask:0xf bound_ctrl:1
	v_mov_b32_dpp v119, v113 row_shr:4 row_mask:0xf bank_mask:0xf bound_ctrl:1
	v_rcp_f32_e32 v52, v48
	v_pk_fma_f32 v[112:113], v[128:129], v[118:119], v[112:113]
	v_add_f32_e32 v90, 1.0, v90
	v_add_f32_e32 v91, 1.0, v91
	v_mov_b32_dpp v118, v112 row_shr:8 row_mask:0xf bank_mask:0xf bound_ctrl:1
	v_mov_b32_dpp v119, v113 row_shr:8 row_mask:0xf bank_mask:0xf bound_ctrl:1
	v_pk_fma_f32 v[112:113], v[130:131], v[118:119], v[112:113]
	v_rcp_f32_e32 v118, v90
	v_mul_f32_e32 v90, 0xc1000000, v94
	v_rcp_f32_e32 v119, v91
	v_mul_f32_e32 v91, 0xc1000000, v95
	v_add_f32_e32 v44, 1.0, v44
	v_mul_f32_e32 v90, v135, v90
	v_mul_f32_e32 v91, v136, v91
	v_rcp_f32_e32 v48, v44
	v_mul_f32_e32 v44, 0xc1000000, v52
	v_mul_f32_e32 v90, 0x3fb8aa3b, v90
	v_mul_f32_e32 v91, 0x3fb8aa3b, v91
	v_mul_f32_e32 v2, v2, v44
	v_exp_f32_e32 v94, v90
	v_exp_f32_e32 v95, v91
	v_mul_f32_e32 v2, 0x3fb8aa3b, v2
	v_exp_f32_e32 v54, v2
	v_fma_f32 v90, -v94, v94, 1.0
	v_fma_f32 v91, -v95, v95, 1.0
	v_sqrt_f32_e32 v120, v90
	v_mov_b32_e32 v90, 1.0
	v_sqrt_f32_e32 v121, v91
	v_mov_b32_e32 v91, 1.0
	v_fma_f32 v2, -v54, v54, 1.0
	v_mov_b32_dpp v90, v94 row_shr:1 row_mask:0xf bank_mask:0xf
	v_mov_b32_dpp v91, v95 row_shr:1 row_mask:0xf bank_mask:0xf
	v_sqrt_f32_e32 v56, v2
	v_add_f32_e32 v2, v49, v57
	v_pk_mul_f32 v[124:125], v[94:95], v[90:91]
	v_mov_b32_e32 v90, 1.0
	v_mov_b32_e32 v91, 1.0
	v_mul_f32_e32 v2, 0xbfb8aa3b, v2
	v_mov_b32_dpp v90, v124 row_shr:2 row_mask:0xf bank_mask:0xf
	v_mov_b32_dpp v91, v125 row_shr:2 row_mask:0xf bank_mask:0xf
	v_exp_f32_e32 v2, v2
	v_pk_mul_f32 v[126:127], v[124:125], v[90:91]
	v_mov_b32_e32 v90, 1.0
	v_mov_b32_e32 v91, 1.0
	v_add_f32_e32 v2, 1.0, v2
	v_mov_b32_dpp v90, v126 row_shr:4 row_mask:0xf bank_mask:0xf
	v_mov_b32_dpp v91, v127 row_shr:4 row_mask:0xf bank_mask:0xf
	v_pk_mul_f32 v[128:129], v[126:127], v[90:91]
	v_mov_b32_e32 v90, 1.0
	v_mov_b32_e32 v91, 1.0
	v_rcp_f32_e32 v2, v2
	v_mov_b32_dpp v90, v128 row_shr:8 row_mask:0xf bank_mask:0xf
	v_mov_b32_dpp v91, v129 row_shr:8 row_mask:0xf bank_mask:0xf
	v_pk_mul_f32 v[130:131], v[128:129], v[90:91]
	v_add_u32_e32 v91, 0x2108, v145
	v_pk_fma_f32 v[112:113], v[132:133], v[110:111], v[112:113]
	ds_read2_b32 v[132:133], v91 offset1:1
	v_add_f32_e32 v45, v45, v61
	v_mul_f32_e32 v45, 0xbfb8aa3b, v45
	v_mul_f32_e32 v2, 0xc1000000, v2
	v_exp_f32_e32 v45, v45
	v_mul_f32_e32 v2, v134, v2
	s_waitcnt lgkmcnt(0)
; __device__ __forceinline__ unsigned pk2(float lo, float hi) { const f32x2_t v = {lo, hi}; const bf16x2_t b = __builtin_convertvector(v, bf16x2_t); return __builtin_bit_cast(unsigned, b); }
; __device__ __forceinline__ float sigmoidf_(float x) { return __builtin_amdgcn_rcpf(1.0f + __expf(-x)); }
; __device__ __forceinline__ void w_lru_m1(const Args& a, int l, unsigned char* ws, const bf16_t* proj, bf16_t* y, LAS unsigned char* wl, int b, int ck_, int h, int lane) {
;     ...
;         for (int tb = 0; tb < 4; ++tb) { const int tok = 16 * tb + lo;
;             f32x4 ga = {0.f, 0.f, 0.f, 0.f}, gx = {0.f, 0.f, 0.f, 0.f};
; #pragma unroll
;             for (int kk = 0; kk < 2; ++kk) { ga = __builtin_amdgcn_mfma_f32_16x16x32_bf16(WaF[kk], Xf[tb][kk], ga, 0, 0, 0); gx = __builtin_amdgcn_mfma_f32_16x16x32_bf16(WxF[kk], Xf[tb][kk], gx, 0, 0, 0); }
;             float hv[4], pv[4];
; #pragma unroll
;             for (int r = 0; r < 4; ++r) {
;                 const float rg = sigmoidf_(ga[r] + bav[r]), ig = sigmoidf_(gx[r] + bxv[r]);
;                 const float la = -8.0f * rg * sp[r]; float A = __expf(la);
;                 float U = __builtin_amdgcn_sqrtf(1.0f - A * A) * (ig * xcf[tok * 65 + j0 + r]);
;                 { const float As = dpp_shr1<1>(A), Us = dpp_shr0<1>(U); U = A * Us + U; A = A * As; }
;                 { const float As = dpp_shr1<2>(A), Us = dpp_shr0<2>(U); U = A * Us + U; A = A * As; }
;                 { const float As = dpp_shr1<4>(A), Us = dpp_shr0<4>(U); U = A * Us + U; A = A * As; }
;                 { const float As = dpp_shr1<8>(A), Us = dpp_shr0<8>(U); U = A * Us + U; A = A * As; }
;                 const float hh = U + A * hc[r], PP = A * Pc[r];
;                 hc[r] = bcast15(hh, lane); Pc[r] = bcast15(PP, lane); hv[r] = hh; pv[r] = PP; }
;             *(unsigned long long*)(y + (size_t)(row0 + tok) * DM + 64 * h + j0) = (unsigned long long)pk2(hv[0], hv[1]) | ((unsigned long long)pk2(hv[2], hv[3]) << 32);
;             *(unsigned long long*)((bf16_t*)(ws + WS_P) + (size_t)(row0 + tok) * 512 + 64 * h + j0) = (unsigned long long)pk2(pv[0], pv[1]) | ((unsigned long long)pk2(pv[2], pv[3]) << 32);
;         }
;         if (lo == 0) { const size_t so = (size_t)(b * NCH + ck_) * 512 + 64 * h + j0;
; #pragma unroll
;             for (int r = 0; r < 4; ++r) { ((float*)(ws + WS_LRUA))[so + r] = Pc[r]; ((float*)(ws + WS_LRUH))[so + r] = hc[r]; } }
	v_pk_mul_f32 v[118:119], v[118:119], v[132:133]
	v_mul_f32_e32 v2, 0x3fb8aa3b, v2
	v_pk_mul_f32 v[118:119], v[120:121], v[118:119]
	v_exp_f32_e32 v55, v2
	v_add_f32_e32 v45, 1.0, v45
	v_mov_b32_dpp v120, v118 row_shr:1 row_mask:0xf bank_mask:0xf bound_ctrl:1
	v_mov_b32_dpp v121, v119 row_shr:1 row_mask:0xf bank_mask:0xf bound_ctrl:1
	v_pk_fma_f32 v[94:95], v[94:95], v[120:121], v[118:119]
	v_mov_b32_e32 v44, 1.0
	v_rcp_f32_e32 v49, v45
	v_mov_b32_dpp v118, v94 row_shr:2 row_mask:0xf bank_mask:0xf bound_ctrl:1
	v_mov_b32_dpp v119, v95 row_shr:2 row_mask:0xf bank_mask:0xf bound_ctrl:1
	v_mov_b32_e32 v45, 1.0
	v_pk_fma_f32 v[94:95], v[124:125], v[118:119], v[94:95]
	v_mov_b32_dpp v44, v54 row_shr:1 row_mask:0xf bank_mask:0xf
	v_mov_b32_dpp v45, v55 row_shr:1 row_mask:0xf bank_mask:0xf
	v_mov_b32_dpp v118, v94 row_shr:4 row_mask:0xf bank_mask:0xf bound_ctrl:1
	v_mov_b32_dpp v119, v95 row_shr:4 row_mask:0xf bank_mask:0xf bound_ctrl:1
	v_pk_mul_f32 v[60:61], v[54:55], v[44:45]
	v_mov_b32_e32 v44, 1.0
	v_mov_b32_e32 v45, 1.0
	v_pk_fma_f32 v[94:95], v[126:127], v[118:119], v[94:95]
	v_mov_b32_dpp v44, v60 row_shr:2 row_mask:0xf bank_mask:0xf
	v_mov_b32_dpp v45, v61 row_shr:2 row_mask:0xf bank_mask:0xf
	ds_bpermute_b32 v88, v1, v92
	ds_bpermute_b32 v89, v1, v93
	v_mov_b32_dpp v118, v94 row_shr:8 row_mask:0xf bank_mask:0xf bound_ctrl:1
	v_mov_b32_dpp v119, v95 row_shr:8 row_mask:0xf bank_mask:0xf bound_ctrl:1
	v_pk_mul_f32 v[64:65], v[60:61], v[44:45]
	v_mov_b32_e32 v44, 1.0
	v_mov_b32_e32 v45, 1.0
	v_pk_fma_f32 v[94:95], v[128:129], v[118:119], v[94:95]
	v_mov_b32_dpp v44, v64 row_shr:4 row_mask:0xf bank_mask:0xf
	v_mov_b32_dpp v45, v65 row_shr:4 row_mask:0xf bank_mask:0xf
	v_pk_mul_f32 v[122:123], v[130:131], v[122:123]
	v_pk_fma_f32 v[108:109], v[130:131], v[108:109], v[94:95]
	v_pk_mul_f32 v[66:67], v[64:65], v[44:45]
	v_mov_b32_e32 v44, 1.0
	v_mov_b32_e32 v45, 1.0
	ds_bpermute_b32 v110, v1, v112
	ds_bpermute_b32 v111, v1, v113
	v_cvt_pk_bf16_f32 v112, v112, v113
	v_cvt_pk_bf16_f32 v113, v108, v109
	v_cvt_pk_bf16_f32 v92, v92, v93
	v_cvt_pk_bf16_f32 v93, v122, v123
	v_fma_f32 v2, -v55, v55, 1.0
	v_mov_b32_dpp v44, v66 row_shr:8 row_mask:0xf bank_mask:0xf
	v_mov_b32_dpp v45, v67 row_shr:8 row_mask:0xf bank_mask:0xf
	v_mov_b64_e32 v[238:239], v[112:113]
	v_mov_b64_e32 v[242:243], v[92:93]
	v_sqrt_f32_e32 v57, v2
	v_pk_mul_f32 v[92:93], v[66:67], v[44:45]
	v_add_u32_e32 v2, 0x3140, v145
	s_waitcnt lgkmcnt(0)
	v_pk_mul_f32 v[52:53], v[92:93], v[88:89]
	ds_read2_b32 v[88:89], v2 offset1:1
	v_add_f32_e32 v2, v50, v58
	v_mul_f32_e32 v2, 0xbfb8aa3b, v2
	v_exp_f32_e32 v2, v2
	v_add_f32_e32 v46, v46, v62
	v_add_f32_e32 v47, v47, v63
	v_mul_f32_e32 v46, 0xbfb8aa3b, v46
	v_add_f32_e32 v2, 1.0, v2
	v_rcp_f32_e32 v2, v2
	v_mul_f32_e32 v47, 0xbfb8aa3b, v47
	v_exp_f32_e32 v46, v46
	v_exp_f32_e32 v47, v47
	v_mul_f32_e32 v2, 0xc1000000, v2
	v_mul_f32_e32 v2, v135, v2
	v_mul_f32_e32 v2, 0x3fb8aa3b, v2
	v_exp_f32_e32 v50, v2
	s_waitcnt lgkmcnt(0)
	v_pk_mul_f32 v[48:49], v[88:89], v[48:49]
	v_add_f32_e32 v46, 1.0, v46
	v_pk_mul_f32 v[48:49], v[48:49], v[56:57]
	v_fma_f32 v2, -v50, v50, 1.0
	v_sqrt_f32_e32 v58, v2
	v_add_f32_e32 v2, v51, v59
	v_mul_f32_e32 v2, 0xbfb8aa3b, v2
	v_exp_f32_e32 v2, v2
	v_mov_b32_dpp v56, v48 row_shr:1 row_mask:0xf bank_mask:0xf bound_ctrl:1
	v_mov_b32_dpp v57, v49 row_shr:1 row_mask:0xf bank_mask:0xf bound_ctrl:1
	v_add_f32_e32 v47, 1.0, v47
	v_add_f32_e32 v2, 1.0, v2
	v_rcp_f32_e32 v2, v2
	v_pk_fma_f32 v[48:49], v[54:55], v[56:57], v[48:49]
	v_rcp_f32_e32 v56, v46
	v_mov_b32_e32 v46, 1.0
	v_mul_f32_e32 v2, 0xc1000000, v2
	v_mul_f32_e32 v2, v136, v2
	v_mul_f32_e32 v2, 0x3fb8aa3b, v2
	v_exp_f32_e32 v51, v2
	v_rcp_f32_e32 v57, v47
	v_mov_b32_e32 v47, 1.0
	v_mov_b32_dpp v54, v48 row_shr:2 row_mask:0xf bank_mask:0xf bound_ctrl:1
	v_mov_b32_dpp v55, v49 row_shr:2 row_mask:0xf bank_mask:0xf bound_ctrl:1
	v_mov_b32_dpp v46, v50 row_shr:1 row_mask:0xf bank_mask:0xf
	v_mov_b32_dpp v47, v51 row_shr:1 row_mask:0xf bank_mask:0xf
	v_pk_fma_f32 v[48:49], v[60:61], v[54:55], v[48:49]
	v_pk_mul_f32 v[62:63], v[50:51], v[46:47]
	v_mov_b32_e32 v46, 1.0
	v_mov_b32_e32 v47, 1.0
	v_mov_b32_dpp v54, v48 row_shr:4 row_mask:0xf bank_mask:0xf bound_ctrl:1
	v_mov_b32_dpp v55, v49 row_shr:4 row_mask:0xf bank_mask:0xf bound_ctrl:1
	v_mov_b32_dpp v46, v62 row_shr:2 row_mask:0xf bank_mask:0xf
	v_mov_b32_dpp v47, v63 row_shr:2 row_mask:0xf bank_mask:0xf
	ds_bpermute_b32 v90, v1, v122
	ds_bpermute_b32 v91, v1, v123
	v_pk_fma_f32 v[48:49], v[64:65], v[54:55], v[48:49]
	v_pk_mul_f32 v[64:65], v[62:63], v[46:47]
	v_mov_b32_e32 v46, 1.0
	v_mov_b32_e32 v47, 1.0
	v_mov_b32_dpp v54, v48 row_shr:8 row_mask:0xf bank_mask:0xf bound_ctrl:1
	v_mov_b32_dpp v55, v49 row_shr:8 row_mask:0xf bank_mask:0xf bound_ctrl:1
	v_mov_b32_dpp v46, v64 row_shr:4 row_mask:0xf bank_mask:0xf
	v_mov_b32_dpp v47, v65 row_shr:4 row_mask:0xf bank_mask:0xf
	v_pk_fma_f32 v[48:49], v[66:67], v[54:55], v[48:49]
	v_pk_mul_f32 v[66:67], v[64:65], v[46:47]
	v_mov_b32_e32 v46, 1.0
	v_mov_b32_e32 v47, 1.0
	v_fma_f32 v2, -v51, v51, 1.0
	v_mov_b32_dpp v46, v66 row_shr:8 row_mask:0xf bank_mask:0xf
	v_mov_b32_dpp v47, v67 row_shr:8 row_mask:0xf bank_mask:0xf
	v_sqrt_f32_e32 v59, v2
	v_pk_mul_f32 v[88:89], v[66:67], v[46:47]
	v_add_u32_e32 v2, 0x3148, v145
	s_waitcnt lgkmcnt(0)
	v_pk_mul_f32 v[60:61], v[88:89], v[90:91]
	ds_read2_b32 v[90:91], v2 offset1:1
	ds_bpermute_b32 v94, v1, v108
	ds_bpermute_b32 v95, v1, v109
	v_pk_fma_f32 v[54:55], v[92:93], v[110:111], v[48:49]
	ds_bpermute_b32 v44, v1, v52
	s_waitcnt lgkmcnt(0)
	v_pk_mul_f32 v[56:57], v[56:57], v[90:91]
	ds_bpermute_b32 v48, v1, v54
	v_pk_mul_f32 v[56:57], v[58:59], v[56:57]
	ds_bpermute_b32 v49, v1, v55
	ds_bpermute_b32 v45, v1, v53
	v_mov_b32_dpp v58, v56 row_shr:1 row_mask:0xf bank_mask:0xf bound_ctrl:1
	v_mov_b32_dpp v59, v57 row_shr:1 row_mask:0xf bank_mask:0xf bound_ctrl:1
	v_pk_fma_f32 v[50:51], v[50:51], v[58:59], v[56:57]
	ds_bpermute_b32 v46, v1, v60
	ds_bpermute_b32 v47, v1, v61
	v_mov_b32_dpp v56, v50 row_shr:2 row_mask:0xf bank_mask:0xf bound_ctrl:1
	v_mov_b32_dpp v57, v51 row_shr:2 row_mask:0xf bank_mask:0xf bound_ctrl:1
	v_pk_fma_f32 v[50:51], v[62:63], v[56:57], v[50:51]
	v_cvt_pk_bf16_f32 v54, v54, v55
	v_cvt_pk_bf16_f32 v52, v52, v53
	v_mov_b32_dpp v56, v50 row_shr:4 row_mask:0xf bank_mask:0xf bound_ctrl:1
	v_mov_b32_dpp v57, v51 row_shr:4 row_mask:0xf bank_mask:0xf bound_ctrl:1
	v_pk_fma_f32 v[50:51], v[64:65], v[56:57], v[50:51]
	v_cvt_pk_bf16_f32 v53, v60, v61
	s_nop 0
	v_mov_b32_dpp v56, v50 row_shr:8 row_mask:0xf bank_mask:0xf bound_ctrl:1
	v_mov_b32_dpp v57, v51 row_shr:8 row_mask:0xf bank_mask:0xf bound_ctrl:1
	v_pk_fma_f32 v[50:51], v[66:67], v[56:57], v[50:51]
	s_nop 0
	v_pk_fma_f32 v[56:57], v[88:89], v[94:95], v[50:51]
	ds_bpermute_b32 v50, v1, v56
	ds_bpermute_b32 v51, v1, v57
	v_cvt_pk_bf16_f32 v55, v56, v57
	v_mov_b64_e32 v[246:247], v[54:55]
	v_mov_b64_e32 v[250:251], v[52:53]
	s_and_saveexec_b64 s[34:35], vcc
	s_cbranch_execz .LBB0_527
; __device__ __forceinline__ void w_lru_m1(const Args& a, int l, unsigned char* ws, const bf16_t* proj, bf16_t* y, LAS unsigned char* wl, int b, int ck_, int h, int lane) {
;     ...
;     for (int jb = 0; jb < 4; ++jb) {
;         bf16x8 WaF[2], WxF[2]; f32x4 pba, pbx, plam;
; #pragma unroll
;         for (int kk = 0; kk < 2; ++kk) { WaF[kk] = nWa[kk]; WxF[kk] = nWx[kk]; }
;         pba = nba; pbx = nbx; plam = nlam;
;         if (jb < 3) {
; #pragma unroll
;             for (int kk = 0; kk < 2; ++kk) { nWa[kk] = *(const bf16x8*)(waT + (16 * (jb + 1) + lo) * 64 + 32 * kk + 8 * fq); nWx[kk] = *(const bf16x8*)(wxT + (16 * (jb + 1) + lo) * 64 + 32 * kk + 8 * fq); }
;             nba = *(const f32x4*)(ba + 16 * (jb + 1) + 4 * fq); nbx = *(const f32x4*)(bx + 16 * (jb + 1) + 4 * fq); nlam = *(const f32x4*)(lam + 16 * (jb + 1) + 4 * fq);
;         }
;         const int j0 = 16 * jb + 4 * fq;
;         float bav[4], bxv[4], sp[4], hc[4], Pc[4];
; #pragma unroll
;         for (int r = 0; r < 4; ++r) { bav[r] = pba[r]; bxv[r] = pbx[r]; sp[r] = log1pf(__expf(-plam[r])); hc[r] = 0.f; Pc[r] = 1.f; }
; #pragma unroll
;         for (int tb = 0; tb < 4; ++tb) { const int tok = 16 * tb + lo;
;             f32x4 ga = {0.f, 0.f, 0.f, 0.f}, gx = {0.f, 0.f, 0.f, 0.f};
; #pragma unroll
;             for (int kk = 0; kk < 2; ++kk) { ga = __builtin_amdgcn_mfma_f32_16x16x32_bf16(WaF[kk], Xf[tb][kk], ga, 0, 0, 0); gx = __builtin_amdgcn_mfma_f32_16x16x32_bf16(WxF[kk], Xf[tb][kk], gx, 0, 0, 0); }
;             float hv[4], pv[4];
; #pragma unroll
;             for (int r = 0; r < 4; ++r) {
;                 const float rg = sigmoidf_(ga[r] + bav[r]), ig = sigmoidf_(gx[r] + bxv[r]);
;                 const float la = -8.0f * rg * sp[r]; float A = __expf(la);
;                 float U = __builtin_amdgcn_sqrtf(1.0f - A * A) * (ig * xcf[tok * 65 + j0 + r]);
;                 { const float As = dpp_shr1<1>(A), Us = dpp_shr0<1>(U); U = A * Us + U; A = A * As; }
;                 { const float As = dpp_shr1<2>(A), Us = dpp_shr0<2>(U); U = A * Us + U; A = A * As; }
;                 { const float As = dpp_shr1<4>(A), Us = dpp_shr0<4>(U); U = A * Us + U; A = A * As; }
;                 { const float As = dpp_shr1<8>(A), Us = dpp_shr0<8>(U); U = A * Us + U; A = A * As; }
;                 const float hh = U + A * hc[r], PP = A * Pc[r];
	v_add_u32_e32 v52, 32, v0
	v_ashrrev_i32_e32 v53, 31, v52
	v_lshl_add_u64 v[52:53], s[42:43], 0, v[52:53]
	v_lshlrev_b64 v[52:53], 2, v[52:53]
	v_lshl_add_u64 v[54:55], s[84:85], 0, v[52:53]
	v_lshl_add_u64 v[52:53], s[86:87], 0, v[52:53]
	s_waitcnt lgkmcnt(0)
	global_store_dwordx4 v[54:55], v[44:47], off
	global_store_dwordx4 v[52:53], v[48:51], off
.LBB0_527:
	s_or_b64 exec, exec, s[34:35]
	s_waitcnt vmcnt(2)
	s_nop 7
	ds_read2_b32 v[64:65], v145 offset0:50 offset1:51
	s_waitcnt lgkmcnt(0)
	s_nop 7
	s_nop 0
	s_nop 7
	s_nop 0
	s_nop 7
	s_nop 0
	s_nop 7
	s_nop 0
	s_nop 7
	s_nop 0
	s_nop 7
	s_nop 1
	s_nop 7
	s_nop 1
	s_nop 7
	s_nop 1
	s_nop 7
	v_mov_b32_e32 v58, v84
	s_nop 7
	s_nop 0
	s_nop 7
	s_nop 0
	s_nop 7
	s_nop 0
	s_nop 7
	s_nop 0
	s_nop 7
	s_nop 0
	s_nop 7
	s_nop 0
	s_nop 7
	s_nop 1
	s_nop 7
	s_nop 1
	s_nop 7
	s_nop 1
	s_nop 7
	v_mov_b32_e32 v60, v85
	s_nop 7
	s_nop 0
	s_nop 7
	s_nop 0
	s_nop 7
	s_nop 0
	s_nop 7
	s_nop 0
	s_nop 7
	s_nop 0
	s_nop 7
	s_nop 0
	s_nop 7
	s_nop 1
	s_nop 7
	s_nop 1
	s_nop 7
	s_nop 1
	s_nop 7
	v_mov_b32_e32 v2, v86
	s_nop 7
	s_nop 0
	s_nop 7
	s_nop 0
	s_nop 7
	s_nop 0
	s_nop 7
	s_nop 0
	s_nop 7
	s_nop 0
	s_nop 7
	s_nop 0
	s_nop 7
	ds_read2_b32 v[54:55], v145 offset0:48 offset1:49
	v_mov_b32_e32 v48, 1.0
	s_nop 7
	v_mov_b32_e32 v49, 1.0
	v_mov_b32_e32 v50, 1.0
	s_nop 7
	v_mov_b32_e32 v51, 1.0
	v_mov_b32_e32 v52, 1.0
	s_nop 7
	v_mov_b32_e32 v59, v87
	v_mfma_f32_16x16x32_bf16 v[44:47], v[68:71], v[16:19], 0
	v_mov_b32_e32 v53, 1.0
	v_mfma_f32_16x16x32_bf16 v[16:19], v[72:75], v[16:19], 0
	v_mfma_f32_16x16x32_bf16 v[44:47], v[76:79], v[32:35], v[44:47]
	v_mfma_f32_16x16x32_bf16 v[16:19], v[80:83], v[32:35], v[16:19]
	s_nop 6
	v_add_f32_e32 v32, v40, v44
	v_mul_f32_e32 v32, 0xbfb8aa3b, v32
	v_exp_f32_e32 v32, v32
	v_add_f32_e32 v16, v36, v16
	v_add_f32_e32 v17, v37, v17
	v_mul_f32_e32 v16, 0xbfb8aa3b, v16
	v_add_f32_e32 v32, 1.0, v32
	v_rcp_f32_e32 v32, v32
	v_mul_f32_e32 v17, 0xbfb8aa3b, v17
	v_exp_f32_e32 v16, v16
	v_exp_f32_e32 v17, v17
	v_mul_f32_e32 v32, 0xc1000000, v32
	v_mul_f32_e32 v32, v58, v32
	v_mul_f32_e32 v32, 0x3fb8aa3b, v32
	v_exp_f32_e32 v32, v32
	v_add_f32_e32 v16, 1.0, v16
	v_add_f32_e32 v17, 1.0, v17
	v_rcp_f32_e32 v16, v16
	v_fma_f32 v33, -v32, v32, 1.0
	v_sqrt_f32_e32 v34, v33
	v_add_f32_e32 v33, v41, v45
	v_mul_f32_e32 v33, 0xbfb8aa3b, v33
	v_exp_f32_e32 v33, v33
	v_rcp_f32_e32 v17, v17
	v_mov_b32_e32 v44, 1.0
	v_mov_b32_e32 v45, 1.0
	v_add_f32_e32 v33, 1.0, v33
	v_rcp_f32_e32 v33, v33
	s_waitcnt lgkmcnt(0)
	v_pk_mul_f32 v[16:17], v[54:55], v[16:17]
	v_mov_b32_dpp v44, v32 row_shr:1 row_mask:0xf bank_mask:0xf
	v_add_f32_e32 v18, v38, v18
	v_mul_f32_e32 v33, 0xc1000000, v33
	v_mul_f32_e32 v33, v60, v33
	v_mul_f32_e32 v33, 0x3fb8aa3b, v33
	v_exp_f32_e32 v33, v33
	v_add_f32_e32 v19, v39, v19
	v_mul_f32_e32 v18, 0xbfb8aa3b, v18
	v_mul_f32_e32 v19, 0xbfb8aa3b, v19
	v_fma_f32 v35, -v33, v33, 1.0
	v_sqrt_f32_e32 v35, v35
	v_mov_b32_dpp v45, v33 row_shr:1 row_mask:0xf bank_mask:0xf
	v_pk_mul_f32 v[44:45], v[32:33], v[44:45]
	v_exp_f32_e32 v18, v18
	v_pk_mul_f32 v[16:17], v[16:17], v[34:35]
	v_mov_b32_dpp v48, v44 row_shr:2 row_mask:0xf bank_mask:0xf
	v_mov_b32_dpp v49, v45 row_shr:2 row_mask:0xf bank_mask:0xf
	v_mov_b32_dpp v34, v16 row_shr:1 row_mask:0xf bank_mask:0xf bound_ctrl:1
	v_mov_b32_dpp v35, v17 row_shr:1 row_mask:0xf bank_mask:0xf bound_ctrl:1
	v_pk_fma_f32 v[16:17], v[32:33], v[34:35], v[16:17]
	v_pk_mul_f32 v[48:49], v[44:45], v[48:49]
	v_exp_f32_e32 v19, v19
	v_mov_b32_dpp v32, v16 row_shr:2 row_mask:0xf bank_mask:0xf bound_ctrl:1
	v_mov_b32_dpp v33, v17 row_shr:2 row_mask:0xf bank_mask:0xf bound_ctrl:1
	v_pk_fma_f32 v[16:17], v[44:45], v[32:33], v[16:17]
	v_mov_b32_dpp v50, v48 row_shr:4 row_mask:0xf bank_mask:0xf
	v_mov_b32_dpp v51, v49 row_shr:4 row_mask:0xf bank_mask:0xf
	v_mov_b32_dpp v32, v16 row_shr:4 row_mask:0xf bank_mask:0xf bound_ctrl:1
	v_mov_b32_dpp v33, v17 row_shr:4 row_mask:0xf bank_mask:0xf bound_ctrl:1
	v_pk_fma_f32 v[16:17], v[48:49], v[32:33], v[16:17]
	v_pk_mul_f32 v[50:51], v[48:49], v[50:51]
	v_add_f32_e32 v18, 1.0, v18
	v_mov_b32_dpp v32, v16 row_shr:8 row_mask:0xf bank_mask:0xf bound_ctrl:1
	v_mov_b32_dpp v33, v17 row_shr:8 row_mask:0xf bank_mask:0xf bound_ctrl:1
	v_pk_fma_f32 v[16:17], v[50:51], v[32:33], v[16:17]
	v_add_f32_e32 v32, v42, v46
	v_mul_f32_e32 v32, 0xbfb8aa3b, v32
	v_exp_f32_e32 v32, v32
	v_add_f32_e32 v19, 1.0, v19
	v_rcp_f32_e32 v18, v18
	v_rcp_f32_e32 v19, v19
	v_add_f32_e32 v32, 1.0, v32
	v_rcp_f32_e32 v32, v32
	v_mov_b32_e32 v46, 1.0
	v_pk_mul_f32 v[18:19], v[18:19], v[64:65]
	v_mov_b32_dpp v52, v50 row_shr:8 row_mask:0xf bank_mask:0xf
	v_mul_f32_e32 v32, 0xc1000000, v32
	v_mul_f32_e32 v32, v2, v32
	v_mul_f32_e32 v32, 0x3fb8aa3b, v32
	v_exp_f32_e32 v32, v32
	v_mov_b32_dpp v53, v51 row_shr:8 row_mask:0xf bank_mask:0xf
	v_pk_mul_f32 v[52:53], v[50:51], v[52:53]
	ds_bpermute_b32 v56, v1, v52
	v_fma_f32 v33, -v32, v32, 1.0
	v_sqrt_f32_e32 v44, v33
	v_add_f32_e32 v33, v43, v47
	v_mul_f32_e32 v33, 0xbfb8aa3b, v33
	v_exp_f32_e32 v33, v33
	v_mov_b32_e32 v47, 1.0
	v_mov_b32_dpp v46, v32 row_shr:1 row_mask:0xf bank_mask:0xf
	v_pk_fma_f32 v[16:17], v[52:53], 0, v[16:17] op_sel_hi:[1,0,1]
	v_add_f32_e32 v33, 1.0, v33
	v_rcp_f32_e32 v33, v33
	ds_bpermute_b32 v34, v1, v16
	ds_bpermute_b32 v35, v1, v17
	v_cvt_pk_bf16_f32 v16, v16, v17
	v_mul_f32_e32 v33, 0xc1000000, v33
	v_mul_f32_e32 v33, v59, v33
	v_mul_f32_e32 v33, 0x3fb8aa3b, v33
	v_exp_f32_e32 v33, v33
	ds_bpermute_b32 v57, v1, v53
	v_fma_f32 v45, -v33, v33, 1.0
	v_sqrt_f32_e32 v45, v45
	v_mov_b32_dpp v47, v33 row_shr:1 row_mask:0xf bank_mask:0xf
	v_pk_mul_f32 v[48:49], v[32:33], v[46:47]
; __device__ __forceinline__ unsigned pk2(float lo, float hi) { const f32x2_t v = {lo, hi}; const bf16x2_t b = __builtin_convertvector(v, bf16x2_t); return __builtin_bit_cast(unsigned, b); }
; __device__ __forceinline__ float sigmoidf_(float x) { return __builtin_amdgcn_rcpf(1.0f + __expf(-x)); }
; __device__ __forceinline__ float bcast15(float v, int lane) { return bperm_f((lane & 48) | 15, v); }
; __device__ __forceinline__ void w_lru_m1(const Args& a, int l, unsigned char* ws, const bf16_t* proj, bf16_t* y, LAS unsigned char* wl, int b, int ck_, int h, int lane) {
;     ...
;         for (int tb = 0; tb < 4; ++tb) { const int tok = 16 * tb + lo;
;             f32x4 ga = {0.f, 0.f, 0.f, 0.f}, gx = {0.f, 0.f, 0.f, 0.f};
; #pragma unroll
;             for (int kk = 0; kk < 2; ++kk) { ga = __builtin_amdgcn_mfma_f32_16x16x32_bf16(WaF[kk], Xf[tb][kk], ga, 0, 0, 0); gx = __builtin_amdgcn_mfma_f32_16x16x32_bf16(WxF[kk], Xf[tb][kk], gx, 0, 0, 0); }
;             float hv[4], pv[4];
; #pragma unroll
;             for (int r = 0; r < 4; ++r) {
;                 const float rg = sigmoidf_(ga[r] + bav[r]), ig = sigmoidf_(gx[r] + bxv[r]);
;                 const float la = -8.0f * rg * sp[r]; float A = __expf(la);
;                 float U = __builtin_amdgcn_sqrtf(1.0f - A * A) * (ig * xcf[tok * 65 + j0 + r]);
;                 { const float As = dpp_shr1<1>(A), Us = dpp_shr0<1>(U); U = A * Us + U; A = A * As; }
;                 { const float As = dpp_shr1<2>(A), Us = dpp_shr0<2>(U); U = A * Us + U; A = A * As; }
;                 { const float As = dpp_shr1<4>(A), Us = dpp_shr0<4>(U); U = A * Us + U; A = A * As; }
;                 { const float As = dpp_shr1<8>(A), Us = dpp_shr0<8>(U); U = A * Us + U; A = A * As; }
;                 const float hh = U + A * hc[r], PP = A * Pc[r];
;                 hc[r] = bcast15(hh, lane); Pc[r] = bcast15(PP, lane); hv[r] = hh; pv[r] = PP; }
;             *(unsigned long long*)(y + (size_t)(row0 + tok) * DM + 64 * h + j0) = (unsigned long long)pk2(hv[0], hv[1]) | ((unsigned long long)pk2(hv[2], hv[3]) << 32);
;             *(unsigned long long*)((bf16_t*)(ws + WS_P) + (size_t)(row0 + tok) * 512 + 64 * h + j0) = (unsigned long long)pk2(pv[0], pv[1]) | ((unsigned long long)pk2(pv[2], pv[3]) << 32);
	v_mov_b32_e32 v46, 1.0
	v_pk_mul_f32 v[18:19], v[44:45], v[18:19]
	v_mov_b32_e32 v47, 1.0
	v_mov_b32_dpp v46, v48 row_shr:2 row_mask:0xf bank_mask:0xf
	v_mov_b32_dpp v44, v18 row_shr:1 row_mask:0xf bank_mask:0xf bound_ctrl:1
	v_mov_b32_dpp v45, v19 row_shr:1 row_mask:0xf bank_mask:0xf bound_ctrl:1
	v_pk_fma_f32 v[18:19], v[32:33], v[44:45], v[18:19]
	v_mov_b32_dpp v47, v49 row_shr:2 row_mask:0xf bank_mask:0xf
	v_pk_mul_f32 v[50:51], v[48:49], v[46:47]
	v_mov_b32_dpp v32, v18 row_shr:2 row_mask:0xf bank_mask:0xf bound_ctrl:1
	v_mov_b32_dpp v33, v19 row_shr:2 row_mask:0xf bank_mask:0xf bound_ctrl:1
	v_mov_b32_e32 v46, 1.0
	v_mov_b32_e32 v47, 1.0
	v_pk_fma_f32 v[18:19], v[48:49], v[32:33], v[18:19]
	v_mov_b32_dpp v46, v50 row_shr:4 row_mask:0xf bank_mask:0xf
	v_mov_b32_dpp v47, v51 row_shr:4 row_mask:0xf bank_mask:0xf
	v_mov_b32_dpp v32, v18 row_shr:4 row_mask:0xf bank_mask:0xf bound_ctrl:1
	v_mov_b32_dpp v33, v19 row_shr:4 row_mask:0xf bank_mask:0xf bound_ctrl:1
	v_pk_mul_f32 v[54:55], v[50:51], v[46:47]
	v_mov_b32_e32 v46, 1.0
	v_mov_b32_e32 v47, 1.0
	v_pk_fma_f32 v[18:19], v[50:51], v[32:33], v[18:19]
	v_mov_b32_dpp v46, v54 row_shr:8 row_mask:0xf bank_mask:0xf
	v_mov_b32_dpp v47, v55 row_shr:8 row_mask:0xf bank_mask:0xf
	v_mov_b32_dpp v32, v18 row_shr:8 row_mask:0xf bank_mask:0xf bound_ctrl:1
	v_mov_b32_dpp v33, v19 row_shr:8 row_mask:0xf bank_mask:0xf bound_ctrl:1
	v_pk_mul_f32 v[62:63], v[54:55], v[46:47]
	v_pk_fma_f32 v[18:19], v[54:55], v[32:33], v[18:19]
	ds_bpermute_b32 v46, v1, v62
	v_pk_fma_f32 v[18:19], v[62:63], 0, v[18:19] op_sel_hi:[1,0,1]
	ds_bpermute_b32 v32, v1, v18
	v_cvt_pk_bf16_f32 v17, v18, v19
	v_mov_b64_e32 v[224:225], v[16:17]
	s_nop 1
	v_permlane16_swap_b32_e32 v222, v224
	v_permlane16_swap_b32_e32 v223, v225
	global_store_dwordx4 v[100:101], v[222:225], off offset:64
	v_cvt_pk_bf16_f32 v16, v52, v53
	v_cvt_pk_bf16_f32 v17, v62, v63
	ds_bpermute_b32 v33, v1, v19
	v_mov_b64_e32 v[228:229], v[16:17]
	s_nop 1
	v_permlane16_swap_b32_e32 v226, v228
	v_permlane16_swap_b32_e32 v227, v229
	global_store_dwordx4 v[102:103], v[226:229], off offset:64
	v_mfma_f32_16x16x32_bf16 v[16:19], v[68:71], v[12:15], 0
	ds_bpermute_b32 v47, v1, v63
	v_mfma_f32_16x16x32_bf16 v[12:15], v[72:75], v[12:15], 0
	v_mfma_f32_16x16x32_bf16 v[16:19], v[76:79], v[28:31], v[16:19]
	v_mfma_f32_16x16x32_bf16 v[12:15], v[80:83], v[28:31], v[12:15]
	s_nop 6
	v_add_f32_e32 v16, v40, v16
	v_mul_f32_e32 v16, 0xbfb8aa3b, v16
	v_exp_f32_e32 v16, v16
	v_add_f32_e32 v12, v36, v12
	v_mul_f32_e32 v12, 0xbfb8aa3b, v12
	v_exp_f32_e32 v12, v12
	v_add_f32_e32 v16, 1.0, v16
	v_rcp_f32_e32 v16, v16
	v_add_f32_e32 v13, v37, v13
	v_add_f32_e32 v12, 1.0, v12
	v_rcp_f32_e32 v28, v12
	v_mul_f32_e32 v12, 0xc1000000, v16
	v_add_f32_e32 v16, v41, v17
	v_mul_f32_e32 v16, 0xbfb8aa3b, v16
	v_exp_f32_e32 v16, v16
	v_mul_f32_e32 v13, 0xbfb8aa3b, v13
	v_exp_f32_e32 v13, v13
	v_mul_f32_e32 v12, v58, v12
	v_add_f32_e32 v16, 1.0, v16
	v_rcp_f32_e32 v16, v16
	v_add_f32_e32 v13, 1.0, v13
	v_rcp_f32_e32 v29, v13
	v_mul_f32_e32 v12, 0x3fb8aa3b, v12
	v_mul_f32_e32 v13, 0xc1000000, v16
	v_mul_f32_e32 v13, v60, v13
	v_mul_f32_e32 v13, 0x3fb8aa3b, v13
	v_exp_f32_e32 v30, v12
	v_exp_f32_e32 v31, v13
	v_add_f32_e32 v18, v42, v18
	v_add_f32_e32 v19, v43, v19
	v_fma_f32 v12, -v30, v30, 1.0
	v_fma_f32 v13, -v31, v31, 1.0
	v_sqrt_f32_e32 v44, v12
	v_mov_b32_e32 v12, 1.0
	v_sqrt_f32_e32 v45, v13
	v_mov_b32_e32 v13, 1.0
	v_mov_b32_dpp v12, v30 row_shr:1 row_mask:0xf bank_mask:0xf
	v_mul_f32_e32 v18, 0xbfb8aa3b, v18
	v_mov_b32_dpp v13, v31 row_shr:1 row_mask:0xf bank_mask:0xf
	v_pk_mul_f32 v[48:49], v[30:31], v[12:13]
	v_mov_b32_e32 v12, 1.0
	v_mov_b32_e32 v13, 1.0
	v_mul_f32_e32 v19, 0xbfb8aa3b, v19
	v_mov_b32_dpp v12, v48 row_shr:2 row_mask:0xf bank_mask:0xf
	v_mov_b32_dpp v13, v49 row_shr:2 row_mask:0xf bank_mask:0xf
	v_pk_mul_f32 v[50:51], v[48:49], v[12:13]
	v_mov_b32_e32 v12, 1.0
	v_mov_b32_e32 v13, 1.0
	v_exp_f32_e32 v18, v18
	v_mov_b32_dpp v12, v50 row_shr:4 row_mask:0xf bank_mask:0xf
	v_mov_b32_dpp v13, v51 row_shr:4 row_mask:0xf bank_mask:0xf
	v_pk_mul_f32 v[52:53], v[50:51], v[12:13]
	v_mov_b32_e32 v12, 1.0
	v_mov_b32_e32 v13, 1.0
	v_exp_f32_e32 v19, v19
	v_mov_b32_dpp v12, v52 row_shr:8 row_mask:0xf bank_mask:0xf
	v_mov_b32_dpp v13, v53 row_shr:8 row_mask:0xf bank_mask:0xf
	v_pk_mul_f32 v[54:55], v[52:53], v[12:13]
	v_add_u32_e32 v13, 0x1100, v145
	s_waitcnt lgkmcnt(0)
	v_pk_mul_f32 v[16:17], v[54:55], v[56:57]
	ds_read2_b32 v[56:57], v13 offset1:1
	v_add_f32_e32 v14, v38, v14
	v_add_f32_e32 v15, v39, v15
	v_mul_f32_e32 v14, 0xbfb8aa3b, v14
	v_mul_f32_e32 v15, 0xbfb8aa3b, v15
	s_waitcnt lgkmcnt(0)
; __device__ __forceinline__ unsigned pk2(float lo, float hi) { const f32x2_t v = {lo, hi}; const bf16x2_t b = __builtin_convertvector(v, bf16x2_t); return __builtin_bit_cast(unsigned, b); }
; __device__ __forceinline__ float sigmoidf_(float x) { return __builtin_amdgcn_rcpf(1.0f + __expf(-x)); }
; __device__ __forceinline__ float bcast15(float v, int lane) { return bperm_f((lane & 48) | 15, v); }
; __device__ __forceinline__ void w_lru_m1(const Args& a, int l, unsigned char* ws, const bf16_t* proj, bf16_t* y, LAS unsigned char* wl, int b, int ck_, int h, int lane) {
;     ...
;         for (int tb = 0; tb < 4; ++tb) { const int tok = 16 * tb + lo;
;             f32x4 ga = {0.f, 0.f, 0.f, 0.f}, gx = {0.f, 0.f, 0.f, 0.f};
; #pragma unroll
;             for (int kk = 0; kk < 2; ++kk) { ga = __builtin_amdgcn_mfma_f32_16x16x32_bf16(WaF[kk], Xf[tb][kk], ga, 0, 0, 0); gx = __builtin_amdgcn_mfma_f32_16x16x32_bf16(WxF[kk], Xf[tb][kk], gx, 0, 0, 0); }
;             float hv[4], pv[4];
; #pragma unroll
;             for (int r = 0; r < 4; ++r) {
;                 const float rg = sigmoidf_(ga[r] + bav[r]), ig = sigmoidf_(gx[r] + bxv[r]);
;                 const float la = -8.0f * rg * sp[r]; float A = __expf(la);
;                 float U = __builtin_amdgcn_sqrtf(1.0f - A * A) * (ig * xcf[tok * 65 + j0 + r]);
;                 { const float As = dpp_shr1<1>(A), Us = dpp_shr0<1>(U); U = A * Us + U; A = A * As; }
;                 { const float As = dpp_shr1<2>(A), Us = dpp_shr0<2>(U); U = A * Us + U; A = A * As; }
;                 { const float As = dpp_shr1<4>(A), Us = dpp_shr0<4>(U); U = A * Us + U; A = A * As; }
;                 { const float As = dpp_shr1<8>(A), Us = dpp_shr0<8>(U); U = A * Us + U; A = A * As; }
;                 const float hh = U + A * hc[r], PP = A * Pc[r];
;                 hc[r] = bcast15(hh, lane); Pc[r] = bcast15(PP, lane); hv[r] = hh; pv[r] = PP; }
;             *(unsigned long long*)(y + (size_t)(row0 + tok) * DM + 64 * h + j0) = (unsigned long long)pk2(hv[0], hv[1]) | ((unsigned long long)pk2(hv[2], hv[3]) << 32);
;             *(unsigned long long*)((bf16_t*)(ws + WS_P) + (size_t)(row0 + tok) * 512 + 64 * h + j0) = (unsigned long long)pk2(pv[0], pv[1]) | ((unsigned long long)pk2(pv[2], pv[3]) << 32);
	v_pk_mul_f32 v[28:29], v[56:57], v[28:29]
	v_add_f32_e32 v18, 1.0, v18
	v_pk_mul_f32 v[28:29], v[28:29], v[44:45]
	v_exp_f32_e32 v14, v14
	v_add_f32_e32 v19, 1.0, v19
	v_mov_b32_dpp v44, v28 row_shr:1 row_mask:0xf bank_mask:0xf bound_ctrl:1
	v_mov_b32_dpp v45, v29 row_shr:1 row_mask:0xf bank_mask:0xf bound_ctrl:1
	v_pk_fma_f32 v[28:29], v[30:31], v[44:45], v[28:29]
	v_exp_f32_e32 v15, v15
	v_rcp_f32_e32 v18, v18
	v_mov_b32_dpp v30, v28 row_shr:2 row_mask:0xf bank_mask:0xf bound_ctrl:1
	v_mov_b32_dpp v31, v29 row_shr:2 row_mask:0xf bank_mask:0xf bound_ctrl:1
	v_pk_fma_f32 v[28:29], v[48:49], v[30:31], v[28:29]
	v_rcp_f32_e32 v19, v19
	v_add_f32_e32 v14, 1.0, v14
	v_mov_b32_dpp v30, v28 row_shr:4 row_mask:0xf bank_mask:0xf bound_ctrl:1
	v_mov_b32_dpp v31, v29 row_shr:4 row_mask:0xf bank_mask:0xf bound_ctrl:1
	v_pk_fma_f32 v[28:29], v[50:51], v[30:31], v[28:29]
	v_add_f32_e32 v15, 1.0, v15
	ds_bpermute_b32 v12, v1, v16
	v_mov_b32_dpp v30, v28 row_shr:8 row_mask:0xf bank_mask:0xf bound_ctrl:1
	v_mov_b32_dpp v31, v29 row_shr:8 row_mask:0xf bank_mask:0xf bound_ctrl:1
	v_pk_fma_f32 v[28:29], v[52:53], v[30:31], v[28:29]
	ds_bpermute_b32 v13, v1, v17
	v_pk_fma_f32 v[30:31], v[54:55], v[34:35], v[28:29]
	v_rcp_f32_e32 v34, v14
	v_mul_f32_e32 v14, 0xc1000000, v18
	v_rcp_f32_e32 v35, v15
	v_mul_f32_e32 v15, 0xc1000000, v19
	v_mul_f32_e32 v14, v2, v14
	v_mul_f32_e32 v15, v59, v15
	v_mul_f32_e32 v14, 0x3fb8aa3b, v14
	v_mul_f32_e32 v15, 0x3fb8aa3b, v15
	v_exp_f32_e32 v18, v14
	v_exp_f32_e32 v19, v15
	ds_bpermute_b32 v28, v1, v30
	ds_bpermute_b32 v29, v1, v31
	v_fma_f32 v14, -v18, v18, 1.0
	v_fma_f32 v15, -v19, v19, 1.0
	v_sqrt_f32_e32 v44, v14
	v_mov_b32_e32 v14, 1.0
	v_sqrt_f32_e32 v45, v15
	v_mov_b32_e32 v15, 1.0
	v_mov_b32_dpp v14, v18 row_shr:1 row_mask:0xf bank_mask:0xf
	v_cvt_pk_bf16_f32 v30, v30, v31
	v_mov_b32_dpp v15, v19 row_shr:1 row_mask:0xf bank_mask:0xf
	v_pk_mul_f32 v[48:49], v[18:19], v[14:15]
	v_mov_b32_e32 v14, 1.0
	v_mov_b32_e32 v15, 1.0
	v_cvt_pk_bf16_f32 v16, v16, v17
	v_mov_b32_dpp v14, v48 row_shr:2 row_mask:0xf bank_mask:0xf
	v_mov_b32_dpp v15, v49 row_shr:2 row_mask:0xf bank_mask:0xf
	v_pk_mul_f32 v[50:51], v[48:49], v[14:15]
	v_mov_b32_e32 v14, 1.0
	v_mov_b32_e32 v15, 1.0
	s_nop 0
	v_mov_b32_dpp v14, v50 row_shr:4 row_mask:0xf bank_mask:0xf
	v_mov_b32_dpp v15, v51 row_shr:4 row_mask:0xf bank_mask:0xf
	v_pk_mul_f32 v[52:53], v[50:51], v[14:15]
	v_mov_b32_e32 v14, 1.0
	v_mov_b32_e32 v15, 1.0
	s_nop 0
	v_mov_b32_dpp v14, v52 row_shr:8 row_mask:0xf bank_mask:0xf
	v_mov_b32_dpp v15, v53 row_shr:8 row_mask:0xf bank_mask:0xf
	v_pk_mul_f32 v[54:55], v[52:53], v[14:15]
	v_add_u32_e32 v15, 0x1108, v145
	ds_read2_b32 v[56:57], v15 offset1:1
	v_pk_mul_f32 v[46:47], v[54:55], v[46:47]
	ds_bpermute_b32 v14, v1, v46
	v_cvt_pk_bf16_f32 v17, v46, v47
	ds_bpermute_b32 v15, v1, v47
	s_waitcnt lgkmcnt(0)
	v_pk_mul_f32 v[34:35], v[34:35], v[56:57]
	s_nop 0
	v_pk_mul_f32 v[34:35], v[44:45], v[34:35]
	s_nop 1
	v_mov_b32_dpp v44, v34 row_shr:1 row_mask:0xf bank_mask:0xf bound_ctrl:1
	v_mov_b32_dpp v45, v35 row_shr:1 row_mask:0xf bank_mask:0xf bound_ctrl:1
	v_pk_fma_f32 v[18:19], v[18:19], v[44:45], v[34:35]
	s_nop 1
	v_mov_b32_dpp v34, v18 row_shr:2 row_mask:0xf bank_mask:0xf bound_ctrl:1
	v_mov_b32_dpp v35, v19 row_shr:2 row_mask:0xf bank_mask:0xf bound_ctrl:1
	v_pk_fma_f32 v[18:19], v[48:49], v[34:35], v[18:19]
	s_nop 1
	v_mov_b32_dpp v34, v18 row_shr:4 row_mask:0xf bank_mask:0xf bound_ctrl:1
	v_mov_b32_dpp v35, v19 row_shr:4 row_mask:0xf bank_mask:0xf bound_ctrl:1
	v_pk_fma_f32 v[18:19], v[50:51], v[34:35], v[18:19]
	s_nop 1
	v_mov_b32_dpp v34, v18 row_shr:8 row_mask:0xf bank_mask:0xf bound_ctrl:1
	v_mov_b32_dpp v35, v19 row_shr:8 row_mask:0xf bank_mask:0xf bound_ctrl:1
	v_pk_fma_f32 v[18:19], v[52:53], v[34:35], v[18:19]
	s_nop 0
	v_pk_fma_f32 v[32:33], v[54:55], v[32:33], v[18:19]
	ds_bpermute_b32 v18, v1, v32
	v_cvt_pk_bf16_f32 v31, v32, v33
	ds_bpermute_b32 v19, v1, v33
	v_mov_b64_e32 v[232:233], v[30:31]
	s_nop 1
	v_permlane16_swap_b32_e32 v230, v232
	v_permlane16_swap_b32_e32 v231, v233
	global_store_dwordx4 v[104:105], v[230:233], off offset:64
	v_mfma_f32_16x16x32_bf16 v[30:33], v[68:71], v[8:11], 0
	v_mov_b64_e32 v[236:237], v[16:17]
	s_nop 1
	v_permlane16_swap_b32_e32 v234, v236
	v_permlane16_swap_b32_e32 v235, v237
	global_store_dwordx4 v[106:107], v[234:237], off offset:64
	v_mfma_f32_16x16x32_bf16 v[8:11], v[72:75], v[8:11], 0
	v_mfma_f32_16x16x32_bf16 v[30:33], v[76:79], v[24:27], v[30:33]
	v_mfma_f32_16x16x32_bf16 v[24:27], v[80:83], v[24:27], v[8:11]
	s_nop 6
	v_add_f32_e32 v8, v40, v30
	v_add_f32_e32 v9, v36, v24
	v_mul_f32_e32 v9, 0xbfb8aa3b, v9
	v_exp_f32_e32 v9, v9
	v_mul_f32_e32 v8, 0xbfb8aa3b, v8
	v_exp_f32_e32 v8, v8
	v_add_f32_e32 v11, v37, v25
	v_add_f32_e32 v9, 1.0, v9
	v_rcp_f32_e32 v10, v9
	v_add_f32_e32 v9, v41, v31
	v_mul_f32_e32 v9, 0xbfb8aa3b, v9
	v_exp_f32_e32 v9, v9
	v_add_f32_e32 v8, 1.0, v8
	v_rcp_f32_e32 v8, v8
	v_mul_f32_e32 v11, 0xbfb8aa3b, v11
	v_add_f32_e32 v9, 1.0, v9
	v_rcp_f32_e32 v9, v9
	v_mul_f32_e32 v8, 0xc1000000, v8
	v_mul_f32_e32 v8, v58, v8
	v_mul_f32_e32 v8, 0x3fb8aa3b, v8
	v_mul_f32_e32 v9, 0xc1000000, v9
	v_mul_f32_e32 v9, v60, v9
	v_mul_f32_e32 v9, 0x3fb8aa3b, v9
	v_exp_f32_e32 v16, v8
	v_exp_f32_e32 v17, v9
	v_exp_f32_e32 v11, v11
	v_fma_f32 v8, -v16, v16, 1.0
	v_fma_f32 v9, -v17, v17, 1.0
	v_sqrt_f32_e32 v30, v8
	v_mov_b32_e32 v8, 1.0
	v_sqrt_f32_e32 v31, v9
	v_mov_b32_e32 v9, 1.0
	v_mov_b32_dpp v8, v16 row_shr:1 row_mask:0xf bank_mask:0xf
	v_add_f32_e32 v11, 1.0, v11
	v_mov_b32_dpp v9, v17 row_shr:1 row_mask:0xf bank_mask:0xf
	v_pk_mul_f32 v[34:35], v[16:17], v[8:9]
	v_mov_b32_e32 v8, 1.0
	v_mov_b32_e32 v9, 1.0
	v_rcp_f32_e32 v11, v11
	v_mov_b32_dpp v8, v34 row_shr:2 row_mask:0xf bank_mask:0xf
	v_mov_b32_dpp v9, v35 row_shr:2 row_mask:0xf bank_mask:0xf
	v_pk_mul_f32 v[44:45], v[34:35], v[8:9]
	v_mov_b32_e32 v8, 1.0
	v_mov_b32_e32 v9, 1.0
	s_nop 0
	v_mov_b32_dpp v8, v44 row_shr:4 row_mask:0xf bank_mask:0xf
	v_mov_b32_dpp v9, v45 row_shr:4 row_mask:0xf bank_mask:0xf
	v_pk_mul_f32 v[46:47], v[44:45], v[8:9]
	v_mov_b32_e32 v8, 1.0
	v_mov_b32_e32 v9, 1.0
	s_nop 0
	v_mov_b32_dpp v8, v46 row_shr:8 row_mask:0xf bank_mask:0xf
	v_mov_b32_dpp v9, v47 row_shr:8 row_mask:0xf bank_mask:0xf
	v_pk_mul_f32 v[48:49], v[46:47], v[8:9]
	s_nop 0
	v_pk_mul_f32 v[8:9], v[48:49], v[12:13]
	v_add_u32_e32 v12, 0x2140, v145
	ds_read2_b32 v[12:13], v12 offset1:1
	ds_bpermute_b32 v24, v1, v8
	ds_bpermute_b32 v25, v1, v9
	v_cvt_pk_bf16_f32 v8, v8, v9
	s_waitcnt lgkmcnt(0)
; __device__ __forceinline__ unsigned pk2(float lo, float hi) { const f32x2_t v = {lo, hi}; const bf16x2_t b = __builtin_convertvector(v, bf16x2_t); return __builtin_bit_cast(unsigned, b); }
; __device__ __forceinline__ float sigmoidf_(float x) { return __builtin_amdgcn_rcpf(1.0f + __expf(-x)); }
; __device__ __forceinline__ float bcast15(float v, int lane) { return bperm_f((lane & 48) | 15, v); }
; __device__ __forceinline__ void w_lru_m1(const Args& a, int l, unsigned char* ws, const bf16_t* proj, bf16_t* y, LAS unsigned char* wl, int b, int ck_, int h, int lane) {
;     ...
;         for (int tb = 0; tb < 4; ++tb) { const int tok = 16 * tb + lo;
;             f32x4 ga = {0.f, 0.f, 0.f, 0.f}, gx = {0.f, 0.f, 0.f, 0.f};
; #pragma unroll
;             for (int kk = 0; kk < 2; ++kk) { ga = __builtin_amdgcn_mfma_f32_16x16x32_bf16(WaF[kk], Xf[tb][kk], ga, 0, 0, 0); gx = __builtin_amdgcn_mfma_f32_16x16x32_bf16(WxF[kk], Xf[tb][kk], gx, 0, 0, 0); }
;             float hv[4], pv[4];
; #pragma unroll
;             for (int r = 0; r < 4; ++r) {
;                 const float rg = sigmoidf_(ga[r] + bav[r]), ig = sigmoidf_(gx[r] + bxv[r]);
;                 const float la = -8.0f * rg * sp[r]; float A = __expf(la);
;                 float U = __builtin_amdgcn_sqrtf(1.0f - A * A) * (ig * xcf[tok * 65 + j0 + r]);
;                 { const float As = dpp_shr1<1>(A), Us = dpp_shr0<1>(U); U = A * Us + U; A = A * As; }
;                 { const float As = dpp_shr1<2>(A), Us = dpp_shr0<2>(U); U = A * Us + U; A = A * As; }
;                 { const float As = dpp_shr1<4>(A), Us = dpp_shr0<4>(U); U = A * Us + U; A = A * As; }
;                 { const float As = dpp_shr1<8>(A), Us = dpp_shr0<8>(U); U = A * Us + U; A = A * As; }
;                 const float hh = U + A * hc[r], PP = A * Pc[r];
;                 hc[r] = bcast15(hh, lane); Pc[r] = bcast15(PP, lane); hv[r] = hh; pv[r] = PP; }
;             *(unsigned long long*)(y + (size_t)(row0 + tok) * DM + 64 * h + j0) = (unsigned long long)pk2(hv[0], hv[1]) | ((unsigned long long)pk2(hv[2], hv[3]) << 32);
;             *(unsigned long long*)((bf16_t*)(ws + WS_P) + (size_t)(row0 + tok) * 512 + 64 * h + j0) = (unsigned long long)pk2(pv[0], pv[1]) | ((unsigned long long)pk2(pv[2], pv[3]) << 32);
	v_pk_mul_f32 v[10:11], v[12:13], v[10:11]
	s_nop 0
	v_pk_mul_f32 v[10:11], v[10:11], v[30:31]
	v_mov_b32_e32 v30, 1.0
	v_mov_b32_e32 v31, 1.0
	v_mov_b32_dpp v12, v10 row_shr:1 row_mask:0xf bank_mask:0xf bound_ctrl:1
	v_mov_b32_dpp v13, v11 row_shr:1 row_mask:0xf bank_mask:0xf bound_ctrl:1
	v_pk_fma_f32 v[10:11], v[16:17], v[12:13], v[10:11]
	s_nop 1
	v_mov_b32_dpp v12, v10 row_shr:2 row_mask:0xf bank_mask:0xf bound_ctrl:1
	v_mov_b32_dpp v13, v11 row_shr:2 row_mask:0xf bank_mask:0xf bound_ctrl:1
	v_pk_fma_f32 v[10:11], v[34:35], v[12:13], v[10:11]
	s_nop 1
	v_mov_b32_dpp v12, v10 row_shr:4 row_mask:0xf bank_mask:0xf bound_ctrl:1
	v_mov_b32_dpp v13, v11 row_shr:4 row_mask:0xf bank_mask:0xf bound_ctrl:1
	v_pk_fma_f32 v[10:11], v[44:45], v[12:13], v[10:11]
	s_nop 1
	v_mov_b32_dpp v12, v10 row_shr:8 row_mask:0xf bank_mask:0xf bound_ctrl:1
	v_mov_b32_dpp v13, v11 row_shr:8 row_mask:0xf bank_mask:0xf bound_ctrl:1
	v_pk_fma_f32 v[10:11], v[46:47], v[12:13], v[10:11]
	v_add_f32_e32 v12, v42, v32
	v_mul_f32_e32 v12, 0xbfb8aa3b, v12
	v_exp_f32_e32 v12, v12
	v_pk_fma_f32 v[10:11], v[48:49], v[28:29], v[10:11]
	v_mov_b32_e32 v32, 1.0
	ds_bpermute_b32 v16, v1, v10
	v_add_f32_e32 v12, 1.0, v12
	v_rcp_f32_e32 v13, v12
	v_add_f32_e32 v12, v38, v26
	v_mul_f32_e32 v12, 0xbfb8aa3b, v12
	v_exp_f32_e32 v12, v12
	v_mul_f32_e32 v13, 0xc1000000, v13
	v_mul_f32_e32 v13, v2, v13
	v_mul_f32_e32 v13, 0x3fb8aa3b, v13
	v_exp_f32_e32 v26, v13
	v_add_f32_e32 v12, 1.0, v12
	v_rcp_f32_e32 v12, v12
	ds_bpermute_b32 v17, v1, v11
	v_fma_f32 v13, -v26, v26, 1.0
	v_sqrt_f32_e32 v28, v13
	v_add_f32_e32 v13, v43, v33
	v_mul_f32_e32 v13, 0xbfb8aa3b, v13
	v_exp_f32_e32 v13, v13
	v_mov_b32_dpp v30, v26 row_shr:1 row_mask:0xf bank_mask:0xf
	v_mov_b32_e32 v33, 1.0
	v_cvt_pk_bf16_f32 v10, v10, v11
	v_add_f32_e32 v13, 1.0, v13
	v_rcp_f32_e32 v29, v13
	v_add_f32_e32 v13, v39, v27
	v_mul_f32_e32 v13, 0xbfb8aa3b, v13
	v_exp_f32_e32 v13, v13
	v_mul_f32_e32 v27, 0xc1000000, v29
	v_mul_f32_e32 v27, v59, v27
	v_mul_f32_e32 v27, 0x3fb8aa3b, v27
	v_exp_f32_e32 v27, v27
	v_add_f32_e32 v13, 1.0, v13
	v_rcp_f32_e32 v13, v13
	v_mov_b32_dpp v31, v27 row_shr:1 row_mask:0xf bank_mask:0xf
	v_pk_mul_f32 v[30:31], v[26:27], v[30:31]
	v_fma_f32 v29, -v27, v27, 1.0
	v_sqrt_f32_e32 v29, v29
	v_mov_b32_dpp v32, v30 row_shr:2 row_mask:0xf bank_mask:0xf
	v_mov_b32_dpp v33, v31 row_shr:2 row_mask:0xf bank_mask:0xf
	v_pk_mul_f32 v[34:35], v[30:31], v[32:33]
	v_mov_b32_e32 v32, 1.0
	v_mov_b32_e32 v33, 1.0
	s_nop 0
	v_mov_b32_dpp v32, v34 row_shr:4 row_mask:0xf bank_mask:0xf
	v_mov_b32_dpp v33, v35 row_shr:4 row_mask:0xf bank_mask:0xf
	v_pk_mul_f32 v[44:45], v[34:35], v[32:33]
	v_mov_b32_e32 v32, 1.0
	v_mov_b32_e32 v33, 1.0
	s_nop 0
	v_mov_b32_dpp v32, v44 row_shr:8 row_mask:0xf bank_mask:0xf
	v_mov_b32_dpp v33, v45 row_shr:8 row_mask:0xf bank_mask:0xf
	v_pk_mul_f32 v[46:47], v[44:45], v[32:33]
	v_add_u32_e32 v33, 0x2148, v145
	ds_read2_b32 v[48:49], v33 offset1:1
	v_pk_mul_f32 v[14:15], v[46:47], v[14:15]
	ds_bpermute_b32 v32, v1, v14
	v_cvt_pk_bf16_f32 v9, v14, v15
	ds_bpermute_b32 v33, v1, v15
	s_waitcnt lgkmcnt(0)
	v_pk_mul_f32 v[12:13], v[12:13], v[48:49]
	s_nop 0
	v_pk_mul_f32 v[12:13], v[28:29], v[12:13]
	s_nop 1
	v_mov_b32_dpp v28, v12 row_shr:1 row_mask:0xf bank_mask:0xf bound_ctrl:1
	v_mov_b32_dpp v29, v13 row_shr:1 row_mask:0xf bank_mask:0xf bound_ctrl:1
	v_pk_fma_f32 v[12:13], v[26:27], v[28:29], v[12:13]
	s_nop 1
	v_mov_b32_dpp v26, v12 row_shr:2 row_mask:0xf bank_mask:0xf bound_ctrl:1
	v_mov_b32_dpp v27, v13 row_shr:2 row_mask:0xf bank_mask:0xf bound_ctrl:1
	v_pk_fma_f32 v[12:13], v[30:31], v[26:27], v[12:13]
	s_nop 1
	v_mov_b32_dpp v26, v12 row_shr:4 row_mask:0xf bank_mask:0xf bound_ctrl:1
	v_mov_b32_dpp v27, v13 row_shr:4 row_mask:0xf bank_mask:0xf bound_ctrl:1
	v_pk_fma_f32 v[12:13], v[34:35], v[26:27], v[12:13]
	s_nop 1
	v_mov_b32_dpp v26, v12 row_shr:8 row_mask:0xf bank_mask:0xf bound_ctrl:1
	v_mov_b32_dpp v27, v13 row_shr:8 row_mask:0xf bank_mask:0xf bound_ctrl:1
	v_pk_fma_f32 v[12:13], v[44:45], v[26:27], v[12:13]
	s_nop 0
	v_pk_fma_f32 v[18:19], v[46:47], v[18:19], v[12:13]
	ds_bpermute_b32 v12, v1, v18
	v_cvt_pk_bf16_f32 v11, v18, v19
	v_mov_b64_e32 v[240:241], v[10:11]
	s_nop 1
	v_permlane16_swap_b32_e32 v238, v240
	v_permlane16_swap_b32_e32 v239, v241
	global_store_dwordx4 v[96:97], v[238:241], off offset:64
	v_mov_b64_e32 v[244:245], v[8:9]
	s_nop 1
	v_permlane16_swap_b32_e32 v242, v244
	v_permlane16_swap_b32_e32 v243, v245
	global_store_dwordx4 v[98:99], v[242:245], off offset:64
	v_mfma_f32_16x16x32_bf16 v[8:11], v[68:71], v[4:7], 0
	ds_bpermute_b32 v13, v1, v19
	v_mfma_f32_16x16x32_bf16 v[4:7], v[72:75], v[4:7], 0
	v_mfma_f32_16x16x32_bf16 v[8:11], v[76:79], v[20:23], v[8:11]
	v_mfma_f32_16x16x32_bf16 v[4:7], v[80:83], v[20:23], v[4:7]
	s_nop 6
	v_add_f32_e32 v8, v40, v8
	v_mul_f32_e32 v8, 0xbfb8aa3b, v8
	v_exp_f32_e32 v8, v8
	v_add_f32_e32 v4, v36, v4
	v_add_f32_e32 v9, v41, v9
	v_mul_f32_e32 v4, 0xbfb8aa3b, v4
	v_mul_f32_e32 v9, 0xbfb8aa3b, v9
	v_add_f32_e32 v8, 1.0, v8
	v_exp_f32_e32 v4, v4
	v_exp_f32_e32 v9, v9
	v_rcp_f32_e32 v14, v8
	v_add_f32_e32 v5, v37, v5
	v_mul_f32_e32 v5, 0xbfb8aa3b, v5
	v_add_f32_e32 v4, 1.0, v4
	v_add_f32_e32 v9, 1.0, v9
	v_exp_f32_e32 v5, v5
	v_rcp_f32_e32 v8, v4
	v_mul_f32_e32 v4, 0xc1000000, v14
	v_rcp_f32_e32 v14, v9
	v_add_f32_e32 v5, 1.0, v5
	v_rcp_f32_e32 v9, v5
	v_mul_f32_e32 v4, v58, v4
	v_mul_f32_e32 v5, 0xc1000000, v14
	v_mul_f32_e32 v5, v60, v5
	v_mul_f32_e32 v4, 0x3fb8aa3b, v4
	v_mul_f32_e32 v5, 0x3fb8aa3b, v5
	v_exp_f32_e32 v18, v4
	v_exp_f32_e32 v19, v5
	v_add_f32_e32 v10, v42, v10
	v_mul_f32_e32 v10, 0xbfb8aa3b, v10
	v_fma_f32 v4, -v18, v18, 1.0
	v_fma_f32 v5, -v19, v19, 1.0
	v_sqrt_f32_e32 v20, v4
	v_mov_b32_e32 v4, 1.0
	v_sqrt_f32_e32 v21, v5
	v_mov_b32_e32 v5, 1.0
	v_mov_b32_dpp v4, v18 row_shr:1 row_mask:0xf bank_mask:0xf
	v_exp_f32_e32 v10, v10
	v_mov_b32_dpp v5, v19 row_shr:1 row_mask:0xf bank_mask:0xf
	v_pk_mul_f32 v[22:23], v[18:19], v[4:5]
	v_mov_b32_e32 v4, 1.0
	v_mov_b32_e32 v5, 1.0
	v_add_f32_e32 v6, v38, v6
	v_mov_b32_dpp v4, v22 row_shr:2 row_mask:0xf bank_mask:0xf
	v_mov_b32_dpp v5, v23 row_shr:2 row_mask:0xf bank_mask:0xf
	v_pk_mul_f32 v[26:27], v[22:23], v[4:5]
	v_mov_b32_e32 v4, 1.0
	v_mov_b32_e32 v5, 1.0
	v_mul_f32_e32 v6, 0xbfb8aa3b, v6
	v_mov_b32_dpp v4, v26 row_shr:4 row_mask:0xf bank_mask:0xf
	v_mov_b32_dpp v5, v27 row_shr:4 row_mask:0xf bank_mask:0xf
	v_pk_mul_f32 v[28:29], v[26:27], v[4:5]
	v_mov_b32_e32 v4, 1.0
	v_mov_b32_e32 v5, 1.0
	v_add_f32_e32 v10, 1.0, v10
	v_mov_b32_dpp v4, v28 row_shr:8 row_mask:0xf bank_mask:0xf
	v_mov_b32_dpp v5, v29 row_shr:8 row_mask:0xf bank_mask:0xf
	v_pk_mul_f32 v[30:31], v[28:29], v[4:5]
	v_add_u32_e32 v5, 0x3180, v145
	v_pk_mul_f32 v[14:15], v[30:31], v[24:25]
	ds_read2_b32 v[24:25], v5 offset1:1
	v_exp_f32_e32 v6, v6
	v_rcp_f32_e32 v10, v10
	v_add_f32_e32 v7, v39, v7
	v_mul_f32_e32 v7, 0xbfb8aa3b, v7
	s_waitcnt lgkmcnt(0)
; __device__ __forceinline__ unsigned pk2(float lo, float hi) { const f32x2_t v = {lo, hi}; const bf16x2_t b = __builtin_convertvector(v, bf16x2_t); return __builtin_bit_cast(unsigned, b); }
; __device__ __forceinline__ float sigmoidf_(float x) { return __builtin_amdgcn_rcpf(1.0f + __expf(-x)); }
; __device__ __forceinline__ void w_lru_m1(const Args& a, int l, unsigned char* ws, const bf16_t* proj, bf16_t* y, LAS unsigned char* wl, int b, int ck_, int h, int lane) {
;     ...
;         for (int tb = 0; tb < 4; ++tb) { const int tok = 16 * tb + lo;
;             f32x4 ga = {0.f, 0.f, 0.f, 0.f}, gx = {0.f, 0.f, 0.f, 0.f};
; #pragma unroll
;             for (int kk = 0; kk < 2; ++kk) { ga = __builtin_amdgcn_mfma_f32_16x16x32_bf16(WaF[kk], Xf[tb][kk], ga, 0, 0, 0); gx = __builtin_amdgcn_mfma_f32_16x16x32_bf16(WxF[kk], Xf[tb][kk], gx, 0, 0, 0); }
;             float hv[4], pv[4];
; #pragma unroll
;             for (int r = 0; r < 4; ++r) {
;                 const float rg = sigmoidf_(ga[r] + bav[r]), ig = sigmoidf_(gx[r] + bxv[r]);
;                 const float la = -8.0f * rg * sp[r]; float A = __expf(la);
;                 float U = __builtin_amdgcn_sqrtf(1.0f - A * A) * (ig * xcf[tok * 65 + j0 + r]);
;                 { const float As = dpp_shr1<1>(A), Us = dpp_shr0<1>(U); U = A * Us + U; A = A * As; }
;                 { const float As = dpp_shr1<2>(A), Us = dpp_shr0<2>(U); U = A * Us + U; A = A * As; }
;                 { const float As = dpp_shr1<4>(A), Us = dpp_shr0<4>(U); U = A * Us + U; A = A * As; }
;                 { const float As = dpp_shr1<8>(A), Us = dpp_shr0<8>(U); U = A * Us + U; A = A * As; }
;                 const float hh = U + A * hc[r], PP = A * Pc[r];
;                 hc[r] = bcast15(hh, lane); Pc[r] = bcast15(PP, lane); hv[r] = hh; pv[r] = PP; }
;             *(unsigned long long*)(y + (size_t)(row0 + tok) * DM + 64 * h + j0) = (unsigned long long)pk2(hv[0], hv[1]) | ((unsigned long long)pk2(hv[2], hv[3]) << 32);
;             *(unsigned long long*)((bf16_t*)(ws + WS_P) + (size_t)(row0 + tok) * 512 + 64 * h + j0) = (unsigned long long)pk2(pv[0], pv[1]) | ((unsigned long long)pk2(pv[2], pv[3]) << 32);
;         }
;         if (lo == 0) { const size_t so = (size_t)(b * NCH + ck_) * 512 + 64 * h + j0;
; #pragma unroll
;             for (int r = 0; r < 4; ++r) { ((float*)(ws + WS_LRUA))[so + r] = Pc[r]; ((float*)(ws + WS_LRUH))[so + r] = hc[r]; } }
	v_pk_mul_f32 v[8:9], v[24:25], v[8:9]
	v_add_f32_e32 v6, 1.0, v6
	v_pk_mul_f32 v[8:9], v[8:9], v[20:21]
	v_exp_f32_e32 v7, v7
	ds_bpermute_b32 v4, v1, v14
	v_mov_b32_dpp v20, v8 row_shr:1 row_mask:0xf bank_mask:0xf bound_ctrl:1
	v_mov_b32_dpp v21, v9 row_shr:1 row_mask:0xf bank_mask:0xf bound_ctrl:1
	v_pk_fma_f32 v[8:9], v[18:19], v[20:21], v[8:9]
	v_add_f32_e32 v7, 1.0, v7
	ds_bpermute_b32 v5, v1, v15
	v_mov_b32_dpp v18, v8 row_shr:2 row_mask:0xf bank_mask:0xf bound_ctrl:1
	v_mov_b32_dpp v19, v9 row_shr:2 row_mask:0xf bank_mask:0xf bound_ctrl:1
	v_pk_fma_f32 v[8:9], v[22:23], v[18:19], v[8:9]
	s_nop 1
	v_mov_b32_dpp v18, v8 row_shr:4 row_mask:0xf bank_mask:0xf bound_ctrl:1
	v_mov_b32_dpp v19, v9 row_shr:4 row_mask:0xf bank_mask:0xf bound_ctrl:1
	v_pk_fma_f32 v[8:9], v[26:27], v[18:19], v[8:9]
	s_nop 1
	v_mov_b32_dpp v18, v8 row_shr:8 row_mask:0xf bank_mask:0xf bound_ctrl:1
	v_mov_b32_dpp v19, v9 row_shr:8 row_mask:0xf bank_mask:0xf bound_ctrl:1
	v_pk_fma_f32 v[8:9], v[28:29], v[18:19], v[8:9]
	v_rcp_f32_e32 v18, v6
	v_mul_f32_e32 v6, 0xc1000000, v10
	v_mul_f32_e32 v2, v2, v6
	v_mul_f32_e32 v2, 0x3fb8aa3b, v2
	v_exp_f32_e32 v10, v2
	v_mov_b32_e32 v6, 1.0
	v_rcp_f32_e32 v19, v7
	v_mov_b32_e32 v7, 1.0
	v_fma_f32 v2, -v10, v10, 1.0
	v_sqrt_f32_e32 v20, v2
	v_add_f32_e32 v2, v43, v11
	v_mul_f32_e32 v2, 0xbfb8aa3b, v2
	v_exp_f32_e32 v2, v2
	v_mov_b32_dpp v6, v10 row_shr:1 row_mask:0xf bank_mask:0xf
	v_pk_fma_f32 v[16:17], v[30:31], v[16:17], v[8:9]
	ds_bpermute_b32 v8, v1, v16
	v_add_f32_e32 v2, 1.0, v2
	v_rcp_f32_e32 v2, v2
	ds_bpermute_b32 v9, v1, v17
	v_cvt_pk_bf16_f32 v16, v16, v17
	v_mul_f32_e32 v2, 0xc1000000, v2
	v_mul_f32_e32 v2, v59, v2
	v_mul_f32_e32 v2, 0x3fb8aa3b, v2
	v_exp_f32_e32 v11, v2
	s_nop 0
	v_fma_f32 v2, -v11, v11, 1.0
	v_mov_b32_dpp v7, v11 row_shr:1 row_mask:0xf bank_mask:0xf
	v_pk_mul_f32 v[24:25], v[10:11], v[6:7]
	v_mov_b32_e32 v6, 1.0
	v_mov_b32_e32 v7, 1.0
	v_sqrt_f32_e32 v21, v2
	v_mov_b32_dpp v6, v24 row_shr:2 row_mask:0xf bank_mask:0xf
	v_mov_b32_dpp v7, v25 row_shr:2 row_mask:0xf bank_mask:0xf
	v_pk_mul_f32 v[26:27], v[24:25], v[6:7]
	v_mov_b32_e32 v6, 1.0
	v_mov_b32_e32 v7, 1.0
	v_add_u32_e32 v2, 0x3188, v145
	v_mov_b32_dpp v6, v26 row_shr:4 row_mask:0xf bank_mask:0xf
	v_mov_b32_dpp v7, v27 row_shr:4 row_mask:0xf bank_mask:0xf
	v_pk_mul_f32 v[28:29], v[26:27], v[6:7]
	v_mov_b32_e32 v6, 1.0
	v_mov_b32_e32 v7, 1.0
	s_nop 0
	v_mov_b32_dpp v6, v28 row_shr:8 row_mask:0xf bank_mask:0xf
	v_mov_b32_dpp v7, v29 row_shr:8 row_mask:0xf bank_mask:0xf
	v_pk_mul_f32 v[30:31], v[28:29], v[6:7]
	s_nop 0
	v_pk_mul_f32 v[22:23], v[30:31], v[32:33]
	ds_read2_b32 v[32:33], v2 offset1:1
	ds_bpermute_b32 v6, v1, v22
	ds_bpermute_b32 v7, v1, v23
	s_waitcnt lgkmcnt(0)
	v_pk_mul_f32 v[18:19], v[18:19], v[32:33]
	s_nop 0
	v_pk_mul_f32 v[18:19], v[20:21], v[18:19]
	s_nop 1
	v_mov_b32_dpp v20, v18 row_shr:1 row_mask:0xf bank_mask:0xf bound_ctrl:1
	v_mov_b32_dpp v21, v19 row_shr:1 row_mask:0xf bank_mask:0xf bound_ctrl:1
	v_pk_fma_f32 v[10:11], v[10:11], v[20:21], v[18:19]
	s_nop 1
	v_mov_b32_dpp v18, v10 row_shr:2 row_mask:0xf bank_mask:0xf bound_ctrl:1
	v_mov_b32_dpp v19, v11 row_shr:2 row_mask:0xf bank_mask:0xf bound_ctrl:1
	v_pk_fma_f32 v[10:11], v[24:25], v[18:19], v[10:11]
	s_nop 1
	v_mov_b32_dpp v18, v10 row_shr:4 row_mask:0xf bank_mask:0xf bound_ctrl:1
	v_mov_b32_dpp v19, v11 row_shr:4 row_mask:0xf bank_mask:0xf bound_ctrl:1
	v_pk_fma_f32 v[10:11], v[26:27], v[18:19], v[10:11]
	s_nop 1
	v_mov_b32_dpp v18, v10 row_shr:8 row_mask:0xf bank_mask:0xf bound_ctrl:1
	v_mov_b32_dpp v19, v11 row_shr:8 row_mask:0xf bank_mask:0xf bound_ctrl:1
	v_pk_fma_f32 v[10:11], v[28:29], v[18:19], v[10:11]
	s_nop 0
	v_pk_fma_f32 v[12:13], v[30:31], v[12:13], v[10:11]
	ds_bpermute_b32 v10, v1, v12
	ds_bpermute_b32 v11, v1, v13
	v_cvt_pk_bf16_f32 v17, v12, v13
	v_cvt_pk_bf16_f32 v12, v14, v15
	v_cvt_pk_bf16_f32 v13, v22, v23
	v_mov_b64_e32 v[248:249], v[16:17]
	s_nop 1
	v_permlane16_swap_b32_e32 v246, v248
	v_permlane16_swap_b32_e32 v247, v249
	global_store_dwordx4 v[114:115], v[246:249], off offset:64
	v_mov_b64_e32 v[252:253], v[12:13]
	s_nop 1
	v_permlane16_swap_b32_e32 v250, v252
	v_permlane16_swap_b32_e32 v251, v253
	global_store_dwordx4 v[116:117], v[250:253], off offset:64
	s_and_saveexec_b64 s[34:35], vcc
	s_cbranch_execz .LBB0_518
	v_add_u32_e32 v0, 48, v0
	v_ashrrev_i32_e32 v1, 31, v0
	v_lshl_add_u64 v[0:1], s[42:43], 0, v[0:1]
	v_lshlrev_b64 v[0:1], 2, v[0:1]
	v_lshl_add_u64 v[12:13], s[84:85], 0, v[0:1]
	v_lshl_add_u64 v[0:1], s[86:87], 0, v[0:1]
	global_store_dwordx4 v[12:13], v[4:7], off
	s_waitcnt lgkmcnt(0)
	global_store_dwordx4 v[0:1], v[8:11], off
	s_branch .LBB0_518
